# v11 + wout and fnetw GEMM k-loops re-emitted with v_mfma_f32_16x16x32_bf16
# speedup vs baseline: 1.0111x; 1.0070x over previous
.LBB0_825:
	s_cmp_gt_i32 s52, 5
	s_cselect_b64 s[0:1], -1, 0
	s_cmp_lt_i32 s53, 6
	s_cselect_b64 s[2:3], -1, 0
	s_or_b64 s[0:1], s[0:1], s[2:3]
	s_and_b64 vcc, exec, s[0:1]
	s_cbranch_vccnz .LBB0_897
	v_readlane_b32 s0, v248, 0
	s_cmpk_gt_u32 s0, 0x17f
	s_cbranch_scc1 .LBB0_829
	v_lshlrev_b32_e32 v2, 4, v1
	v_and_b32_e32 v74, 0x70, v2
	v_mov_b32_e32 v75, 0
	v_lshl_add_u64 v[2:3], s[82:83], 0, v[74:75]
	s_mov_b64 s[6:7], 0xb000000
	v_lshl_add_u64 v[76:77], v[2:3], 0, s[6:7]
	s_mov_b64 s[6:7], 0xc900000
	v_lshl_add_u64 v[78:79], v[2:3], 0, s[6:7]
	v_lshrrev_b32_e32 v2, 1, v1
	v_readlane_b32 s4, v248, 0
	v_and_b32_e32 v97, 0x1c0, v2
	s_lshr_b32 s2, s4, 3
	s_lshr_b32 s3, s50, 3
	v_lshrrev_b32_e32 v93, 3, v1
	v_and_or_b32 v3, v1, 31, v97
	v_and_b32_e32 v2, 16, v2
	s_movk_i32 s5, 0x90
	s_add_u32 s0, s82, 0x4800000
	v_mad_u32_u24 v98, v3, s5, v2
	v_mul_u32_u24_e32 v3, 0x48, v93
	s_addc_u32 s1, s83, 0
	v_lshl_add_u32 v100, v3, 1, v74
	v_lshrrev_b32_e32 v246, 3, v1
	v_and_b32_e32 v246, 15, v246
	v_add_u32_e32 v246, 4, v246
	v_bfe_u32 v246, v246, 3, 1
	v_and_b32_e32 v249, 1, v1
	v_lshlrev_b32_e32 v249, 1, v249
	v_sub_u32_e32 v249, 1, v249
	v_mul_i32_i24_e32 v246, v246, v249
	v_lshlrev_b32_e32 v246, 4, v246
	v_add_u32_e32 v100, v246, v100
	v_lshlrev_b32_e32 v74, 1, v97
	v_and_b32_e32 v92, 0x5f, v1
	s_and_b32 s4, s4, 7
	v_lshl_add_u64 v[4:5], s[0:1], 0, v[74:75]
	v_mov_b32_e32 v3, v75
	s_mul_i32 s4, s4, 12
	v_add_u32_e32 v94, 32, v93
	v_add_u32_e32 v95, 64, v93
	v_add_u32_e32 v96, 0x60, v93
	v_mad_u32_u24 v99, v92, s5, v2
	v_add_u32_e32 v101, 0x9000, v100
	v_lshl_add_u64 v[80:81], v[4:5], 0, v[2:3]
	v_lshl_add_u64 v[82:83], s[0:1], 0, v[2:3]
	s_mov_b32 s1, 0
	s_mov_b32 s5, s2
	s_mov_b32 s0, s2
	s_mov_b32 s6, 0
.LBB0_828:
	s_lshr_b32 s8, s0, 2
	s_lshl_b32 s0, s0, 7
	s_and_b32 s7, s0, 0x180
	v_or_b32_e32 v2, s7, v93
	v_lshlrev_b32_e32 v74, 10, v2
	s_add_i32 s8, s8, s4
	v_lshl_add_u64 v[66:67], v[76:77], 0, v[74:75]
	v_add_lshl_u32 v74, s7, v94, 10
	s_lshl_b32 s0, s8, 7
	v_lshl_add_u64 v[68:69], v[76:77], 0, v[74:75]
	v_add_lshl_u32 v74, s7, v95, 10
	v_lshl_add_u64 v[70:71], v[76:77], 0, v[74:75]
	v_add_lshl_u32 v74, s7, v96, 10
	v_or_b32_e32 v2, s0, v93
	v_lshl_add_u64 v[72:73], v[76:77], 0, v[74:75]
	v_lshlrev_b32_e32 v74, 10, v2
	v_lshl_add_u64 v[84:85], v[78:79], 0, v[74:75]
	v_add_lshl_u32 v74, s0, v94, 10
	v_lshl_add_u64 v[86:87], v[78:79], 0, v[74:75]
	v_add_lshl_u32 v74, s0, v95, 10
	v_lshl_add_u64 v[88:89], v[78:79], 0, v[74:75]
	v_add_lshl_u32 v74, s0, v96, 10
	v_lshl_add_u64 v[90:91], v[78:79], 0, v[74:75]
	global_load_dwordx4 v[2:5], v[66:67], off
	global_load_dwordx4 v[6:9], v[68:69], off
	global_load_dwordx4 v[10:13], v[70:71], off
	global_load_dwordx4 v[14:17], v[72:73], off
	global_load_dwordx4 v[18:21], v[84:85], off
	global_load_dwordx4 v[22:25], v[86:87], off
	global_load_dwordx4 v[26:29], v[88:89], off
	global_load_dwordx4 v[30:33], v[90:91], off
	global_load_dwordx4 v[102:105], v[66:67], off offset:128
	global_load_dwordx4 v[106:109], v[68:69], off offset:128
	global_load_dwordx4 v[110:113], v[70:71], off offset:128
	global_load_dwordx4 v[114:117], v[72:73], off offset:128
	global_load_dwordx4 v[118:121], v[84:85], off offset:128
	global_load_dwordx4 v[122:125], v[86:87], off offset:128
	global_load_dwordx4 v[126:129], v[88:89], off offset:128
	global_load_dwordx4 v[136:139], v[90:91], off offset:128
	s_waitcnt vmcnt(15)
	ds_write_b128 v100, v[2:5]
	s_waitcnt vmcnt(14)
	ds_write_b128 v100, v[6:9] offset:4608
	s_waitcnt vmcnt(13)
	ds_write_b128 v100, v[10:13] offset:9216
	s_waitcnt vmcnt(12)
	ds_write_b128 v100, v[14:17] offset:13824
	s_waitcnt vmcnt(11)
	ds_write_b128 v100, v[18:21] offset:36864
	s_waitcnt vmcnt(10)
	ds_write_b128 v100, v[22:25] offset:41472
	s_waitcnt vmcnt(9)
	ds_write_b128 v100, v[26:29] offset:46080
	s_waitcnt vmcnt(8)
	ds_write_b128 v100, v[30:33] offset:50688
	s_waitcnt lgkmcnt(0)
	s_barrier
	global_load_dwordx4 v[140:143], v[66:67], off offset:256
	global_load_dwordx4 v[144:147], v[68:69], off offset:256
	global_load_dwordx4 v[148:151], v[70:71], off offset:256
	global_load_dwordx4 v[152:155], v[72:73], off offset:256
	global_load_dwordx4 v[156:159], v[84:85], off offset:256
	global_load_dwordx4 v[160:163], v[86:87], off offset:256
	global_load_dwordx4 v[164:167], v[88:89], off offset:256
	global_load_dwordx4 v[168:171], v[90:91], off offset:256
	v_and_b32_e32 v246, 15, v1
	v_add_u32_e32 v246, 4, v246
	v_bfe_u32 v246, v246, 3, 1
	v_bfe_u32 v249, v1, 4, 2
	v_xor_b32_e32 v246, v246, v249
	v_bfe_u32 v249, v1, 5, 1
	v_sub_u32_e32 v246, v246, v249
	v_lshlrev_b32_e32 v246, 4, v246
	v_bfe_u32 v249, v1, 4, 1
	v_mul_u32_u24_e32 v249, 0x900, v249
	v_sub_u32_e32 v246, v246, v249
	v_add_u32_e32 v244, v246, v98
	v_add_u32_e32 v245, v246, v99
	ds_read_b128 v[212:215], v245 offset:36864
	ds_read_b128 v[196:199], v244
	ds_read_b128 v[216:219], v245 offset:39168
	ds_read_b128 v[220:223], v245 offset:41472
	ds_read_b128 v[224:227], v245 offset:43776
	ds_read_b128 v[200:203], v244 offset:2304
	ds_read_b128 v[204:207], v244 offset:4608
	ds_read_b128 v[208:211], v244 offset:6912
	s_waitcnt lgkmcnt(6)
	v_mfma_f32_16x16x32_bf16 v[50:53], v[196:199], v[212:215], 0
	ds_read_b128 v[228:231], v245 offset:36928
	s_waitcnt lgkmcnt(6)
	v_mfma_f32_16x16x32_bf16 v[54:57], v[196:199], v[216:219], 0
	ds_read_b128 v[232:235], v245 offset:39232
	s_waitcnt lgkmcnt(6)
	v_mfma_f32_16x16x32_bf16 v[18:21], v[196:199], v[220:223], 0
	ds_read_b128 v[236:239], v245 offset:41536
	s_waitcnt lgkmcnt(6)
	v_mfma_f32_16x16x32_bf16 v[22:25], v[196:199], v[224:227], 0
	ds_read_b128 v[240:243], v245 offset:43840
	ds_read_b128 v[196:199], v244 offset:64
	s_waitcnt lgkmcnt(7)
	v_mfma_f32_16x16x32_bf16 v[58:61], v[200:203], v[212:215], 0
	v_mfma_f32_16x16x32_bf16 v[62:65], v[200:203], v[216:219], 0
	v_mfma_f32_16x16x32_bf16 v[26:29], v[200:203], v[220:223], 0
	v_mfma_f32_16x16x32_bf16 v[30:33], v[200:203], v[224:227], 0
	ds_read_b128 v[200:203], v244 offset:2368
	s_waitcnt lgkmcnt(7)
	v_mfma_f32_16x16x32_bf16 v[34:37], v[204:207], v[212:215], 0
	v_mfma_f32_16x16x32_bf16 v[38:41], v[204:207], v[216:219], 0
	v_mfma_f32_16x16x32_bf16 v[2:5], v[204:207], v[220:223], 0
	v_mfma_f32_16x16x32_bf16 v[6:9], v[204:207], v[224:227], 0
	ds_read_b128 v[204:207], v244 offset:4672
	s_waitcnt vmcnt(15)
	ds_write_b128 v100, v[102:105] offset:18432
	s_waitcnt vmcnt(14)
	ds_write_b128 v100, v[106:109] offset:23040
	s_waitcnt lgkmcnt(9)
	v_mfma_f32_16x16x32_bf16 v[42:45], v[208:211], v[212:215], 0
	v_mfma_f32_16x16x32_bf16 v[46:49], v[208:211], v[216:219], 0
	v_mfma_f32_16x16x32_bf16 v[10:13], v[208:211], v[220:223], 0
	v_mfma_f32_16x16x32_bf16 v[14:17], v[208:211], v[224:227], 0
	ds_read_b128 v[208:211], v244 offset:6976
	s_waitcnt vmcnt(13)
	ds_write_b128 v100, v[110:113] offset:27648
	s_waitcnt vmcnt(12)
	ds_write_b128 v100, v[114:117] offset:32256
	s_waitcnt lgkmcnt(7)
	v_mfma_f32_16x16x32_bf16 v[50:53], v[196:199], v[228:231], v[50:53]
	v_mfma_f32_16x16x32_bf16 v[54:57], v[196:199], v[232:235], v[54:57]
	v_mfma_f32_16x16x32_bf16 v[18:21], v[196:199], v[236:239], v[18:21]
	v_mfma_f32_16x16x32_bf16 v[22:25], v[196:199], v[240:243], v[22:25]
	s_waitcnt vmcnt(11)
	ds_write_b128 v100, v[118:121] offset:55296
	s_waitcnt vmcnt(10)
	ds_write_b128 v100, v[122:125] offset:59904
	s_waitcnt lgkmcnt(8)
	v_mfma_f32_16x16x32_bf16 v[58:61], v[200:203], v[228:231], v[58:61]
	v_mfma_f32_16x16x32_bf16 v[62:65], v[200:203], v[232:235], v[62:65]
	v_mfma_f32_16x16x32_bf16 v[26:29], v[200:203], v[236:239], v[26:29]
	v_mfma_f32_16x16x32_bf16 v[30:33], v[200:203], v[240:243], v[30:33]
	s_waitcnt vmcnt(9)
	ds_write_b128 v100, v[126:129] offset:64512
	s_waitcnt vmcnt(8)
	ds_write_b128 v101, v[136:139] offset:32256
	s_waitcnt lgkmcnt(9)
	v_mfma_f32_16x16x32_bf16 v[34:37], v[204:207], v[228:231], v[34:37]
	v_mfma_f32_16x16x32_bf16 v[38:41], v[204:207], v[232:235], v[38:41]
	v_mfma_f32_16x16x32_bf16 v[2:5], v[204:207], v[236:239], v[2:5]
	v_mfma_f32_16x16x32_bf16 v[6:9], v[204:207], v[240:243], v[6:9]
	s_waitcnt lgkmcnt(6)
	v_mfma_f32_16x16x32_bf16 v[42:45], v[208:211], v[228:231], v[42:45]
	v_mfma_f32_16x16x32_bf16 v[46:49], v[208:211], v[232:235], v[46:49]
	v_mfma_f32_16x16x32_bf16 v[10:13], v[208:211], v[236:239], v[10:13]
	v_mfma_f32_16x16x32_bf16 v[14:17], v[208:211], v[240:243], v[14:17]
	s_waitcnt lgkmcnt(0)
	s_barrier
	global_load_dwordx4 v[102:105], v[66:67], off offset:384
	global_load_dwordx4 v[106:109], v[68:69], off offset:384
	global_load_dwordx4 v[110:113], v[70:71], off offset:384
	global_load_dwordx4 v[114:117], v[72:73], off offset:384
	global_load_dwordx4 v[118:121], v[84:85], off offset:384
	global_load_dwordx4 v[122:125], v[86:87], off offset:384
	global_load_dwordx4 v[126:129], v[88:89], off offset:384
	global_load_dwordx4 v[136:139], v[90:91], off offset:384
	ds_read_b128 v[212:215], v245 offset:55296
	ds_read_b128 v[196:199], v244 offset:18432
	ds_read_b128 v[216:219], v245 offset:57600
	ds_read_b128 v[220:223], v245 offset:59904
	ds_read_b128 v[224:227], v245 offset:62208
	ds_read_b128 v[200:203], v244 offset:20736
	ds_read_b128 v[204:207], v244 offset:23040
	ds_read_b128 v[208:211], v244 offset:25344
	s_waitcnt lgkmcnt(6)
	v_mfma_f32_16x16x32_bf16 v[50:53], v[196:199], v[212:215], v[50:53]
	ds_read_b128 v[228:231], v245 offset:55360
	s_waitcnt lgkmcnt(6)
	v_mfma_f32_16x16x32_bf16 v[54:57], v[196:199], v[216:219], v[54:57]
	ds_read_b128 v[232:235], v245 offset:57664
	s_waitcnt lgkmcnt(6)
	v_mfma_f32_16x16x32_bf16 v[18:21], v[196:199], v[220:223], v[18:21]
	ds_read_b128 v[236:239], v245 offset:59968
	s_waitcnt lgkmcnt(6)
	v_mfma_f32_16x16x32_bf16 v[22:25], v[196:199], v[224:227], v[22:25]
	ds_read_b128 v[240:243], v245 offset:62272
	ds_read_b128 v[196:199], v244 offset:18496
	s_waitcnt lgkmcnt(7)
	v_mfma_f32_16x16x32_bf16 v[58:61], v[200:203], v[212:215], v[58:61]
	v_mfma_f32_16x16x32_bf16 v[62:65], v[200:203], v[216:219], v[62:65]
	v_mfma_f32_16x16x32_bf16 v[26:29], v[200:203], v[220:223], v[26:29]
	v_mfma_f32_16x16x32_bf16 v[30:33], v[200:203], v[224:227], v[30:33]
	ds_read_b128 v[200:203], v244 offset:20800
	s_waitcnt lgkmcnt(7)
	v_mfma_f32_16x16x32_bf16 v[34:37], v[204:207], v[212:215], v[34:37]
	v_mfma_f32_16x16x32_bf16 v[38:41], v[204:207], v[216:219], v[38:41]
	v_mfma_f32_16x16x32_bf16 v[2:5], v[204:207], v[220:223], v[2:5]
	v_mfma_f32_16x16x32_bf16 v[6:9], v[204:207], v[224:227], v[6:9]
	ds_read_b128 v[204:207], v244 offset:23104
	s_waitcnt vmcnt(15)
	ds_write_b128 v100, v[140:143]
	s_waitcnt vmcnt(14)
	ds_write_b128 v100, v[144:147] offset:4608
	s_waitcnt lgkmcnt(9)
	v_mfma_f32_16x16x32_bf16 v[42:45], v[208:211], v[212:215], v[42:45]
	v_mfma_f32_16x16x32_bf16 v[46:49], v[208:211], v[216:219], v[46:49]
	v_mfma_f32_16x16x32_bf16 v[10:13], v[208:211], v[220:223], v[10:13]
	v_mfma_f32_16x16x32_bf16 v[14:17], v[208:211], v[224:227], v[14:17]
	ds_read_b128 v[208:211], v244 offset:25408
	s_waitcnt vmcnt(13)
	ds_write_b128 v100, v[148:151] offset:9216
	s_waitcnt vmcnt(12)
	ds_write_b128 v100, v[152:155] offset:13824
	s_waitcnt lgkmcnt(7)
	v_mfma_f32_16x16x32_bf16 v[50:53], v[196:199], v[228:231], v[50:53]
	v_mfma_f32_16x16x32_bf16 v[54:57], v[196:199], v[232:235], v[54:57]
	v_mfma_f32_16x16x32_bf16 v[18:21], v[196:199], v[236:239], v[18:21]
	v_mfma_f32_16x16x32_bf16 v[22:25], v[196:199], v[240:243], v[22:25]
	s_waitcnt vmcnt(11)
	ds_write_b128 v100, v[156:159] offset:36864
	s_waitcnt vmcnt(10)
	ds_write_b128 v100, v[160:163] offset:41472
	s_waitcnt lgkmcnt(8)
	v_mfma_f32_16x16x32_bf16 v[58:61], v[200:203], v[228:231], v[58:61]
	v_mfma_f32_16x16x32_bf16 v[62:65], v[200:203], v[232:235], v[62:65]
	v_mfma_f32_16x16x32_bf16 v[26:29], v[200:203], v[236:239], v[26:29]
	v_mfma_f32_16x16x32_bf16 v[30:33], v[200:203], v[240:243], v[30:33]
	s_waitcnt vmcnt(9)
	ds_write_b128 v100, v[164:167] offset:46080
	s_waitcnt vmcnt(8)
	ds_write_b128 v100, v[168:171] offset:50688
	s_waitcnt lgkmcnt(9)
	v_mfma_f32_16x16x32_bf16 v[34:37], v[204:207], v[228:231], v[34:37]
	v_mfma_f32_16x16x32_bf16 v[38:41], v[204:207], v[232:235], v[38:41]
	v_mfma_f32_16x16x32_bf16 v[2:5], v[204:207], v[236:239], v[2:5]
	v_mfma_f32_16x16x32_bf16 v[6:9], v[204:207], v[240:243], v[6:9]
	s_waitcnt lgkmcnt(6)
	v_mfma_f32_16x16x32_bf16 v[42:45], v[208:211], v[228:231], v[42:45]
	v_mfma_f32_16x16x32_bf16 v[46:49], v[208:211], v[232:235], v[46:49]
	v_mfma_f32_16x16x32_bf16 v[10:13], v[208:211], v[236:239], v[10:13]
	v_mfma_f32_16x16x32_bf16 v[14:17], v[208:211], v[240:243], v[14:17]
	s_waitcnt lgkmcnt(0)
	s_barrier
	global_load_dwordx4 v[140:143], v[66:67], off offset:512
	global_load_dwordx4 v[144:147], v[68:69], off offset:512
	global_load_dwordx4 v[148:151], v[70:71], off offset:512
	global_load_dwordx4 v[152:155], v[72:73], off offset:512
	global_load_dwordx4 v[156:159], v[84:85], off offset:512
	global_load_dwordx4 v[160:163], v[86:87], off offset:512
	global_load_dwordx4 v[164:167], v[88:89], off offset:512
	global_load_dwordx4 v[168:171], v[90:91], off offset:512
	ds_read_b128 v[212:215], v245 offset:36864
	ds_read_b128 v[196:199], v244
	ds_read_b128 v[216:219], v245 offset:39168
	ds_read_b128 v[220:223], v245 offset:41472
	ds_read_b128 v[224:227], v245 offset:43776
	ds_read_b128 v[200:203], v244 offset:2304
	ds_read_b128 v[204:207], v244 offset:4608
	ds_read_b128 v[208:211], v244 offset:6912
	s_waitcnt lgkmcnt(6)
	v_mfma_f32_16x16x32_bf16 v[50:53], v[196:199], v[212:215], v[50:53]
	ds_read_b128 v[228:231], v245 offset:36928
	s_waitcnt lgkmcnt(6)
	v_mfma_f32_16x16x32_bf16 v[54:57], v[196:199], v[216:219], v[54:57]
	ds_read_b128 v[232:235], v245 offset:39232
	s_waitcnt lgkmcnt(6)
	v_mfma_f32_16x16x32_bf16 v[18:21], v[196:199], v[220:223], v[18:21]
	ds_read_b128 v[236:239], v245 offset:41536
	s_waitcnt lgkmcnt(6)
	v_mfma_f32_16x16x32_bf16 v[22:25], v[196:199], v[224:227], v[22:25]
	ds_read_b128 v[240:243], v245 offset:43840
	ds_read_b128 v[196:199], v244 offset:64
	s_waitcnt lgkmcnt(7)
	v_mfma_f32_16x16x32_bf16 v[58:61], v[200:203], v[212:215], v[58:61]
	v_mfma_f32_16x16x32_bf16 v[62:65], v[200:203], v[216:219], v[62:65]
	v_mfma_f32_16x16x32_bf16 v[26:29], v[200:203], v[220:223], v[26:29]
	v_mfma_f32_16x16x32_bf16 v[30:33], v[200:203], v[224:227], v[30:33]
	ds_read_b128 v[200:203], v244 offset:2368
	s_waitcnt lgkmcnt(7)
	v_mfma_f32_16x16x32_bf16 v[34:37], v[204:207], v[212:215], v[34:37]
	v_mfma_f32_16x16x32_bf16 v[38:41], v[204:207], v[216:219], v[38:41]
	v_mfma_f32_16x16x32_bf16 v[2:5], v[204:207], v[220:223], v[2:5]
	v_mfma_f32_16x16x32_bf16 v[6:9], v[204:207], v[224:227], v[6:9]
	ds_read_b128 v[204:207], v244 offset:4672
	s_waitcnt vmcnt(15)
	ds_write_b128 v100, v[102:105] offset:18432
	s_waitcnt vmcnt(14)
	ds_write_b128 v100, v[106:109] offset:23040
	s_waitcnt lgkmcnt(9)
	v_mfma_f32_16x16x32_bf16 v[42:45], v[208:211], v[212:215], v[42:45]
	v_mfma_f32_16x16x32_bf16 v[46:49], v[208:211], v[216:219], v[46:49]
	v_mfma_f32_16x16x32_bf16 v[10:13], v[208:211], v[220:223], v[10:13]
	v_mfma_f32_16x16x32_bf16 v[14:17], v[208:211], v[224:227], v[14:17]
	ds_read_b128 v[208:211], v244 offset:6976
	s_waitcnt vmcnt(13)
	ds_write_b128 v100, v[110:113] offset:27648
	s_waitcnt vmcnt(12)
	ds_write_b128 v100, v[114:117] offset:32256
	s_waitcnt lgkmcnt(7)
	v_mfma_f32_16x16x32_bf16 v[50:53], v[196:199], v[228:231], v[50:53]
	v_mfma_f32_16x16x32_bf16 v[54:57], v[196:199], v[232:235], v[54:57]
	v_mfma_f32_16x16x32_bf16 v[18:21], v[196:199], v[236:239], v[18:21]
	v_mfma_f32_16x16x32_bf16 v[22:25], v[196:199], v[240:243], v[22:25]
	s_waitcnt vmcnt(11)
	ds_write_b128 v100, v[118:121] offset:55296
	s_waitcnt vmcnt(10)
	ds_write_b128 v100, v[122:125] offset:59904
	s_waitcnt lgkmcnt(8)
	v_mfma_f32_16x16x32_bf16 v[58:61], v[200:203], v[228:231], v[58:61]
	v_mfma_f32_16x16x32_bf16 v[62:65], v[200:203], v[232:235], v[62:65]
	v_mfma_f32_16x16x32_bf16 v[26:29], v[200:203], v[236:239], v[26:29]
	v_mfma_f32_16x16x32_bf16 v[30:33], v[200:203], v[240:243], v[30:33]
	s_waitcnt vmcnt(9)
	ds_write_b128 v100, v[126:129] offset:64512
	s_waitcnt vmcnt(8)
	ds_write_b128 v101, v[136:139] offset:32256
	s_waitcnt lgkmcnt(9)
	v_mfma_f32_16x16x32_bf16 v[34:37], v[204:207], v[228:231], v[34:37]
	v_mfma_f32_16x16x32_bf16 v[38:41], v[204:207], v[232:235], v[38:41]
	v_mfma_f32_16x16x32_bf16 v[2:5], v[204:207], v[236:239], v[2:5]
	v_mfma_f32_16x16x32_bf16 v[6:9], v[204:207], v[240:243], v[6:9]
	s_waitcnt lgkmcnt(6)
	v_mfma_f32_16x16x32_bf16 v[42:45], v[208:211], v[228:231], v[42:45]
	v_mfma_f32_16x16x32_bf16 v[46:49], v[208:211], v[232:235], v[46:49]
	v_mfma_f32_16x16x32_bf16 v[10:13], v[208:211], v[236:239], v[10:13]
	v_mfma_f32_16x16x32_bf16 v[14:17], v[208:211], v[240:243], v[14:17]
	s_waitcnt lgkmcnt(0)
	s_barrier
	global_load_dwordx4 v[102:105], v[66:67], off offset:640
	global_load_dwordx4 v[106:109], v[68:69], off offset:640
	global_load_dwordx4 v[110:113], v[70:71], off offset:640
	global_load_dwordx4 v[114:117], v[72:73], off offset:640
	global_load_dwordx4 v[118:121], v[84:85], off offset:640
	global_load_dwordx4 v[122:125], v[86:87], off offset:640
	global_load_dwordx4 v[126:129], v[88:89], off offset:640
	global_load_dwordx4 v[136:139], v[90:91], off offset:640
	ds_read_b128 v[212:215], v245 offset:55296
	ds_read_b128 v[196:199], v244 offset:18432
	ds_read_b128 v[216:219], v245 offset:57600
	ds_read_b128 v[220:223], v245 offset:59904
	ds_read_b128 v[224:227], v245 offset:62208
	ds_read_b128 v[200:203], v244 offset:20736
	ds_read_b128 v[204:207], v244 offset:23040
	ds_read_b128 v[208:211], v244 offset:25344
	s_waitcnt lgkmcnt(6)
	v_mfma_f32_16x16x32_bf16 v[50:53], v[196:199], v[212:215], v[50:53]
	ds_read_b128 v[228:231], v245 offset:55360
	s_waitcnt lgkmcnt(6)
	v_mfma_f32_16x16x32_bf16 v[54:57], v[196:199], v[216:219], v[54:57]
	ds_read_b128 v[232:235], v245 offset:57664
	s_waitcnt lgkmcnt(6)
	v_mfma_f32_16x16x32_bf16 v[18:21], v[196:199], v[220:223], v[18:21]
	ds_read_b128 v[236:239], v245 offset:59968
	s_waitcnt lgkmcnt(6)
	v_mfma_f32_16x16x32_bf16 v[22:25], v[196:199], v[224:227], v[22:25]
	ds_read_b128 v[240:243], v245 offset:62272
	ds_read_b128 v[196:199], v244 offset:18496
	s_waitcnt lgkmcnt(7)
	v_mfma_f32_16x16x32_bf16 v[58:61], v[200:203], v[212:215], v[58:61]
	v_mfma_f32_16x16x32_bf16 v[62:65], v[200:203], v[216:219], v[62:65]
	v_mfma_f32_16x16x32_bf16 v[26:29], v[200:203], v[220:223], v[26:29]
	v_mfma_f32_16x16x32_bf16 v[30:33], v[200:203], v[224:227], v[30:33]
	ds_read_b128 v[200:203], v244 offset:20800
	s_waitcnt lgkmcnt(7)
	v_mfma_f32_16x16x32_bf16 v[34:37], v[204:207], v[212:215], v[34:37]
	v_mfma_f32_16x16x32_bf16 v[38:41], v[204:207], v[216:219], v[38:41]
	v_mfma_f32_16x16x32_bf16 v[2:5], v[204:207], v[220:223], v[2:5]
	v_mfma_f32_16x16x32_bf16 v[6:9], v[204:207], v[224:227], v[6:9]
	ds_read_b128 v[204:207], v244 offset:23104
	s_waitcnt vmcnt(15)
	ds_write_b128 v100, v[140:143]
	s_waitcnt vmcnt(14)
	ds_write_b128 v100, v[144:147] offset:4608
	s_waitcnt lgkmcnt(9)
	v_mfma_f32_16x16x32_bf16 v[42:45], v[208:211], v[212:215], v[42:45]
	v_mfma_f32_16x16x32_bf16 v[46:49], v[208:211], v[216:219], v[46:49]
	v_mfma_f32_16x16x32_bf16 v[10:13], v[208:211], v[220:223], v[10:13]
	v_mfma_f32_16x16x32_bf16 v[14:17], v[208:211], v[224:227], v[14:17]
	ds_read_b128 v[208:211], v244 offset:25408
	s_waitcnt vmcnt(13)
	ds_write_b128 v100, v[148:151] offset:9216
	s_waitcnt vmcnt(12)
	ds_write_b128 v100, v[152:155] offset:13824
	s_waitcnt lgkmcnt(7)
	v_mfma_f32_16x16x32_bf16 v[50:53], v[196:199], v[228:231], v[50:53]
	v_mfma_f32_16x16x32_bf16 v[54:57], v[196:199], v[232:235], v[54:57]
	v_mfma_f32_16x16x32_bf16 v[18:21], v[196:199], v[236:239], v[18:21]
	v_mfma_f32_16x16x32_bf16 v[22:25], v[196:199], v[240:243], v[22:25]
	s_waitcnt vmcnt(11)
	ds_write_b128 v100, v[156:159] offset:36864
	s_waitcnt vmcnt(10)
	ds_write_b128 v100, v[160:163] offset:41472
	s_waitcnt lgkmcnt(8)
	v_mfma_f32_16x16x32_bf16 v[58:61], v[200:203], v[228:231], v[58:61]
	v_mfma_f32_16x16x32_bf16 v[62:65], v[200:203], v[232:235], v[62:65]
	v_mfma_f32_16x16x32_bf16 v[26:29], v[200:203], v[236:239], v[26:29]
	v_mfma_f32_16x16x32_bf16 v[30:33], v[200:203], v[240:243], v[30:33]
	s_waitcnt vmcnt(9)
	ds_write_b128 v100, v[164:167] offset:46080
	s_waitcnt vmcnt(8)
	ds_write_b128 v100, v[168:171] offset:50688
	s_waitcnt lgkmcnt(9)
	v_mfma_f32_16x16x32_bf16 v[34:37], v[204:207], v[228:231], v[34:37]
	v_mfma_f32_16x16x32_bf16 v[38:41], v[204:207], v[232:235], v[38:41]
	v_mfma_f32_16x16x32_bf16 v[2:5], v[204:207], v[236:239], v[2:5]
	v_mfma_f32_16x16x32_bf16 v[6:9], v[204:207], v[240:243], v[6:9]
	s_waitcnt lgkmcnt(6)
	v_mfma_f32_16x16x32_bf16 v[42:45], v[208:211], v[228:231], v[42:45]
	v_mfma_f32_16x16x32_bf16 v[46:49], v[208:211], v[232:235], v[46:49]
	v_mfma_f32_16x16x32_bf16 v[10:13], v[208:211], v[236:239], v[10:13]
	v_mfma_f32_16x16x32_bf16 v[14:17], v[208:211], v[240:243], v[14:17]
	s_waitcnt lgkmcnt(0)
	s_barrier
	global_load_dwordx4 v[140:143], v[66:67], off offset:768
	global_load_dwordx4 v[144:147], v[68:69], off offset:768
	global_load_dwordx4 v[148:151], v[70:71], off offset:768
	global_load_dwordx4 v[152:155], v[72:73], off offset:768
	global_load_dwordx4 v[156:159], v[84:85], off offset:768
	global_load_dwordx4 v[160:163], v[86:87], off offset:768
	global_load_dwordx4 v[164:167], v[88:89], off offset:768
	global_load_dwordx4 v[168:171], v[90:91], off offset:768
	ds_read_b128 v[212:215], v245 offset:36864
	ds_read_b128 v[196:199], v244
	ds_read_b128 v[216:219], v245 offset:39168
	ds_read_b128 v[220:223], v245 offset:41472
	ds_read_b128 v[224:227], v245 offset:43776
	ds_read_b128 v[200:203], v244 offset:2304
	ds_read_b128 v[204:207], v244 offset:4608
	ds_read_b128 v[208:211], v244 offset:6912
	s_waitcnt lgkmcnt(6)
	v_mfma_f32_16x16x32_bf16 v[50:53], v[196:199], v[212:215], v[50:53]
	ds_read_b128 v[228:231], v245 offset:36928
	s_waitcnt lgkmcnt(6)
	v_mfma_f32_16x16x32_bf16 v[54:57], v[196:199], v[216:219], v[54:57]
	ds_read_b128 v[232:235], v245 offset:39232
	s_waitcnt lgkmcnt(6)
	v_mfma_f32_16x16x32_bf16 v[18:21], v[196:199], v[220:223], v[18:21]
	ds_read_b128 v[236:239], v245 offset:41536
	s_waitcnt lgkmcnt(6)
	v_mfma_f32_16x16x32_bf16 v[22:25], v[196:199], v[224:227], v[22:25]
	ds_read_b128 v[240:243], v245 offset:43840
	ds_read_b128 v[196:199], v244 offset:64
	s_waitcnt lgkmcnt(7)
	v_mfma_f32_16x16x32_bf16 v[58:61], v[200:203], v[212:215], v[58:61]
	v_mfma_f32_16x16x32_bf16 v[62:65], v[200:203], v[216:219], v[62:65]
	v_mfma_f32_16x16x32_bf16 v[26:29], v[200:203], v[220:223], v[26:29]
	v_mfma_f32_16x16x32_bf16 v[30:33], v[200:203], v[224:227], v[30:33]
	ds_read_b128 v[200:203], v244 offset:2368
	s_waitcnt lgkmcnt(7)
	v_mfma_f32_16x16x32_bf16 v[34:37], v[204:207], v[212:215], v[34:37]
	v_mfma_f32_16x16x32_bf16 v[38:41], v[204:207], v[216:219], v[38:41]
	v_mfma_f32_16x16x32_bf16 v[2:5], v[204:207], v[220:223], v[2:5]
	v_mfma_f32_16x16x32_bf16 v[6:9], v[204:207], v[224:227], v[6:9]
	ds_read_b128 v[204:207], v244 offset:4672
	s_waitcnt vmcnt(15)
	ds_write_b128 v100, v[102:105] offset:18432
	s_waitcnt vmcnt(14)
	ds_write_b128 v100, v[106:109] offset:23040
	s_waitcnt lgkmcnt(9)
	v_mfma_f32_16x16x32_bf16 v[42:45], v[208:211], v[212:215], v[42:45]
	v_mfma_f32_16x16x32_bf16 v[46:49], v[208:211], v[216:219], v[46:49]
	v_mfma_f32_16x16x32_bf16 v[10:13], v[208:211], v[220:223], v[10:13]
	v_mfma_f32_16x16x32_bf16 v[14:17], v[208:211], v[224:227], v[14:17]
	ds_read_b128 v[208:211], v244 offset:6976
	s_waitcnt vmcnt(13)
	ds_write_b128 v100, v[110:113] offset:27648
	s_waitcnt vmcnt(12)
	ds_write_b128 v100, v[114:117] offset:32256
	s_waitcnt lgkmcnt(7)
	v_mfma_f32_16x16x32_bf16 v[50:53], v[196:199], v[228:231], v[50:53]
	v_mfma_f32_16x16x32_bf16 v[54:57], v[196:199], v[232:235], v[54:57]
	v_mfma_f32_16x16x32_bf16 v[18:21], v[196:199], v[236:239], v[18:21]
	v_mfma_f32_16x16x32_bf16 v[22:25], v[196:199], v[240:243], v[22:25]
	s_waitcnt vmcnt(11)
	ds_write_b128 v100, v[118:121] offset:55296
	s_waitcnt vmcnt(10)
	ds_write_b128 v100, v[122:125] offset:59904
	s_waitcnt lgkmcnt(8)
	v_mfma_f32_16x16x32_bf16 v[58:61], v[200:203], v[228:231], v[58:61]
	v_mfma_f32_16x16x32_bf16 v[62:65], v[200:203], v[232:235], v[62:65]
	v_mfma_f32_16x16x32_bf16 v[26:29], v[200:203], v[236:239], v[26:29]
	v_mfma_f32_16x16x32_bf16 v[30:33], v[200:203], v[240:243], v[30:33]
	s_waitcnt vmcnt(9)
	ds_write_b128 v100, v[126:129] offset:64512
	s_waitcnt vmcnt(8)
	ds_write_b128 v101, v[136:139] offset:32256
	s_waitcnt lgkmcnt(9)
	v_mfma_f32_16x16x32_bf16 v[34:37], v[204:207], v[228:231], v[34:37]
	v_mfma_f32_16x16x32_bf16 v[38:41], v[204:207], v[232:235], v[38:41]
	v_mfma_f32_16x16x32_bf16 v[2:5], v[204:207], v[236:239], v[2:5]
	v_mfma_f32_16x16x32_bf16 v[6:9], v[204:207], v[240:243], v[6:9]
	s_waitcnt lgkmcnt(6)
	v_mfma_f32_16x16x32_bf16 v[42:45], v[208:211], v[228:231], v[42:45]
	v_mfma_f32_16x16x32_bf16 v[46:49], v[208:211], v[232:235], v[46:49]
	v_mfma_f32_16x16x32_bf16 v[10:13], v[208:211], v[236:239], v[10:13]
	v_mfma_f32_16x16x32_bf16 v[14:17], v[208:211], v[240:243], v[14:17]
	s_waitcnt lgkmcnt(0)
	s_barrier
	global_load_dwordx4 v[102:105], v[66:67], off offset:896
	s_nop 0
	global_load_dwordx4 v[66:69], v[68:69], off offset:896
	s_nop 0
	global_load_dwordx4 v[106:109], v[70:71], off offset:896
	s_nop 0
	global_load_dwordx4 v[70:73], v[72:73], off offset:896
	s_nop 0
	global_load_dwordx4 v[110:113], v[84:85], off offset:896
	s_nop 0
	global_load_dwordx4 v[84:87], v[86:87], off offset:896
	s_nop 0
	global_load_dwordx4 v[114:117], v[88:89], off offset:896
	s_nop 0
	global_load_dwordx4 v[88:91], v[90:91], off offset:896
	ds_read_b128 v[212:215], v245 offset:55296
	ds_read_b128 v[196:199], v244 offset:18432
	ds_read_b128 v[216:219], v245 offset:57600
	ds_read_b128 v[220:223], v245 offset:59904
	ds_read_b128 v[224:227], v245 offset:62208
	ds_read_b128 v[200:203], v244 offset:20736
	ds_read_b128 v[204:207], v244 offset:23040
	ds_read_b128 v[208:211], v244 offset:25344
	s_waitcnt lgkmcnt(6)
	v_mfma_f32_16x16x32_bf16 v[50:53], v[196:199], v[212:215], v[50:53]
	ds_read_b128 v[228:231], v245 offset:55360
	s_waitcnt lgkmcnt(6)
	v_mfma_f32_16x16x32_bf16 v[54:57], v[196:199], v[216:219], v[54:57]
	ds_read_b128 v[232:235], v245 offset:57664
	s_waitcnt lgkmcnt(6)
	v_mfma_f32_16x16x32_bf16 v[18:21], v[196:199], v[220:223], v[18:21]
	ds_read_b128 v[236:239], v245 offset:59968
	s_waitcnt lgkmcnt(6)
	v_mfma_f32_16x16x32_bf16 v[22:25], v[196:199], v[224:227], v[22:25]
	ds_read_b128 v[240:243], v245 offset:62272
	ds_read_b128 v[196:199], v244 offset:18496
	s_waitcnt lgkmcnt(7)
	v_mfma_f32_16x16x32_bf16 v[58:61], v[200:203], v[212:215], v[58:61]
	v_mfma_f32_16x16x32_bf16 v[62:65], v[200:203], v[216:219], v[62:65]
	v_mfma_f32_16x16x32_bf16 v[26:29], v[200:203], v[220:223], v[26:29]
	v_mfma_f32_16x16x32_bf16 v[30:33], v[200:203], v[224:227], v[30:33]
	ds_read_b128 v[200:203], v244 offset:20800
	s_waitcnt lgkmcnt(7)
	v_mfma_f32_16x16x32_bf16 v[34:37], v[204:207], v[212:215], v[34:37]
	v_mfma_f32_16x16x32_bf16 v[38:41], v[204:207], v[216:219], v[38:41]
	v_mfma_f32_16x16x32_bf16 v[2:5], v[204:207], v[220:223], v[2:5]
	v_mfma_f32_16x16x32_bf16 v[6:9], v[204:207], v[224:227], v[6:9]
	ds_read_b128 v[204:207], v244 offset:23104
	s_waitcnt vmcnt(15)
	ds_write_b128 v100, v[140:143]
	s_waitcnt vmcnt(14)
	ds_write_b128 v100, v[144:147] offset:4608
	s_waitcnt lgkmcnt(9)
	v_mfma_f32_16x16x32_bf16 v[42:45], v[208:211], v[212:215], v[42:45]
	v_mfma_f32_16x16x32_bf16 v[46:49], v[208:211], v[216:219], v[46:49]
	v_mfma_f32_16x16x32_bf16 v[10:13], v[208:211], v[220:223], v[10:13]
	v_mfma_f32_16x16x32_bf16 v[14:17], v[208:211], v[224:227], v[14:17]
	ds_read_b128 v[208:211], v244 offset:25408
	s_waitcnt vmcnt(13)
	ds_write_b128 v100, v[148:151] offset:9216
	s_waitcnt vmcnt(12)
	ds_write_b128 v100, v[152:155] offset:13824
	s_waitcnt lgkmcnt(7)
	v_mfma_f32_16x16x32_bf16 v[50:53], v[196:199], v[228:231], v[50:53]
	v_mfma_f32_16x16x32_bf16 v[54:57], v[196:199], v[232:235], v[54:57]
	v_mfma_f32_16x16x32_bf16 v[18:21], v[196:199], v[236:239], v[18:21]
	v_mfma_f32_16x16x32_bf16 v[22:25], v[196:199], v[240:243], v[22:25]
	s_waitcnt vmcnt(11)
	ds_write_b128 v100, v[156:159] offset:36864
	s_waitcnt vmcnt(10)
	ds_write_b128 v100, v[160:163] offset:41472
	s_waitcnt lgkmcnt(8)
	v_mfma_f32_16x16x32_bf16 v[58:61], v[200:203], v[228:231], v[58:61]
	v_mfma_f32_16x16x32_bf16 v[62:65], v[200:203], v[232:235], v[62:65]
	v_mfma_f32_16x16x32_bf16 v[26:29], v[200:203], v[236:239], v[26:29]
	v_mfma_f32_16x16x32_bf16 v[30:33], v[200:203], v[240:243], v[30:33]
	s_waitcnt vmcnt(9)
	ds_write_b128 v100, v[164:167] offset:46080
	s_waitcnt vmcnt(8)
	ds_write_b128 v100, v[168:171] offset:50688
	s_waitcnt lgkmcnt(9)
	v_mfma_f32_16x16x32_bf16 v[34:37], v[204:207], v[228:231], v[34:37]
	v_mfma_f32_16x16x32_bf16 v[38:41], v[204:207], v[232:235], v[38:41]
	v_mfma_f32_16x16x32_bf16 v[2:5], v[204:207], v[236:239], v[2:5]
	v_mfma_f32_16x16x32_bf16 v[6:9], v[204:207], v[240:243], v[6:9]
	s_waitcnt lgkmcnt(6)
	v_mfma_f32_16x16x32_bf16 v[42:45], v[208:211], v[228:231], v[42:45]
	v_mfma_f32_16x16x32_bf16 v[46:49], v[208:211], v[232:235], v[46:49]
	v_mfma_f32_16x16x32_bf16 v[10:13], v[208:211], v[236:239], v[10:13]
	v_mfma_f32_16x16x32_bf16 v[14:17], v[208:211], v[240:243], v[14:17]
	s_waitcnt lgkmcnt(0)
	s_barrier
	ds_read_b128 v[212:215], v245 offset:36864
	ds_read_b128 v[196:199], v244
	ds_read_b128 v[216:219], v245 offset:39168
	ds_read_b128 v[220:223], v245 offset:41472
	ds_read_b128 v[224:227], v245 offset:43776
	ds_read_b128 v[200:203], v244 offset:2304
	ds_read_b128 v[204:207], v244 offset:4608
	ds_read_b128 v[208:211], v244 offset:6912
	s_waitcnt lgkmcnt(6)
	v_mfma_f32_16x16x32_bf16 v[50:53], v[196:199], v[212:215], v[50:53]
	ds_read_b128 v[228:231], v245 offset:36928
	s_waitcnt lgkmcnt(6)
	v_mfma_f32_16x16x32_bf16 v[54:57], v[196:199], v[216:219], v[54:57]
	ds_read_b128 v[232:235], v245 offset:39232
	s_waitcnt lgkmcnt(6)
	v_mfma_f32_16x16x32_bf16 v[18:21], v[196:199], v[220:223], v[18:21]
	ds_read_b128 v[236:239], v245 offset:41536
	s_waitcnt lgkmcnt(6)
	v_mfma_f32_16x16x32_bf16 v[22:25], v[196:199], v[224:227], v[22:25]
	ds_read_b128 v[240:243], v245 offset:43840
	ds_read_b128 v[196:199], v244 offset:64
	s_waitcnt lgkmcnt(7)
	v_mfma_f32_16x16x32_bf16 v[58:61], v[200:203], v[212:215], v[58:61]
	v_mfma_f32_16x16x32_bf16 v[62:65], v[200:203], v[216:219], v[62:65]
	v_mfma_f32_16x16x32_bf16 v[26:29], v[200:203], v[220:223], v[26:29]
	v_mfma_f32_16x16x32_bf16 v[30:33], v[200:203], v[224:227], v[30:33]
	ds_read_b128 v[200:203], v244 offset:2368
	s_waitcnt lgkmcnt(7)
	v_mfma_f32_16x16x32_bf16 v[34:37], v[204:207], v[212:215], v[34:37]
	v_mfma_f32_16x16x32_bf16 v[38:41], v[204:207], v[216:219], v[38:41]
	v_mfma_f32_16x16x32_bf16 v[2:5], v[204:207], v[220:223], v[2:5]
	v_mfma_f32_16x16x32_bf16 v[6:9], v[204:207], v[224:227], v[6:9]
	ds_read_b128 v[204:207], v244 offset:4672
	s_waitcnt vmcnt(7)
	ds_write_b128 v100, v[102:105] offset:18432
	s_waitcnt vmcnt(6)
	ds_write_b128 v100, v[66:69] offset:23040
	s_waitcnt lgkmcnt(9)
	v_mfma_f32_16x16x32_bf16 v[42:45], v[208:211], v[212:215], v[42:45]
	v_mfma_f32_16x16x32_bf16 v[46:49], v[208:211], v[216:219], v[46:49]
	v_mfma_f32_16x16x32_bf16 v[10:13], v[208:211], v[220:223], v[10:13]
	v_mfma_f32_16x16x32_bf16 v[14:17], v[208:211], v[224:227], v[14:17]
	ds_read_b128 v[208:211], v244 offset:6976
	s_waitcnt vmcnt(5)
	ds_write_b128 v100, v[106:109] offset:27648
	s_waitcnt vmcnt(4)
	ds_write_b128 v100, v[70:73] offset:32256
	s_waitcnt lgkmcnt(7)
	v_mfma_f32_16x16x32_bf16 v[50:53], v[196:199], v[228:231], v[50:53]
	v_mfma_f32_16x16x32_bf16 v[54:57], v[196:199], v[232:235], v[54:57]
	v_mfma_f32_16x16x32_bf16 v[18:21], v[196:199], v[236:239], v[18:21]
	v_mfma_f32_16x16x32_bf16 v[22:25], v[196:199], v[240:243], v[22:25]
	s_waitcnt vmcnt(3)
	ds_write_b128 v100, v[110:113] offset:55296
	s_waitcnt vmcnt(2)
	ds_write_b128 v100, v[84:87] offset:59904
	s_waitcnt lgkmcnt(8)
	v_mfma_f32_16x16x32_bf16 v[58:61], v[200:203], v[228:231], v[58:61]
	v_mfma_f32_16x16x32_bf16 v[62:65], v[200:203], v[232:235], v[62:65]
	v_mfma_f32_16x16x32_bf16 v[26:29], v[200:203], v[236:239], v[26:29]
	v_mfma_f32_16x16x32_bf16 v[30:33], v[200:203], v[240:243], v[30:33]
	s_waitcnt vmcnt(1)
	ds_write_b128 v100, v[114:117] offset:64512
	s_waitcnt vmcnt(0)
	ds_write_b128 v101, v[88:91] offset:32256
	s_waitcnt lgkmcnt(9)
	v_mfma_f32_16x16x32_bf16 v[34:37], v[204:207], v[228:231], v[34:37]
	v_mfma_f32_16x16x32_bf16 v[38:41], v[204:207], v[232:235], v[38:41]
	v_mfma_f32_16x16x32_bf16 v[2:5], v[204:207], v[236:239], v[2:5]
	v_mfma_f32_16x16x32_bf16 v[6:9], v[204:207], v[240:243], v[6:9]
	s_waitcnt lgkmcnt(6)
	v_mfma_f32_16x16x32_bf16 v[42:45], v[208:211], v[228:231], v[42:45]
	v_mfma_f32_16x16x32_bf16 v[46:49], v[208:211], v[232:235], v[46:49]
	v_mfma_f32_16x16x32_bf16 v[10:13], v[208:211], v[236:239], v[10:13]
	v_mfma_f32_16x16x32_bf16 v[14:17], v[208:211], v[240:243], v[14:17]
	s_waitcnt lgkmcnt(0)
	s_barrier
	ds_read_b128 v[212:215], v245 offset:55296
	ds_read_b128 v[196:199], v244 offset:18432
	ds_read_b128 v[216:219], v245 offset:57600
	ds_read_b128 v[220:223], v245 offset:59904
	ds_read_b128 v[224:227], v245 offset:62208
	ds_read_b128 v[200:203], v244 offset:20736
	ds_read_b128 v[204:207], v244 offset:23040
	ds_read_b128 v[208:211], v244 offset:25344
	s_waitcnt lgkmcnt(6)
	v_mfma_f32_16x16x32_bf16 v[50:53], v[196:199], v[212:215], v[50:53]
	ds_read_b128 v[228:231], v245 offset:55360
	s_waitcnt lgkmcnt(6)
	v_mfma_f32_16x16x32_bf16 v[54:57], v[196:199], v[216:219], v[54:57]
	ds_read_b128 v[232:235], v245 offset:57664
	s_waitcnt lgkmcnt(6)
	v_mfma_f32_16x16x32_bf16 v[18:21], v[196:199], v[220:223], v[18:21]
	ds_read_b128 v[236:239], v245 offset:59968
	s_waitcnt lgkmcnt(6)
	v_mfma_f32_16x16x32_bf16 v[22:25], v[196:199], v[224:227], v[22:25]
	ds_read_b128 v[240:243], v245 offset:62272
	ds_read_b128 v[196:199], v244 offset:18496
	s_waitcnt lgkmcnt(7)
	v_mfma_f32_16x16x32_bf16 v[58:61], v[200:203], v[212:215], v[58:61]
	v_mfma_f32_16x16x32_bf16 v[62:65], v[200:203], v[216:219], v[62:65]
	v_mfma_f32_16x16x32_bf16 v[26:29], v[200:203], v[220:223], v[26:29]
	v_mfma_f32_16x16x32_bf16 v[30:33], v[200:203], v[224:227], v[30:33]
	ds_read_b128 v[200:203], v244 offset:20800
	s_waitcnt lgkmcnt(7)
	v_mfma_f32_16x16x32_bf16 v[34:37], v[204:207], v[212:215], v[34:37]
	v_mfma_f32_16x16x32_bf16 v[38:41], v[204:207], v[216:219], v[38:41]
	v_mfma_f32_16x16x32_bf16 v[2:5], v[204:207], v[220:223], v[2:5]
	v_mfma_f32_16x16x32_bf16 v[6:9], v[204:207], v[224:227], v[6:9]
	ds_read_b128 v[204:207], v244 offset:23104
	s_waitcnt lgkmcnt(7)
	v_mfma_f32_16x16x32_bf16 v[42:45], v[208:211], v[212:215], v[42:45]
	v_mfma_f32_16x16x32_bf16 v[46:49], v[208:211], v[216:219], v[46:49]
	v_mfma_f32_16x16x32_bf16 v[10:13], v[208:211], v[220:223], v[10:13]
	v_mfma_f32_16x16x32_bf16 v[14:17], v[208:211], v[224:227], v[14:17]
	ds_read_b128 v[208:211], v244 offset:25408
	s_waitcnt lgkmcnt(3)
	v_mfma_f32_16x16x32_bf16 v[50:53], v[196:199], v[228:231], v[50:53]
	v_mfma_f32_16x16x32_bf16 v[54:57], v[196:199], v[232:235], v[54:57]
	v_mfma_f32_16x16x32_bf16 v[18:21], v[196:199], v[236:239], v[18:21]
	v_mfma_f32_16x16x32_bf16 v[22:25], v[196:199], v[240:243], v[22:25]
	s_waitcnt lgkmcnt(2)
	v_mfma_f32_16x16x32_bf16 v[58:61], v[200:203], v[228:231], v[58:61]
	v_mfma_f32_16x16x32_bf16 v[62:65], v[200:203], v[232:235], v[62:65]
	v_mfma_f32_16x16x32_bf16 v[26:29], v[200:203], v[236:239], v[26:29]
	v_mfma_f32_16x16x32_bf16 v[30:33], v[200:203], v[240:243], v[30:33]
	s_waitcnt lgkmcnt(1)
	v_mfma_f32_16x16x32_bf16 v[34:37], v[204:207], v[228:231], v[34:37]
	v_mfma_f32_16x16x32_bf16 v[38:41], v[204:207], v[232:235], v[38:41]
	v_mfma_f32_16x16x32_bf16 v[2:5], v[204:207], v[236:239], v[2:5]
	v_mfma_f32_16x16x32_bf16 v[6:9], v[204:207], v[240:243], v[6:9]
	s_waitcnt lgkmcnt(0)
	v_mfma_f32_16x16x32_bf16 v[42:45], v[208:211], v[228:231], v[42:45]
	v_mfma_f32_16x16x32_bf16 v[46:49], v[208:211], v[232:235], v[46:49]
	v_mfma_f32_16x16x32_bf16 v[10:13], v[208:211], v[236:239], v[10:13]
	v_mfma_f32_16x16x32_bf16 v[14:17], v[208:211], v[240:243], v[14:17]
	s_add_i32 s6, s6, 1
	s_add_i32 s5, s5, s3
	v_or_b32_e32 v70, s0, v92
	s_lshl_b32 s0, s7, 1
	v_lshl_add_u64 v[110:111], v[80:81], 0, s[0:1]
	v_lshlrev_b32_e32 v74, 10, v70
	v_lshl_add_u64 v[112:113], v[110:111], 0, v[74:75]
	s_waitcnt lgkmcnt(0)
	s_barrier
	s_nop 7
	v_permlane16_swap_b32_e32 v50, v54
	v_permlane16_swap_b32_e32 v51, v55
	v_permlane16_swap_b32_e32 v52, v56
	v_permlane16_swap_b32_e32 v53, v57
	v_permlane16_swap_b32_e32 v58, v62
	v_permlane16_swap_b32_e32 v59, v63
	v_permlane16_swap_b32_e32 v60, v64
	v_permlane16_swap_b32_e32 v61, v65
	v_permlane16_swap_b32_e32 v18, v22
	v_permlane16_swap_b32_e32 v19, v23
	v_permlane16_swap_b32_e32 v20, v24
	v_permlane16_swap_b32_e32 v21, v25
	v_permlane16_swap_b32_e32 v26, v30
	v_permlane16_swap_b32_e32 v27, v31
	v_permlane16_swap_b32_e32 v28, v32
	v_permlane16_swap_b32_e32 v29, v33
	v_permlane16_swap_b32_e32 v34, v38
	v_permlane16_swap_b32_e32 v35, v39
	v_permlane16_swap_b32_e32 v36, v40
	v_permlane16_swap_b32_e32 v37, v41
	v_permlane16_swap_b32_e32 v42, v46
	v_permlane16_swap_b32_e32 v43, v47
	v_permlane16_swap_b32_e32 v44, v48
	v_permlane16_swap_b32_e32 v45, v49
	v_permlane16_swap_b32_e32 v2, v6
	v_permlane16_swap_b32_e32 v3, v7
	v_permlane16_swap_b32_e32 v4, v8
	v_permlane16_swap_b32_e32 v5, v9
	v_permlane16_swap_b32_e32 v10, v14
	v_permlane16_swap_b32_e32 v11, v15
	v_permlane16_swap_b32_e32 v12, v16
	v_permlane16_swap_b32_e32 v13, v17
	v_permlane32_swap_b32_e32 v50, v54
	v_permlane32_swap_b32_e32 v51, v55
	v_permlane32_swap_b32_e32 v52, v56
	v_permlane32_swap_b32_e32 v53, v57
	v_permlane32_swap_b32_e32 v58, v62
	v_permlane32_swap_b32_e32 v59, v63
	v_permlane32_swap_b32_e32 v60, v64
	v_permlane32_swap_b32_e32 v61, v65
	v_permlane32_swap_b32_e32 v18, v22
	v_permlane32_swap_b32_e32 v19, v23
	v_permlane32_swap_b32_e32 v20, v24
	v_permlane32_swap_b32_e32 v21, v25
	v_permlane32_swap_b32_e32 v26, v30
	v_permlane32_swap_b32_e32 v27, v31
	v_permlane32_swap_b32_e32 v28, v32
	v_permlane32_swap_b32_e32 v29, v33
	v_permlane32_swap_b32_e32 v34, v38
	v_permlane32_swap_b32_e32 v35, v39
	v_permlane32_swap_b32_e32 v36, v40
	v_permlane32_swap_b32_e32 v37, v41
	v_permlane32_swap_b32_e32 v42, v46
	v_permlane32_swap_b32_e32 v43, v47
	v_permlane32_swap_b32_e32 v44, v48
	v_permlane32_swap_b32_e32 v45, v49
	v_permlane32_swap_b32_e32 v2, v6
	v_permlane32_swap_b32_e32 v3, v7
	v_permlane32_swap_b32_e32 v4, v8
	v_permlane32_swap_b32_e32 v5, v9
	v_permlane32_swap_b32_e32 v10, v14
	v_permlane32_swap_b32_e32 v11, v15
	v_permlane32_swap_b32_e32 v12, v16
	v_permlane32_swap_b32_e32 v13, v17
	global_load_dwordx4 v[106:109], v[112:113], off
	s_mul_i32 s0, s6, s3
	s_add_i32 s0, s0, s2
	s_cmp_lt_u32 s5, 48
	global_load_dwordx4 v[88:91], v[112:113], off offset:32
	global_load_dwordx4 v[70:73], v[112:113], off offset:64
	s_waitcnt vmcnt(2)
	v_mov_b32_e32 v86, v108
	global_load_dwordx4 v[66:69], v[112:113], off offset:96
	v_permlane32_swap_b32_e32 v106, v86
	v_mov_b32_e32 v102, v109
	s_nop 1
	v_permlane32_swap_b32_e32 v107, v102
	s_waitcnt vmcnt(2)
	v_mov_b32_e32 v108, v90
	v_mov_b32_e32 v109, v91
	s_nop 0
	v_permlane32_swap_b32_e32 v88, v108
	v_permlane32_swap_b32_e32 v89, v109
	s_waitcnt vmcnt(1)
	v_mov_b32_e32 v112, v72
	v_mov_b32_e32 v113, v73
	v_lshlrev_b32_e32 v72, 16, v106
	v_and_b32_e32 v73, 0xffff0000, v106
	v_pk_mul_f32 v[72:73], v[50:51], v[72:73]
	v_lshlrev_b32_e32 v50, 16, v107
	v_and_b32_e32 v51, 0xffff0000, v107
	v_pk_mul_f32 v[84:85], v[52:53], v[50:51]
	v_lshlrev_b32_e32 v50, 16, v86
	v_and_b32_e32 v51, 0xffff0000, v86
	v_pk_mul_f32 v[86:87], v[54:55], v[50:51]
	v_lshlrev_b32_e32 v54, 16, v102
	v_and_b32_e32 v55, 0xffff0000, v102
	v_pk_mul_f32 v[102:103], v[56:57], v[54:55]
	v_cvt_pk_bf16_f32 v55, v84, v85
	v_cvt_pk_bf16_f32 v56, v86, v87
	v_cvt_pk_bf16_f32 v57, v102, v103
	v_cvt_pk_bf16_f32 v54, v72, v73
	v_add_lshl_u32 v72, s7, v97, 1
	v_mov_b32_e32 v73, v75
	v_permlane32_swap_b32_e32 v54, v56
	v_permlane32_swap_b32_e32 v55, v57
	v_lshlrev_b32_e32 v106, 16, v88
	v_and_b32_e32 v107, 0xffff0000, v88
	v_lshlrev_b32_e32 v88, 16, v89
	v_and_b32_e32 v89, 0xffff0000, v89
	v_pk_mul_f32 v[60:61], v[60:61], v[88:89]
	v_lshlrev_b32_e32 v88, 16, v108
	v_and_b32_e32 v89, 0xffff0000, v108
	v_pk_mul_f32 v[62:63], v[62:63], v[88:89]
	v_lshlrev_b32_e32 v88, 16, v109
	v_and_b32_e32 v89, 0xffff0000, v109
	v_pk_mul_f32 v[58:59], v[58:59], v[106:107]
	v_pk_mul_f32 v[64:65], v[64:65], v[88:89]
	v_cvt_pk_bf16_f32 v58, v58, v59
	v_cvt_pk_bf16_f32 v59, v60, v61
	v_cvt_pk_bf16_f32 v60, v62, v63
	v_cvt_pk_bf16_f32 v61, v64, v65
	v_permlane32_swap_b32_e32 v70, v112
	v_permlane32_swap_b32_e32 v58, v60
	v_permlane32_swap_b32_e32 v59, v61
	v_permlane32_swap_b32_e32 v71, v113
	s_waitcnt vmcnt(0)
	v_mov_b32_e32 v114, v68
	v_mov_b32_e32 v115, v69
	v_lshl_add_u64 v[68:69], v[82:83], 0, v[74:75]
	v_or_b32_e32 v74, 0x8000, v74
	v_lshl_add_u64 v[90:91], v[110:111], 0, v[74:75]
	global_load_dwordx4 v[50:53], v[90:91], off
	global_load_dwordx4 v[84:87], v[90:91], off offset:32
	global_load_dwordx4 v[102:105], v[90:91], off offset:64
	v_lshl_add_u64 v[68:69], v[68:69], 0, v[72:73]
	global_store_dwordx4 v[68:69], v[54:57], off
	global_load_dwordx4 v[54:57], v[90:91], off offset:96
	v_permlane32_swap_b32_e32 v66, v114
	global_store_dwordx4 v[68:69], v[58:61], off offset:32
	v_permlane32_swap_b32_e32 v67, v115
	s_nop 0
	v_lshlrev_b32_e32 v58, 16, v70
	v_and_b32_e32 v59, 0xffff0000, v70
	v_pk_mul_f32 v[34:35], v[34:35], v[58:59]
	v_lshlrev_b32_e32 v58, 16, v71
	v_and_b32_e32 v59, 0xffff0000, v71
	v_pk_mul_f32 v[36:37], v[36:37], v[58:59]
	v_lshlrev_b32_e32 v58, 16, v112
	v_and_b32_e32 v59, 0xffff0000, v112
	v_pk_mul_f32 v[38:39], v[38:39], v[58:59]
	v_lshlrev_b32_e32 v58, 16, v113
	v_and_b32_e32 v59, 0xffff0000, v113
	v_pk_mul_f32 v[40:41], v[40:41], v[58:59]
	v_cvt_pk_bf16_f32 v34, v34, v35
	v_cvt_pk_bf16_f32 v35, v36, v37
	v_cvt_pk_bf16_f32 v36, v38, v39
	v_cvt_pk_bf16_f32 v37, v40, v41
	s_nop 0
	v_permlane32_swap_b32_e32 v34, v36
	v_permlane32_swap_b32_e32 v35, v37
	global_store_dwordx4 v[68:69], v[34:37], off offset:64
	v_lshlrev_b32_e32 v38, 16, v114
	v_and_b32_e32 v39, 0xffff0000, v114
	v_lshlrev_b32_e32 v34, 16, v66
	v_and_b32_e32 v35, 0xffff0000, v66
	v_lshlrev_b32_e32 v36, 16, v67
	v_and_b32_e32 v37, 0xffff0000, v67
	v_lshlrev_b32_e32 v40, 16, v115
	v_and_b32_e32 v41, 0xffff0000, v115
	v_pk_mul_f32 v[34:35], v[42:43], v[34:35]
	v_pk_mul_f32 v[36:37], v[44:45], v[36:37]
	v_pk_mul_f32 v[38:39], v[46:47], v[38:39]
	v_pk_mul_f32 v[40:41], v[48:49], v[40:41]
	v_cvt_pk_bf16_f32 v34, v34, v35
	v_cvt_pk_bf16_f32 v35, v36, v37
	v_cvt_pk_bf16_f32 v36, v38, v39
	v_cvt_pk_bf16_f32 v37, v40, v41
	s_nop 0
	v_permlane32_swap_b32_e32 v34, v36
	v_permlane32_swap_b32_e32 v35, v37
	global_store_dwordx4 v[68:69], v[34:37], off offset:96
	s_waitcnt vmcnt(7)
	v_mov_b32_e32 v38, v52
	s_nop 1
	v_permlane32_swap_b32_e32 v50, v38
	v_mov_b32_e32 v39, v53
	s_nop 1
	v_permlane32_swap_b32_e32 v51, v39
	v_lshlrev_b32_e32 v36, 16, v50
	v_and_b32_e32 v37, 0xffff0000, v50
	v_pk_mul_f32 v[18:19], v[18:19], v[36:37]
	v_lshlrev_b32_e32 v36, 16, v51
	v_and_b32_e32 v37, 0xffff0000, v51
	v_pk_mul_f32 v[20:21], v[20:21], v[36:37]
	v_lshlrev_b32_e32 v36, 16, v38
	v_and_b32_e32 v37, 0xffff0000, v38
	v_pk_mul_f32 v[22:23], v[22:23], v[36:37]
	v_lshlrev_b32_e32 v36, 16, v39
	v_and_b32_e32 v37, 0xffff0000, v39
	v_pk_mul_f32 v[24:25], v[24:25], v[36:37]
	s_waitcnt vmcnt(6)
	v_mov_b32_e32 v40, v86
	v_lshl_add_u64 v[34:35], v[82:83], 0, v[74:75]
	v_cvt_pk_bf16_f32 v18, v18, v19
	v_cvt_pk_bf16_f32 v19, v20, v21
	v_cvt_pk_bf16_f32 v20, v22, v23
	v_cvt_pk_bf16_f32 v21, v24, v25
	v_permlane32_swap_b32_e32 v84, v40
	v_mov_b32_e32 v41, v87
	v_permlane32_swap_b32_e32 v18, v20
	v_permlane32_swap_b32_e32 v19, v21
	v_lshl_add_u64 v[22:23], v[34:35], 0, v[72:73]
	v_permlane32_swap_b32_e32 v85, v41
	global_store_dwordx4 v[22:23], v[18:21], off
	v_lshlrev_b32_e32 v24, 16, v40
	v_and_b32_e32 v25, 0xffff0000, v40
	v_lshlrev_b32_e32 v18, 16, v84
	v_and_b32_e32 v19, 0xffff0000, v84
	v_pk_mul_f32 v[18:19], v[26:27], v[18:19]
	v_lshlrev_b32_e32 v20, 16, v85
	v_and_b32_e32 v21, 0xffff0000, v85
	v_lshlrev_b32_e32 v26, 16, v41
	v_and_b32_e32 v27, 0xffff0000, v41
	v_pk_mul_f32 v[20:21], v[28:29], v[20:21]
	v_pk_mul_f32 v[24:25], v[30:31], v[24:25]
	v_pk_mul_f32 v[26:27], v[32:33], v[26:27]
	s_waitcnt vmcnt(6)
	v_mov_b32_e32 v42, v104
	v_cvt_pk_bf16_f32 v18, v18, v19
	v_cvt_pk_bf16_f32 v19, v20, v21
	v_cvt_pk_bf16_f32 v20, v24, v25
	v_cvt_pk_bf16_f32 v21, v26, v27
	v_permlane32_swap_b32_e32 v102, v42
	v_mov_b32_e32 v43, v105
	v_permlane32_swap_b32_e32 v18, v20
	v_permlane32_swap_b32_e32 v19, v21
	v_permlane32_swap_b32_e32 v103, v43
	global_store_dwordx4 v[22:23], v[18:21], off offset:32
	s_waitcnt vmcnt(5)
	v_mov_b32_e32 v44, v56
	v_mov_b32_e32 v45, v57
	v_lshlrev_b32_e32 v18, 16, v102
	v_and_b32_e32 v19, 0xffff0000, v102
	v_pk_mul_f32 v[2:3], v[2:3], v[18:19]
	v_lshlrev_b32_e32 v18, 16, v103
	v_and_b32_e32 v19, 0xffff0000, v103
	v_pk_mul_f32 v[4:5], v[4:5], v[18:19]
	v_lshlrev_b32_e32 v18, 16, v42
	v_and_b32_e32 v19, 0xffff0000, v42
	v_pk_mul_f32 v[6:7], v[6:7], v[18:19]
	v_lshlrev_b32_e32 v18, 16, v43
	v_and_b32_e32 v19, 0xffff0000, v43
	v_pk_mul_f32 v[8:9], v[8:9], v[18:19]
	v_cvt_pk_bf16_f32 v2, v2, v3
	v_cvt_pk_bf16_f32 v3, v4, v5
	v_cvt_pk_bf16_f32 v4, v6, v7
	v_cvt_pk_bf16_f32 v5, v8, v9
	v_permlane32_swap_b32_e32 v54, v44
	v_permlane32_swap_b32_e32 v55, v45
	v_permlane32_swap_b32_e32 v2, v4
	v_permlane32_swap_b32_e32 v3, v5
	global_store_dwordx4 v[22:23], v[2:5], off offset:64
	v_lshlrev_b32_e32 v6, 16, v44
	v_and_b32_e32 v7, 0xffff0000, v44
	v_lshlrev_b32_e32 v2, 16, v54
	v_and_b32_e32 v3, 0xffff0000, v54
	v_lshlrev_b32_e32 v4, 16, v55
	v_and_b32_e32 v5, 0xffff0000, v55
	v_lshlrev_b32_e32 v8, 16, v45
	v_and_b32_e32 v9, 0xffff0000, v45
	v_pk_mul_f32 v[2:3], v[10:11], v[2:3]
	v_pk_mul_f32 v[4:5], v[12:13], v[4:5]
	v_pk_mul_f32 v[6:7], v[14:15], v[6:7]
	v_pk_mul_f32 v[8:9], v[16:17], v[8:9]
	v_cvt_pk_bf16_f32 v2, v2, v3
	v_cvt_pk_bf16_f32 v3, v4, v5
	v_cvt_pk_bf16_f32 v4, v6, v7
	v_cvt_pk_bf16_f32 v5, v8, v9
	s_nop 0
	v_permlane32_swap_b32_e32 v2, v4
	v_permlane32_swap_b32_e32 v3, v5
	global_store_dwordx4 v[22:23], v[2:5], off offset:96
	s_cbranch_scc1 .LBB0_828

.LBB0_976:
	s_cmp_gt_i32 s52, 7
	s_cselect_b64 s[0:1], -1, 0
	s_cmp_lt_i32 s53, 8
	s_cselect_b64 s[2:3], -1, 0
	s_or_b64 s[0:1], s[0:1], s[2:3]
	s_and_b64 vcc, exec, s[0:1]
	s_cbranch_vccnz .LBB0_1048
	v_readlane_b32 s0, v248, 0
	v_readlane_b32 s16, v248, 9
	s_cmpk_gt_u32 s0, 0x2ff
	v_readlane_b32 s17, v248, 10
	v_readlane_b32 s18, v248, 11
	v_readlane_b32 s19, v248, 12
	v_readlane_b32 s20, v248, 13
	v_readlane_b32 s21, v248, 14
	v_readlane_b32 s22, v248, 15
	v_readlane_b32 s23, v248, 16
	v_readlane_b32 s24, v248, 17
	v_readlane_b32 s25, v248, 18
	v_readlane_b32 s26, v248, 19
	v_readlane_b32 s27, v248, 20
	v_readlane_b32 s28, v248, 21
	v_readlane_b32 s29, v248, 22
	v_readlane_b32 s30, v248, 23
	v_readlane_b32 s31, v248, 24
	s_cbranch_scc1 .LBB0_980
	v_readlane_b32 s1, v248, 0
	v_lshlrev_b32_e32 v2, 4, v1
	s_lshl_b32 s0, s1, 2
	v_and_b32_e32 v66, 0x70, v2
	v_mov_b32_e32 v67, 0
	s_lshr_b32 s6, s1, 3
	s_and_b32 s8, s0, 4
	s_bfe_u32 s9, s1, 0x20001
	v_lshl_add_u64 v[2:3], s[82:83], 0, v[66:67]
	s_mov_b64 s[0:1], 0xac00000
	v_lshl_add_u64 v[68:69], v[2:3], 0, s[0:1]
	s_mov_b64 s[0:1], 0x3000000
	v_lshl_add_u64 v[70:71], v[2:3], 0, s[0:1]
	v_lshrrev_b32_e32 v2, 1, v1
	v_and_b32_e32 v3, 0x1c0, v2
	v_and_b32_e32 v88, 0x5f, v1
	v_lshrrev_b32_e32 v89, 3, v1
	v_and_or_b32 v4, v1, 31, v3
	v_and_b32_e32 v2, 16, v2
	s_movk_i32 s0, 0x90
	v_mad_u32_u24 v93, v4, s0, v2
	v_mad_u32_u24 v94, v88, s0, v2
	v_mul_u32_u24_e32 v2, 0x48, v89
	v_lshl_add_u32 v95, v2, 1, v66
	v_lshrrev_b32_e32 v246, 3, v1
	v_and_b32_e32 v246, 15, v246
	v_add_u32_e32 v246, 4, v246
	v_bfe_u32 v246, v246, 3, 1
	v_and_b32_e32 v249, 1, v1
	v_lshlrev_b32_e32 v249, 1, v249
	v_sub_u32_e32 v249, 1, v249
	v_mul_i32_i24_e32 v246, v246, v249
	v_lshlrev_b32_e32 v246, 4, v246
	v_add_u32_e32 v95, v246, v95
	s_lshr_b32 s7, s50, 3
	s_mul_i32 s9, s9, 24
	v_add_u32_e32 v90, 32, v89
	v_add_u32_e32 v91, 64, v89
	v_add_u32_e32 v92, 0x60, v89
	v_add_u32_e32 v96, 0x9000, v95
	v_and_or_b32 v97, v89, 4, v3
	s_mov_b32 s1, 0
	s_mov_b32 s10, s6
	s_mov_b32 s2, s6
	s_mov_b32 s11, 0
.LBB0_979:
	s_lshr_b32 s0, s2, 2
	s_and_b32 s2, s2, 3
	s_or_b32 s2, s2, s8
	s_lshl_b32 s2, s2, 7
	v_or_b32_e32 v2, s2, v89
	v_lshlrev_b32_e32 v66, 11, v2
	s_add_i32 s0, s0, s9
	v_lshl_add_u64 v[72:73], v[68:69], 0, v[66:67]
	v_add_lshl_u32 v66, s2, v90, 11
	s_lshl_b32 s3, s0, 7
	v_lshl_add_u64 v[74:75], v[68:69], 0, v[66:67]
	v_add_lshl_u32 v66, s2, v91, 11
	v_lshl_add_u64 v[76:77], v[68:69], 0, v[66:67]
	v_add_lshl_u32 v66, s2, v92, 11
	v_or_b32_e32 v2, s3, v89
	v_lshl_add_u64 v[78:79], v[68:69], 0, v[66:67]
	v_lshlrev_b32_e32 v66, 11, v2
	v_lshl_add_u64 v[80:81], v[70:71], 0, v[66:67]
	v_add_lshl_u32 v66, s3, v90, 11
	v_lshl_add_u64 v[82:83], v[70:71], 0, v[66:67]
	v_add_lshl_u32 v66, s3, v91, 11
	v_lshl_add_u64 v[84:85], v[70:71], 0, v[66:67]
	v_add_lshl_u32 v66, s3, v92, 11
	v_lshl_add_u64 v[86:87], v[70:71], 0, v[66:67]
	global_load_dwordx4 v[2:5], v[72:73], off
	global_load_dwordx4 v[6:9], v[74:75], off
	global_load_dwordx4 v[10:13], v[76:77], off
	global_load_dwordx4 v[14:17], v[78:79], off
	global_load_dwordx4 v[18:21], v[80:81], off
	global_load_dwordx4 v[22:25], v[82:83], off
	global_load_dwordx4 v[26:29], v[84:85], off
	global_load_dwordx4 v[30:33], v[86:87], off
	global_load_dwordx4 v[98:101], v[72:73], off offset:128
	global_load_dwordx4 v[102:105], v[74:75], off offset:128
	global_load_dwordx4 v[106:109], v[76:77], off offset:128
	global_load_dwordx4 v[110:113], v[78:79], off offset:128
	global_load_dwordx4 v[114:117], v[80:81], off offset:128
	global_load_dwordx4 v[118:121], v[82:83], off offset:128
	global_load_dwordx4 v[122:125], v[84:85], off offset:128
	global_load_dwordx4 v[126:129], v[86:87], off offset:128
	s_waitcnt vmcnt(15)
	ds_write_b128 v95, v[2:5]
	s_waitcnt vmcnt(14)
	ds_write_b128 v95, v[6:9] offset:4608
	s_waitcnt vmcnt(13)
	ds_write_b128 v95, v[10:13] offset:9216
	s_waitcnt vmcnt(12)
	ds_write_b128 v95, v[14:17] offset:13824
	s_waitcnt vmcnt(11)
	ds_write_b128 v95, v[18:21] offset:36864
	s_waitcnt vmcnt(10)
	ds_write_b128 v95, v[22:25] offset:41472
	s_waitcnt vmcnt(9)
	ds_write_b128 v95, v[26:29] offset:46080
	s_waitcnt vmcnt(8)
	ds_write_b128 v95, v[30:33] offset:50688
	s_waitcnt lgkmcnt(0)
	s_barrier
	global_load_dwordx4 v[136:139], v[72:73], off offset:256
	global_load_dwordx4 v[140:143], v[74:75], off offset:256
	global_load_dwordx4 v[144:147], v[76:77], off offset:256
	global_load_dwordx4 v[148:151], v[78:79], off offset:256
	global_load_dwordx4 v[152:155], v[80:81], off offset:256
	global_load_dwordx4 v[156:159], v[82:83], off offset:256
	global_load_dwordx4 v[160:163], v[84:85], off offset:256
	global_load_dwordx4 v[164:167], v[86:87], off offset:256
	v_and_b32_e32 v246, 15, v1
	v_add_u32_e32 v246, 4, v246
	v_bfe_u32 v246, v246, 3, 1
	v_bfe_u32 v249, v1, 4, 2
	v_xor_b32_e32 v246, v246, v249
	v_bfe_u32 v249, v1, 5, 1
	v_sub_u32_e32 v246, v246, v249
	v_lshlrev_b32_e32 v246, 4, v246
	v_bfe_u32 v249, v1, 4, 1
	v_mul_u32_u24_e32 v249, 0x900, v249
	v_sub_u32_e32 v246, v246, v249
	v_add_u32_e32 v244, v246, v93
	v_add_u32_e32 v245, v246, v94
	ds_read_b128 v[212:215], v245 offset:36864
	ds_read_b128 v[196:199], v244
	ds_read_b128 v[216:219], v245 offset:39168
	ds_read_b128 v[220:223], v245 offset:41472
	ds_read_b128 v[224:227], v245 offset:43776
	ds_read_b128 v[200:203], v244 offset:2304
	ds_read_b128 v[204:207], v244 offset:4608
	ds_read_b128 v[208:211], v244 offset:6912
	s_waitcnt lgkmcnt(6)
	v_mfma_f32_16x16x32_bf16 v[34:37], v[196:199], v[212:215], 0
	ds_read_b128 v[228:231], v245 offset:36928
	s_waitcnt lgkmcnt(6)
	v_mfma_f32_16x16x32_bf16 v[38:41], v[196:199], v[216:219], 0
	ds_read_b128 v[232:235], v245 offset:39232
	s_waitcnt lgkmcnt(6)
	v_mfma_f32_16x16x32_bf16 v[2:5], v[196:199], v[220:223], 0
	ds_read_b128 v[236:239], v245 offset:41536
	s_waitcnt lgkmcnt(6)
	v_mfma_f32_16x16x32_bf16 v[6:9], v[196:199], v[224:227], 0
	ds_read_b128 v[240:243], v245 offset:43840
	ds_read_b128 v[196:199], v244 offset:64
	s_waitcnt lgkmcnt(7)
	v_mfma_f32_16x16x32_bf16 v[42:45], v[200:203], v[212:215], 0
	v_mfma_f32_16x16x32_bf16 v[46:49], v[200:203], v[216:219], 0
	v_mfma_f32_16x16x32_bf16 v[10:13], v[200:203], v[220:223], 0
	v_mfma_f32_16x16x32_bf16 v[14:17], v[200:203], v[224:227], 0
	ds_read_b128 v[200:203], v244 offset:2368
	s_waitcnt lgkmcnt(7)
	v_mfma_f32_16x16x32_bf16 v[50:53], v[204:207], v[212:215], 0
	v_mfma_f32_16x16x32_bf16 v[54:57], v[204:207], v[216:219], 0
	v_mfma_f32_16x16x32_bf16 v[18:21], v[204:207], v[220:223], 0
	v_mfma_f32_16x16x32_bf16 v[22:25], v[204:207], v[224:227], 0
	ds_read_b128 v[204:207], v244 offset:4672
	s_waitcnt vmcnt(15)
	ds_write_b128 v95, v[98:101] offset:18432
	s_waitcnt vmcnt(14)
	ds_write_b128 v95, v[102:105] offset:23040
	s_waitcnt lgkmcnt(9)
	v_mfma_f32_16x16x32_bf16 v[58:61], v[208:211], v[212:215], 0
	v_mfma_f32_16x16x32_bf16 v[62:65], v[208:211], v[216:219], 0
	v_mfma_f32_16x16x32_bf16 v[26:29], v[208:211], v[220:223], 0
	v_mfma_f32_16x16x32_bf16 v[30:33], v[208:211], v[224:227], 0
	ds_read_b128 v[208:211], v244 offset:6976
	s_waitcnt vmcnt(13)
	ds_write_b128 v95, v[106:109] offset:27648
	s_waitcnt vmcnt(12)
	ds_write_b128 v95, v[110:113] offset:32256
	s_waitcnt lgkmcnt(7)
	v_mfma_f32_16x16x32_bf16 v[34:37], v[196:199], v[228:231], v[34:37]
	v_mfma_f32_16x16x32_bf16 v[38:41], v[196:199], v[232:235], v[38:41]
	v_mfma_f32_16x16x32_bf16 v[2:5], v[196:199], v[236:239], v[2:5]
	v_mfma_f32_16x16x32_bf16 v[6:9], v[196:199], v[240:243], v[6:9]
	s_waitcnt vmcnt(11)
	ds_write_b128 v95, v[114:117] offset:55296
	s_waitcnt vmcnt(10)
	ds_write_b128 v95, v[118:121] offset:59904
	s_waitcnt lgkmcnt(8)
	v_mfma_f32_16x16x32_bf16 v[42:45], v[200:203], v[228:231], v[42:45]
	v_mfma_f32_16x16x32_bf16 v[46:49], v[200:203], v[232:235], v[46:49]
	v_mfma_f32_16x16x32_bf16 v[10:13], v[200:203], v[236:239], v[10:13]
	v_mfma_f32_16x16x32_bf16 v[14:17], v[200:203], v[240:243], v[14:17]
	s_waitcnt vmcnt(9)
	ds_write_b128 v95, v[122:125] offset:64512
	s_waitcnt vmcnt(8)
	ds_write_b128 v96, v[126:129] offset:32256
	s_waitcnt lgkmcnt(9)
	v_mfma_f32_16x16x32_bf16 v[50:53], v[204:207], v[228:231], v[50:53]
	v_mfma_f32_16x16x32_bf16 v[54:57], v[204:207], v[232:235], v[54:57]
	v_mfma_f32_16x16x32_bf16 v[18:21], v[204:207], v[236:239], v[18:21]
	v_mfma_f32_16x16x32_bf16 v[22:25], v[204:207], v[240:243], v[22:25]
	s_waitcnt lgkmcnt(6)
	v_mfma_f32_16x16x32_bf16 v[58:61], v[208:211], v[228:231], v[58:61]
	v_mfma_f32_16x16x32_bf16 v[62:65], v[208:211], v[232:235], v[62:65]
	v_mfma_f32_16x16x32_bf16 v[26:29], v[208:211], v[236:239], v[26:29]
	v_mfma_f32_16x16x32_bf16 v[30:33], v[208:211], v[240:243], v[30:33]
	s_waitcnt lgkmcnt(0)
	s_barrier
	global_load_dwordx4 v[98:101], v[72:73], off offset:384
	global_load_dwordx4 v[102:105], v[74:75], off offset:384
	global_load_dwordx4 v[106:109], v[76:77], off offset:384
	global_load_dwordx4 v[110:113], v[78:79], off offset:384
	global_load_dwordx4 v[114:117], v[80:81], off offset:384
	global_load_dwordx4 v[118:121], v[82:83], off offset:384
	global_load_dwordx4 v[122:125], v[84:85], off offset:384
	global_load_dwordx4 v[126:129], v[86:87], off offset:384
	ds_read_b128 v[212:215], v245 offset:55296
	ds_read_b128 v[196:199], v244 offset:18432
	ds_read_b128 v[216:219], v245 offset:57600
	ds_read_b128 v[220:223], v245 offset:59904
	ds_read_b128 v[224:227], v245 offset:62208
	ds_read_b128 v[200:203], v244 offset:20736
	ds_read_b128 v[204:207], v244 offset:23040
	ds_read_b128 v[208:211], v244 offset:25344
	s_waitcnt lgkmcnt(6)
	v_mfma_f32_16x16x32_bf16 v[34:37], v[196:199], v[212:215], v[34:37]
	ds_read_b128 v[228:231], v245 offset:55360
	s_waitcnt lgkmcnt(6)
	v_mfma_f32_16x16x32_bf16 v[38:41], v[196:199], v[216:219], v[38:41]
	ds_read_b128 v[232:235], v245 offset:57664
	s_waitcnt lgkmcnt(6)
	v_mfma_f32_16x16x32_bf16 v[2:5], v[196:199], v[220:223], v[2:5]
	ds_read_b128 v[236:239], v245 offset:59968
	s_waitcnt lgkmcnt(6)
	v_mfma_f32_16x16x32_bf16 v[6:9], v[196:199], v[224:227], v[6:9]
	ds_read_b128 v[240:243], v245 offset:62272
	ds_read_b128 v[196:199], v244 offset:18496
	s_waitcnt lgkmcnt(7)
	v_mfma_f32_16x16x32_bf16 v[42:45], v[200:203], v[212:215], v[42:45]
	v_mfma_f32_16x16x32_bf16 v[46:49], v[200:203], v[216:219], v[46:49]
	v_mfma_f32_16x16x32_bf16 v[10:13], v[200:203], v[220:223], v[10:13]
	v_mfma_f32_16x16x32_bf16 v[14:17], v[200:203], v[224:227], v[14:17]
	ds_read_b128 v[200:203], v244 offset:20800
	s_waitcnt lgkmcnt(7)
	v_mfma_f32_16x16x32_bf16 v[50:53], v[204:207], v[212:215], v[50:53]
	v_mfma_f32_16x16x32_bf16 v[54:57], v[204:207], v[216:219], v[54:57]
	v_mfma_f32_16x16x32_bf16 v[18:21], v[204:207], v[220:223], v[18:21]
	v_mfma_f32_16x16x32_bf16 v[22:25], v[204:207], v[224:227], v[22:25]
	ds_read_b128 v[204:207], v244 offset:23104
	s_waitcnt vmcnt(15)
	ds_write_b128 v95, v[136:139]
	s_waitcnt vmcnt(14)
	ds_write_b128 v95, v[140:143] offset:4608
	s_waitcnt lgkmcnt(9)
	v_mfma_f32_16x16x32_bf16 v[58:61], v[208:211], v[212:215], v[58:61]
	v_mfma_f32_16x16x32_bf16 v[62:65], v[208:211], v[216:219], v[62:65]
	v_mfma_f32_16x16x32_bf16 v[26:29], v[208:211], v[220:223], v[26:29]
	v_mfma_f32_16x16x32_bf16 v[30:33], v[208:211], v[224:227], v[30:33]
	ds_read_b128 v[208:211], v244 offset:25408
	s_waitcnt vmcnt(13)
	ds_write_b128 v95, v[144:147] offset:9216
	s_waitcnt vmcnt(12)
	ds_write_b128 v95, v[148:151] offset:13824
	s_waitcnt lgkmcnt(7)
	v_mfma_f32_16x16x32_bf16 v[34:37], v[196:199], v[228:231], v[34:37]
	v_mfma_f32_16x16x32_bf16 v[38:41], v[196:199], v[232:235], v[38:41]
	v_mfma_f32_16x16x32_bf16 v[2:5], v[196:199], v[236:239], v[2:5]
	v_mfma_f32_16x16x32_bf16 v[6:9], v[196:199], v[240:243], v[6:9]
	s_waitcnt vmcnt(11)
	ds_write_b128 v95, v[152:155] offset:36864
	s_waitcnt vmcnt(10)
	ds_write_b128 v95, v[156:159] offset:41472
	s_waitcnt lgkmcnt(8)
	v_mfma_f32_16x16x32_bf16 v[42:45], v[200:203], v[228:231], v[42:45]
	v_mfma_f32_16x16x32_bf16 v[46:49], v[200:203], v[232:235], v[46:49]
	v_mfma_f32_16x16x32_bf16 v[10:13], v[200:203], v[236:239], v[10:13]
	v_mfma_f32_16x16x32_bf16 v[14:17], v[200:203], v[240:243], v[14:17]
	s_waitcnt vmcnt(9)
	ds_write_b128 v95, v[160:163] offset:46080
	s_waitcnt vmcnt(8)
	ds_write_b128 v95, v[164:167] offset:50688
	s_waitcnt lgkmcnt(9)
	v_mfma_f32_16x16x32_bf16 v[50:53], v[204:207], v[228:231], v[50:53]
	v_mfma_f32_16x16x32_bf16 v[54:57], v[204:207], v[232:235], v[54:57]
	v_mfma_f32_16x16x32_bf16 v[18:21], v[204:207], v[236:239], v[18:21]
	v_mfma_f32_16x16x32_bf16 v[22:25], v[204:207], v[240:243], v[22:25]
	s_waitcnt lgkmcnt(6)
	v_mfma_f32_16x16x32_bf16 v[58:61], v[208:211], v[228:231], v[58:61]
	v_mfma_f32_16x16x32_bf16 v[62:65], v[208:211], v[232:235], v[62:65]
	v_mfma_f32_16x16x32_bf16 v[26:29], v[208:211], v[236:239], v[26:29]
	v_mfma_f32_16x16x32_bf16 v[30:33], v[208:211], v[240:243], v[30:33]
	s_waitcnt lgkmcnt(0)
	s_barrier
	global_load_dwordx4 v[136:139], v[72:73], off offset:512
	global_load_dwordx4 v[140:143], v[74:75], off offset:512
	global_load_dwordx4 v[144:147], v[76:77], off offset:512
	global_load_dwordx4 v[148:151], v[78:79], off offset:512
	global_load_dwordx4 v[152:155], v[80:81], off offset:512
	global_load_dwordx4 v[156:159], v[82:83], off offset:512
	global_load_dwordx4 v[160:163], v[84:85], off offset:512
	global_load_dwordx4 v[164:167], v[86:87], off offset:512
	ds_read_b128 v[212:215], v245 offset:36864
	ds_read_b128 v[196:199], v244
	ds_read_b128 v[216:219], v245 offset:39168
	ds_read_b128 v[220:223], v245 offset:41472
	ds_read_b128 v[224:227], v245 offset:43776
	ds_read_b128 v[200:203], v244 offset:2304
	ds_read_b128 v[204:207], v244 offset:4608
	ds_read_b128 v[208:211], v244 offset:6912
	s_waitcnt lgkmcnt(6)
	v_mfma_f32_16x16x32_bf16 v[34:37], v[196:199], v[212:215], v[34:37]
	ds_read_b128 v[228:231], v245 offset:36928
	s_waitcnt lgkmcnt(6)
	v_mfma_f32_16x16x32_bf16 v[38:41], v[196:199], v[216:219], v[38:41]
	ds_read_b128 v[232:235], v245 offset:39232
	s_waitcnt lgkmcnt(6)
	v_mfma_f32_16x16x32_bf16 v[2:5], v[196:199], v[220:223], v[2:5]
	ds_read_b128 v[236:239], v245 offset:41536
	s_waitcnt lgkmcnt(6)
	v_mfma_f32_16x16x32_bf16 v[6:9], v[196:199], v[224:227], v[6:9]
	ds_read_b128 v[240:243], v245 offset:43840
	ds_read_b128 v[196:199], v244 offset:64
	s_waitcnt lgkmcnt(7)
	v_mfma_f32_16x16x32_bf16 v[42:45], v[200:203], v[212:215], v[42:45]
	v_mfma_f32_16x16x32_bf16 v[46:49], v[200:203], v[216:219], v[46:49]
	v_mfma_f32_16x16x32_bf16 v[10:13], v[200:203], v[220:223], v[10:13]
	v_mfma_f32_16x16x32_bf16 v[14:17], v[200:203], v[224:227], v[14:17]
	ds_read_b128 v[200:203], v244 offset:2368
	s_waitcnt lgkmcnt(7)
	v_mfma_f32_16x16x32_bf16 v[50:53], v[204:207], v[212:215], v[50:53]
	v_mfma_f32_16x16x32_bf16 v[54:57], v[204:207], v[216:219], v[54:57]
	v_mfma_f32_16x16x32_bf16 v[18:21], v[204:207], v[220:223], v[18:21]
	v_mfma_f32_16x16x32_bf16 v[22:25], v[204:207], v[224:227], v[22:25]
	ds_read_b128 v[204:207], v244 offset:4672
	s_waitcnt vmcnt(15)
	ds_write_b128 v95, v[98:101] offset:18432
	s_waitcnt vmcnt(14)
	ds_write_b128 v95, v[102:105] offset:23040
	s_waitcnt lgkmcnt(9)
	v_mfma_f32_16x16x32_bf16 v[58:61], v[208:211], v[212:215], v[58:61]
	v_mfma_f32_16x16x32_bf16 v[62:65], v[208:211], v[216:219], v[62:65]
	v_mfma_f32_16x16x32_bf16 v[26:29], v[208:211], v[220:223], v[26:29]
	v_mfma_f32_16x16x32_bf16 v[30:33], v[208:211], v[224:227], v[30:33]
	ds_read_b128 v[208:211], v244 offset:6976
	s_waitcnt vmcnt(13)
	ds_write_b128 v95, v[106:109] offset:27648
	s_waitcnt vmcnt(12)
	ds_write_b128 v95, v[110:113] offset:32256
	s_waitcnt lgkmcnt(7)
	v_mfma_f32_16x16x32_bf16 v[34:37], v[196:199], v[228:231], v[34:37]
	v_mfma_f32_16x16x32_bf16 v[38:41], v[196:199], v[232:235], v[38:41]
	v_mfma_f32_16x16x32_bf16 v[2:5], v[196:199], v[236:239], v[2:5]
	v_mfma_f32_16x16x32_bf16 v[6:9], v[196:199], v[240:243], v[6:9]
	s_waitcnt vmcnt(11)
	ds_write_b128 v95, v[114:117] offset:55296
	s_waitcnt vmcnt(10)
	ds_write_b128 v95, v[118:121] offset:59904
	s_waitcnt lgkmcnt(8)
	v_mfma_f32_16x16x32_bf16 v[42:45], v[200:203], v[228:231], v[42:45]
	v_mfma_f32_16x16x32_bf16 v[46:49], v[200:203], v[232:235], v[46:49]
	v_mfma_f32_16x16x32_bf16 v[10:13], v[200:203], v[236:239], v[10:13]
	v_mfma_f32_16x16x32_bf16 v[14:17], v[200:203], v[240:243], v[14:17]
	s_waitcnt vmcnt(9)
	ds_write_b128 v95, v[122:125] offset:64512
	s_waitcnt vmcnt(8)
	ds_write_b128 v96, v[126:129] offset:32256
	s_waitcnt lgkmcnt(9)
	v_mfma_f32_16x16x32_bf16 v[50:53], v[204:207], v[228:231], v[50:53]
	v_mfma_f32_16x16x32_bf16 v[54:57], v[204:207], v[232:235], v[54:57]
	v_mfma_f32_16x16x32_bf16 v[18:21], v[204:207], v[236:239], v[18:21]
	v_mfma_f32_16x16x32_bf16 v[22:25], v[204:207], v[240:243], v[22:25]
	s_waitcnt lgkmcnt(6)
	v_mfma_f32_16x16x32_bf16 v[58:61], v[208:211], v[228:231], v[58:61]
	v_mfma_f32_16x16x32_bf16 v[62:65], v[208:211], v[232:235], v[62:65]
	v_mfma_f32_16x16x32_bf16 v[26:29], v[208:211], v[236:239], v[26:29]
	v_mfma_f32_16x16x32_bf16 v[30:33], v[208:211], v[240:243], v[30:33]
	s_waitcnt lgkmcnt(0)
	s_barrier
	global_load_dwordx4 v[98:101], v[72:73], off offset:640
	global_load_dwordx4 v[102:105], v[74:75], off offset:640
	global_load_dwordx4 v[106:109], v[76:77], off offset:640
	global_load_dwordx4 v[110:113], v[78:79], off offset:640
	global_load_dwordx4 v[114:117], v[80:81], off offset:640
	global_load_dwordx4 v[118:121], v[82:83], off offset:640
	global_load_dwordx4 v[122:125], v[84:85], off offset:640
	global_load_dwordx4 v[126:129], v[86:87], off offset:640
	ds_read_b128 v[212:215], v245 offset:55296
	ds_read_b128 v[196:199], v244 offset:18432
	ds_read_b128 v[216:219], v245 offset:57600
	ds_read_b128 v[220:223], v245 offset:59904
	ds_read_b128 v[224:227], v245 offset:62208
	ds_read_b128 v[200:203], v244 offset:20736
	ds_read_b128 v[204:207], v244 offset:23040
	ds_read_b128 v[208:211], v244 offset:25344
	s_waitcnt lgkmcnt(6)
	v_mfma_f32_16x16x32_bf16 v[34:37], v[196:199], v[212:215], v[34:37]
	ds_read_b128 v[228:231], v245 offset:55360
	s_waitcnt lgkmcnt(6)
	v_mfma_f32_16x16x32_bf16 v[38:41], v[196:199], v[216:219], v[38:41]
	ds_read_b128 v[232:235], v245 offset:57664
	s_waitcnt lgkmcnt(6)
	v_mfma_f32_16x16x32_bf16 v[2:5], v[196:199], v[220:223], v[2:5]
	ds_read_b128 v[236:239], v245 offset:59968
	s_waitcnt lgkmcnt(6)
	v_mfma_f32_16x16x32_bf16 v[6:9], v[196:199], v[224:227], v[6:9]
	ds_read_b128 v[240:243], v245 offset:62272
	ds_read_b128 v[196:199], v244 offset:18496
	s_waitcnt lgkmcnt(7)
	v_mfma_f32_16x16x32_bf16 v[42:45], v[200:203], v[212:215], v[42:45]
	v_mfma_f32_16x16x32_bf16 v[46:49], v[200:203], v[216:219], v[46:49]
	v_mfma_f32_16x16x32_bf16 v[10:13], v[200:203], v[220:223], v[10:13]
	v_mfma_f32_16x16x32_bf16 v[14:17], v[200:203], v[224:227], v[14:17]
	ds_read_b128 v[200:203], v244 offset:20800
	s_waitcnt lgkmcnt(7)
	v_mfma_f32_16x16x32_bf16 v[50:53], v[204:207], v[212:215], v[50:53]
	v_mfma_f32_16x16x32_bf16 v[54:57], v[204:207], v[216:219], v[54:57]
	v_mfma_f32_16x16x32_bf16 v[18:21], v[204:207], v[220:223], v[18:21]
	v_mfma_f32_16x16x32_bf16 v[22:25], v[204:207], v[224:227], v[22:25]
	ds_read_b128 v[204:207], v244 offset:23104
	s_waitcnt vmcnt(15)
	ds_write_b128 v95, v[136:139]
	s_waitcnt vmcnt(14)
	ds_write_b128 v95, v[140:143] offset:4608
	s_waitcnt lgkmcnt(9)
	v_mfma_f32_16x16x32_bf16 v[58:61], v[208:211], v[212:215], v[58:61]
	v_mfma_f32_16x16x32_bf16 v[62:65], v[208:211], v[216:219], v[62:65]
	v_mfma_f32_16x16x32_bf16 v[26:29], v[208:211], v[220:223], v[26:29]
	v_mfma_f32_16x16x32_bf16 v[30:33], v[208:211], v[224:227], v[30:33]
	ds_read_b128 v[208:211], v244 offset:25408
	s_waitcnt vmcnt(13)
	ds_write_b128 v95, v[144:147] offset:9216
	s_waitcnt vmcnt(12)
	ds_write_b128 v95, v[148:151] offset:13824
	s_waitcnt lgkmcnt(7)
	v_mfma_f32_16x16x32_bf16 v[34:37], v[196:199], v[228:231], v[34:37]
	v_mfma_f32_16x16x32_bf16 v[38:41], v[196:199], v[232:235], v[38:41]
	v_mfma_f32_16x16x32_bf16 v[2:5], v[196:199], v[236:239], v[2:5]
	v_mfma_f32_16x16x32_bf16 v[6:9], v[196:199], v[240:243], v[6:9]
	s_waitcnt vmcnt(11)
	ds_write_b128 v95, v[152:155] offset:36864
	s_waitcnt vmcnt(10)
	ds_write_b128 v95, v[156:159] offset:41472
	s_waitcnt lgkmcnt(8)
	v_mfma_f32_16x16x32_bf16 v[42:45], v[200:203], v[228:231], v[42:45]
	v_mfma_f32_16x16x32_bf16 v[46:49], v[200:203], v[232:235], v[46:49]
	v_mfma_f32_16x16x32_bf16 v[10:13], v[200:203], v[236:239], v[10:13]
	v_mfma_f32_16x16x32_bf16 v[14:17], v[200:203], v[240:243], v[14:17]
	s_waitcnt vmcnt(9)
	ds_write_b128 v95, v[160:163] offset:46080
	s_waitcnt vmcnt(8)
	ds_write_b128 v95, v[164:167] offset:50688
	s_waitcnt lgkmcnt(9)
	v_mfma_f32_16x16x32_bf16 v[50:53], v[204:207], v[228:231], v[50:53]
	v_mfma_f32_16x16x32_bf16 v[54:57], v[204:207], v[232:235], v[54:57]
	v_mfma_f32_16x16x32_bf16 v[18:21], v[204:207], v[236:239], v[18:21]
	v_mfma_f32_16x16x32_bf16 v[22:25], v[204:207], v[240:243], v[22:25]
	s_waitcnt lgkmcnt(6)
	v_mfma_f32_16x16x32_bf16 v[58:61], v[208:211], v[228:231], v[58:61]
	v_mfma_f32_16x16x32_bf16 v[62:65], v[208:211], v[232:235], v[62:65]
	v_mfma_f32_16x16x32_bf16 v[26:29], v[208:211], v[236:239], v[26:29]
	v_mfma_f32_16x16x32_bf16 v[30:33], v[208:211], v[240:243], v[30:33]
	s_waitcnt lgkmcnt(0)
	s_barrier
	global_load_dwordx4 v[136:139], v[72:73], off offset:768
	global_load_dwordx4 v[140:143], v[74:75], off offset:768
	global_load_dwordx4 v[144:147], v[76:77], off offset:768
	global_load_dwordx4 v[148:151], v[78:79], off offset:768
	global_load_dwordx4 v[152:155], v[80:81], off offset:768
	global_load_dwordx4 v[156:159], v[82:83], off offset:768
	global_load_dwordx4 v[160:163], v[84:85], off offset:768
	global_load_dwordx4 v[164:167], v[86:87], off offset:768
	ds_read_b128 v[212:215], v245 offset:36864
	ds_read_b128 v[196:199], v244
	ds_read_b128 v[216:219], v245 offset:39168
	ds_read_b128 v[220:223], v245 offset:41472
	ds_read_b128 v[224:227], v245 offset:43776
	ds_read_b128 v[200:203], v244 offset:2304
	ds_read_b128 v[204:207], v244 offset:4608
	ds_read_b128 v[208:211], v244 offset:6912
	s_waitcnt lgkmcnt(6)
	v_mfma_f32_16x16x32_bf16 v[34:37], v[196:199], v[212:215], v[34:37]
	ds_read_b128 v[228:231], v245 offset:36928
	s_waitcnt lgkmcnt(6)
	v_mfma_f32_16x16x32_bf16 v[38:41], v[196:199], v[216:219], v[38:41]
	ds_read_b128 v[232:235], v245 offset:39232
	s_waitcnt lgkmcnt(6)
	v_mfma_f32_16x16x32_bf16 v[2:5], v[196:199], v[220:223], v[2:5]
	ds_read_b128 v[236:239], v245 offset:41536
	s_waitcnt lgkmcnt(6)
	v_mfma_f32_16x16x32_bf16 v[6:9], v[196:199], v[224:227], v[6:9]
	ds_read_b128 v[240:243], v245 offset:43840
	ds_read_b128 v[196:199], v244 offset:64
	s_waitcnt lgkmcnt(7)
	v_mfma_f32_16x16x32_bf16 v[42:45], v[200:203], v[212:215], v[42:45]
	v_mfma_f32_16x16x32_bf16 v[46:49], v[200:203], v[216:219], v[46:49]
	v_mfma_f32_16x16x32_bf16 v[10:13], v[200:203], v[220:223], v[10:13]
	v_mfma_f32_16x16x32_bf16 v[14:17], v[200:203], v[224:227], v[14:17]
	ds_read_b128 v[200:203], v244 offset:2368
	s_waitcnt lgkmcnt(7)
	v_mfma_f32_16x16x32_bf16 v[50:53], v[204:207], v[212:215], v[50:53]
	v_mfma_f32_16x16x32_bf16 v[54:57], v[204:207], v[216:219], v[54:57]
	v_mfma_f32_16x16x32_bf16 v[18:21], v[204:207], v[220:223], v[18:21]
	v_mfma_f32_16x16x32_bf16 v[22:25], v[204:207], v[224:227], v[22:25]
	ds_read_b128 v[204:207], v244 offset:4672
	s_waitcnt vmcnt(15)
	ds_write_b128 v95, v[98:101] offset:18432
	s_waitcnt vmcnt(14)
	ds_write_b128 v95, v[102:105] offset:23040
	s_waitcnt lgkmcnt(9)
	v_mfma_f32_16x16x32_bf16 v[58:61], v[208:211], v[212:215], v[58:61]
	v_mfma_f32_16x16x32_bf16 v[62:65], v[208:211], v[216:219], v[62:65]
	v_mfma_f32_16x16x32_bf16 v[26:29], v[208:211], v[220:223], v[26:29]
	v_mfma_f32_16x16x32_bf16 v[30:33], v[208:211], v[224:227], v[30:33]
	ds_read_b128 v[208:211], v244 offset:6976
	s_waitcnt vmcnt(13)
	ds_write_b128 v95, v[106:109] offset:27648
	s_waitcnt vmcnt(12)
	ds_write_b128 v95, v[110:113] offset:32256
	s_waitcnt lgkmcnt(7)
	v_mfma_f32_16x16x32_bf16 v[34:37], v[196:199], v[228:231], v[34:37]
	v_mfma_f32_16x16x32_bf16 v[38:41], v[196:199], v[232:235], v[38:41]
	v_mfma_f32_16x16x32_bf16 v[2:5], v[196:199], v[236:239], v[2:5]
	v_mfma_f32_16x16x32_bf16 v[6:9], v[196:199], v[240:243], v[6:9]
	s_waitcnt vmcnt(11)
	ds_write_b128 v95, v[114:117] offset:55296
	s_waitcnt vmcnt(10)
	ds_write_b128 v95, v[118:121] offset:59904
	s_waitcnt lgkmcnt(8)
	v_mfma_f32_16x16x32_bf16 v[42:45], v[200:203], v[228:231], v[42:45]
	v_mfma_f32_16x16x32_bf16 v[46:49], v[200:203], v[232:235], v[46:49]
	v_mfma_f32_16x16x32_bf16 v[10:13], v[200:203], v[236:239], v[10:13]
	v_mfma_f32_16x16x32_bf16 v[14:17], v[200:203], v[240:243], v[14:17]
	s_waitcnt vmcnt(9)
	ds_write_b128 v95, v[122:125] offset:64512
	s_waitcnt vmcnt(8)
	ds_write_b128 v96, v[126:129] offset:32256
	s_waitcnt lgkmcnt(9)
	v_mfma_f32_16x16x32_bf16 v[50:53], v[204:207], v[228:231], v[50:53]
	v_mfma_f32_16x16x32_bf16 v[54:57], v[204:207], v[232:235], v[54:57]
	v_mfma_f32_16x16x32_bf16 v[18:21], v[204:207], v[236:239], v[18:21]
	v_mfma_f32_16x16x32_bf16 v[22:25], v[204:207], v[240:243], v[22:25]
	s_waitcnt lgkmcnt(6)
	v_mfma_f32_16x16x32_bf16 v[58:61], v[208:211], v[228:231], v[58:61]
	v_mfma_f32_16x16x32_bf16 v[62:65], v[208:211], v[232:235], v[62:65]
	v_mfma_f32_16x16x32_bf16 v[26:29], v[208:211], v[236:239], v[26:29]
	v_mfma_f32_16x16x32_bf16 v[30:33], v[208:211], v[240:243], v[30:33]
	s_waitcnt lgkmcnt(0)
	s_barrier
	global_load_dwordx4 v[98:101], v[72:73], off offset:896
	global_load_dwordx4 v[102:105], v[74:75], off offset:896
	global_load_dwordx4 v[106:109], v[76:77], off offset:896
	global_load_dwordx4 v[110:113], v[78:79], off offset:896
	global_load_dwordx4 v[114:117], v[80:81], off offset:896
	global_load_dwordx4 v[118:121], v[82:83], off offset:896
	global_load_dwordx4 v[122:125], v[84:85], off offset:896
	global_load_dwordx4 v[126:129], v[86:87], off offset:896
	ds_read_b128 v[212:215], v245 offset:55296
	ds_read_b128 v[196:199], v244 offset:18432
	ds_read_b128 v[216:219], v245 offset:57600
	ds_read_b128 v[220:223], v245 offset:59904
	ds_read_b128 v[224:227], v245 offset:62208
	ds_read_b128 v[200:203], v244 offset:20736
	ds_read_b128 v[204:207], v244 offset:23040
	ds_read_b128 v[208:211], v244 offset:25344
	s_waitcnt lgkmcnt(6)
	v_mfma_f32_16x16x32_bf16 v[34:37], v[196:199], v[212:215], v[34:37]
	ds_read_b128 v[228:231], v245 offset:55360
	s_waitcnt lgkmcnt(6)
	v_mfma_f32_16x16x32_bf16 v[38:41], v[196:199], v[216:219], v[38:41]
	ds_read_b128 v[232:235], v245 offset:57664
	s_waitcnt lgkmcnt(6)
	v_mfma_f32_16x16x32_bf16 v[2:5], v[196:199], v[220:223], v[2:5]
	ds_read_b128 v[236:239], v245 offset:59968
	s_waitcnt lgkmcnt(6)
	v_mfma_f32_16x16x32_bf16 v[6:9], v[196:199], v[224:227], v[6:9]
	ds_read_b128 v[240:243], v245 offset:62272
	ds_read_b128 v[196:199], v244 offset:18496
	s_waitcnt lgkmcnt(7)
	v_mfma_f32_16x16x32_bf16 v[42:45], v[200:203], v[212:215], v[42:45]
	v_mfma_f32_16x16x32_bf16 v[46:49], v[200:203], v[216:219], v[46:49]
	v_mfma_f32_16x16x32_bf16 v[10:13], v[200:203], v[220:223], v[10:13]
	v_mfma_f32_16x16x32_bf16 v[14:17], v[200:203], v[224:227], v[14:17]
	ds_read_b128 v[200:203], v244 offset:20800
	s_waitcnt lgkmcnt(7)
	v_mfma_f32_16x16x32_bf16 v[50:53], v[204:207], v[212:215], v[50:53]
	v_mfma_f32_16x16x32_bf16 v[54:57], v[204:207], v[216:219], v[54:57]
	v_mfma_f32_16x16x32_bf16 v[18:21], v[204:207], v[220:223], v[18:21]
	v_mfma_f32_16x16x32_bf16 v[22:25], v[204:207], v[224:227], v[22:25]
	ds_read_b128 v[204:207], v244 offset:23104
	s_waitcnt vmcnt(15)
	ds_write_b128 v95, v[136:139]
	s_waitcnt vmcnt(14)
	ds_write_b128 v95, v[140:143] offset:4608
	s_waitcnt lgkmcnt(9)
	v_mfma_f32_16x16x32_bf16 v[58:61], v[208:211], v[212:215], v[58:61]
	v_mfma_f32_16x16x32_bf16 v[62:65], v[208:211], v[216:219], v[62:65]
	v_mfma_f32_16x16x32_bf16 v[26:29], v[208:211], v[220:223], v[26:29]
	v_mfma_f32_16x16x32_bf16 v[30:33], v[208:211], v[224:227], v[30:33]
	ds_read_b128 v[208:211], v244 offset:25408
	s_waitcnt vmcnt(13)
	ds_write_b128 v95, v[144:147] offset:9216
	s_waitcnt vmcnt(12)
	ds_write_b128 v95, v[148:151] offset:13824
	s_waitcnt lgkmcnt(7)
	v_mfma_f32_16x16x32_bf16 v[34:37], v[196:199], v[228:231], v[34:37]
	v_mfma_f32_16x16x32_bf16 v[38:41], v[196:199], v[232:235], v[38:41]
	v_mfma_f32_16x16x32_bf16 v[2:5], v[196:199], v[236:239], v[2:5]
	v_mfma_f32_16x16x32_bf16 v[6:9], v[196:199], v[240:243], v[6:9]
	s_waitcnt vmcnt(11)
	ds_write_b128 v95, v[152:155] offset:36864
	s_waitcnt vmcnt(10)
	ds_write_b128 v95, v[156:159] offset:41472
	s_waitcnt lgkmcnt(8)
	v_mfma_f32_16x16x32_bf16 v[42:45], v[200:203], v[228:231], v[42:45]
	v_mfma_f32_16x16x32_bf16 v[46:49], v[200:203], v[232:235], v[46:49]
	v_mfma_f32_16x16x32_bf16 v[10:13], v[200:203], v[236:239], v[10:13]
	v_mfma_f32_16x16x32_bf16 v[14:17], v[200:203], v[240:243], v[14:17]
	s_waitcnt vmcnt(9)
	ds_write_b128 v95, v[160:163] offset:46080
	s_waitcnt vmcnt(8)
	ds_write_b128 v95, v[164:167] offset:50688
	s_waitcnt lgkmcnt(9)
	v_mfma_f32_16x16x32_bf16 v[50:53], v[204:207], v[228:231], v[50:53]
	v_mfma_f32_16x16x32_bf16 v[54:57], v[204:207], v[232:235], v[54:57]
	v_mfma_f32_16x16x32_bf16 v[18:21], v[204:207], v[236:239], v[18:21]
	v_mfma_f32_16x16x32_bf16 v[22:25], v[204:207], v[240:243], v[22:25]
	s_waitcnt lgkmcnt(6)
	v_mfma_f32_16x16x32_bf16 v[58:61], v[208:211], v[228:231], v[58:61]
	v_mfma_f32_16x16x32_bf16 v[62:65], v[208:211], v[232:235], v[62:65]
	v_mfma_f32_16x16x32_bf16 v[26:29], v[208:211], v[236:239], v[26:29]
	v_mfma_f32_16x16x32_bf16 v[30:33], v[208:211], v[240:243], v[30:33]
	s_waitcnt lgkmcnt(0)
	s_barrier
	global_load_dwordx4 v[136:139], v[72:73], off offset:1024
	global_load_dwordx4 v[140:143], v[74:75], off offset:1024
	global_load_dwordx4 v[144:147], v[76:77], off offset:1024
	global_load_dwordx4 v[148:151], v[78:79], off offset:1024
	global_load_dwordx4 v[152:155], v[80:81], off offset:1024
	global_load_dwordx4 v[156:159], v[82:83], off offset:1024
	global_load_dwordx4 v[160:163], v[84:85], off offset:1024
	global_load_dwordx4 v[164:167], v[86:87], off offset:1024
	ds_read_b128 v[212:215], v245 offset:36864
	ds_read_b128 v[196:199], v244
	ds_read_b128 v[216:219], v245 offset:39168
	ds_read_b128 v[220:223], v245 offset:41472
	ds_read_b128 v[224:227], v245 offset:43776
	ds_read_b128 v[200:203], v244 offset:2304
	ds_read_b128 v[204:207], v244 offset:4608
	ds_read_b128 v[208:211], v244 offset:6912
	s_waitcnt lgkmcnt(6)
	v_mfma_f32_16x16x32_bf16 v[34:37], v[196:199], v[212:215], v[34:37]
	ds_read_b128 v[228:231], v245 offset:36928
	s_waitcnt lgkmcnt(6)
	v_mfma_f32_16x16x32_bf16 v[38:41], v[196:199], v[216:219], v[38:41]
	ds_read_b128 v[232:235], v245 offset:39232
	s_waitcnt lgkmcnt(6)
	v_mfma_f32_16x16x32_bf16 v[2:5], v[196:199], v[220:223], v[2:5]
	ds_read_b128 v[236:239], v245 offset:41536
	s_waitcnt lgkmcnt(6)
	v_mfma_f32_16x16x32_bf16 v[6:9], v[196:199], v[224:227], v[6:9]
	ds_read_b128 v[240:243], v245 offset:43840
	ds_read_b128 v[196:199], v244 offset:64
	s_waitcnt lgkmcnt(7)
	v_mfma_f32_16x16x32_bf16 v[42:45], v[200:203], v[212:215], v[42:45]
	v_mfma_f32_16x16x32_bf16 v[46:49], v[200:203], v[216:219], v[46:49]
	v_mfma_f32_16x16x32_bf16 v[10:13], v[200:203], v[220:223], v[10:13]
	v_mfma_f32_16x16x32_bf16 v[14:17], v[200:203], v[224:227], v[14:17]
	ds_read_b128 v[200:203], v244 offset:2368
	s_waitcnt lgkmcnt(7)
	v_mfma_f32_16x16x32_bf16 v[50:53], v[204:207], v[212:215], v[50:53]
	v_mfma_f32_16x16x32_bf16 v[54:57], v[204:207], v[216:219], v[54:57]
	v_mfma_f32_16x16x32_bf16 v[18:21], v[204:207], v[220:223], v[18:21]
	v_mfma_f32_16x16x32_bf16 v[22:25], v[204:207], v[224:227], v[22:25]
	ds_read_b128 v[204:207], v244 offset:4672
	s_waitcnt vmcnt(15)
	ds_write_b128 v95, v[98:101] offset:18432
	s_waitcnt vmcnt(14)
	ds_write_b128 v95, v[102:105] offset:23040
	s_waitcnt lgkmcnt(9)
	v_mfma_f32_16x16x32_bf16 v[58:61], v[208:211], v[212:215], v[58:61]
	v_mfma_f32_16x16x32_bf16 v[62:65], v[208:211], v[216:219], v[62:65]
	v_mfma_f32_16x16x32_bf16 v[26:29], v[208:211], v[220:223], v[26:29]
	v_mfma_f32_16x16x32_bf16 v[30:33], v[208:211], v[224:227], v[30:33]
	ds_read_b128 v[208:211], v244 offset:6976
	s_waitcnt vmcnt(13)
	ds_write_b128 v95, v[106:109] offset:27648
	s_waitcnt vmcnt(12)
	ds_write_b128 v95, v[110:113] offset:32256
	s_waitcnt lgkmcnt(7)
	v_mfma_f32_16x16x32_bf16 v[34:37], v[196:199], v[228:231], v[34:37]
	v_mfma_f32_16x16x32_bf16 v[38:41], v[196:199], v[232:235], v[38:41]
	v_mfma_f32_16x16x32_bf16 v[2:5], v[196:199], v[236:239], v[2:5]
	v_mfma_f32_16x16x32_bf16 v[6:9], v[196:199], v[240:243], v[6:9]
	s_waitcnt vmcnt(11)
	ds_write_b128 v95, v[114:117] offset:55296
	s_waitcnt vmcnt(10)
	ds_write_b128 v95, v[118:121] offset:59904
	s_waitcnt lgkmcnt(8)
	v_mfma_f32_16x16x32_bf16 v[42:45], v[200:203], v[228:231], v[42:45]
	v_mfma_f32_16x16x32_bf16 v[46:49], v[200:203], v[232:235], v[46:49]
	v_mfma_f32_16x16x32_bf16 v[10:13], v[200:203], v[236:239], v[10:13]
	v_mfma_f32_16x16x32_bf16 v[14:17], v[200:203], v[240:243], v[14:17]
	s_waitcnt vmcnt(9)
	ds_write_b128 v95, v[122:125] offset:64512
	s_waitcnt vmcnt(8)
	ds_write_b128 v96, v[126:129] offset:32256
	s_waitcnt lgkmcnt(9)
	v_mfma_f32_16x16x32_bf16 v[50:53], v[204:207], v[228:231], v[50:53]
	v_mfma_f32_16x16x32_bf16 v[54:57], v[204:207], v[232:235], v[54:57]
	v_mfma_f32_16x16x32_bf16 v[18:21], v[204:207], v[236:239], v[18:21]
	v_mfma_f32_16x16x32_bf16 v[22:25], v[204:207], v[240:243], v[22:25]
	s_waitcnt lgkmcnt(6)
	v_mfma_f32_16x16x32_bf16 v[58:61], v[208:211], v[228:231], v[58:61]
	v_mfma_f32_16x16x32_bf16 v[62:65], v[208:211], v[232:235], v[62:65]
	v_mfma_f32_16x16x32_bf16 v[26:29], v[208:211], v[236:239], v[26:29]
	v_mfma_f32_16x16x32_bf16 v[30:33], v[208:211], v[240:243], v[30:33]
	s_waitcnt lgkmcnt(0)
	s_barrier
	global_load_dwordx4 v[98:101], v[72:73], off offset:1152
	global_load_dwordx4 v[102:105], v[74:75], off offset:1152
	global_load_dwordx4 v[106:109], v[76:77], off offset:1152
	global_load_dwordx4 v[110:113], v[78:79], off offset:1152
	global_load_dwordx4 v[114:117], v[80:81], off offset:1152
	global_load_dwordx4 v[118:121], v[82:83], off offset:1152
	global_load_dwordx4 v[122:125], v[84:85], off offset:1152
	global_load_dwordx4 v[126:129], v[86:87], off offset:1152
	ds_read_b128 v[212:215], v245 offset:55296
	ds_read_b128 v[196:199], v244 offset:18432
	ds_read_b128 v[216:219], v245 offset:57600
	ds_read_b128 v[220:223], v245 offset:59904
	ds_read_b128 v[224:227], v245 offset:62208
	ds_read_b128 v[200:203], v244 offset:20736
	ds_read_b128 v[204:207], v244 offset:23040
	ds_read_b128 v[208:211], v244 offset:25344
	s_waitcnt lgkmcnt(6)
	v_mfma_f32_16x16x32_bf16 v[34:37], v[196:199], v[212:215], v[34:37]
	ds_read_b128 v[228:231], v245 offset:55360
	s_waitcnt lgkmcnt(6)
	v_mfma_f32_16x16x32_bf16 v[38:41], v[196:199], v[216:219], v[38:41]
	ds_read_b128 v[232:235], v245 offset:57664
	s_waitcnt lgkmcnt(6)
	v_mfma_f32_16x16x32_bf16 v[2:5], v[196:199], v[220:223], v[2:5]
	ds_read_b128 v[236:239], v245 offset:59968
	s_waitcnt lgkmcnt(6)
	v_mfma_f32_16x16x32_bf16 v[6:9], v[196:199], v[224:227], v[6:9]
	ds_read_b128 v[240:243], v245 offset:62272
	ds_read_b128 v[196:199], v244 offset:18496
	s_waitcnt lgkmcnt(7)
	v_mfma_f32_16x16x32_bf16 v[42:45], v[200:203], v[212:215], v[42:45]
	v_mfma_f32_16x16x32_bf16 v[46:49], v[200:203], v[216:219], v[46:49]
	v_mfma_f32_16x16x32_bf16 v[10:13], v[200:203], v[220:223], v[10:13]
	v_mfma_f32_16x16x32_bf16 v[14:17], v[200:203], v[224:227], v[14:17]
	ds_read_b128 v[200:203], v244 offset:20800
	s_waitcnt lgkmcnt(7)
	v_mfma_f32_16x16x32_bf16 v[50:53], v[204:207], v[212:215], v[50:53]
	v_mfma_f32_16x16x32_bf16 v[54:57], v[204:207], v[216:219], v[54:57]
	v_mfma_f32_16x16x32_bf16 v[18:21], v[204:207], v[220:223], v[18:21]
	v_mfma_f32_16x16x32_bf16 v[22:25], v[204:207], v[224:227], v[22:25]
	ds_read_b128 v[204:207], v244 offset:23104
	s_waitcnt vmcnt(15)
	ds_write_b128 v95, v[136:139]
	s_waitcnt vmcnt(14)
	ds_write_b128 v95, v[140:143] offset:4608
	s_waitcnt lgkmcnt(9)
	v_mfma_f32_16x16x32_bf16 v[58:61], v[208:211], v[212:215], v[58:61]
	v_mfma_f32_16x16x32_bf16 v[62:65], v[208:211], v[216:219], v[62:65]
	v_mfma_f32_16x16x32_bf16 v[26:29], v[208:211], v[220:223], v[26:29]
	v_mfma_f32_16x16x32_bf16 v[30:33], v[208:211], v[224:227], v[30:33]
	ds_read_b128 v[208:211], v244 offset:25408
	s_waitcnt vmcnt(13)
	ds_write_b128 v95, v[144:147] offset:9216
	s_waitcnt vmcnt(12)
	ds_write_b128 v95, v[148:151] offset:13824
	s_waitcnt lgkmcnt(7)
	v_mfma_f32_16x16x32_bf16 v[34:37], v[196:199], v[228:231], v[34:37]
	v_mfma_f32_16x16x32_bf16 v[38:41], v[196:199], v[232:235], v[38:41]
	v_mfma_f32_16x16x32_bf16 v[2:5], v[196:199], v[236:239], v[2:5]
	v_mfma_f32_16x16x32_bf16 v[6:9], v[196:199], v[240:243], v[6:9]
	s_waitcnt vmcnt(11)
	ds_write_b128 v95, v[152:155] offset:36864
	s_waitcnt vmcnt(10)
	ds_write_b128 v95, v[156:159] offset:41472
	s_waitcnt lgkmcnt(8)
	v_mfma_f32_16x16x32_bf16 v[42:45], v[200:203], v[228:231], v[42:45]
	v_mfma_f32_16x16x32_bf16 v[46:49], v[200:203], v[232:235], v[46:49]
	v_mfma_f32_16x16x32_bf16 v[10:13], v[200:203], v[236:239], v[10:13]
	v_mfma_f32_16x16x32_bf16 v[14:17], v[200:203], v[240:243], v[14:17]
	s_waitcnt vmcnt(9)
	ds_write_b128 v95, v[160:163] offset:46080
	s_waitcnt vmcnt(8)
	ds_write_b128 v95, v[164:167] offset:50688
	s_waitcnt lgkmcnt(9)
	v_mfma_f32_16x16x32_bf16 v[50:53], v[204:207], v[228:231], v[50:53]
	v_mfma_f32_16x16x32_bf16 v[54:57], v[204:207], v[232:235], v[54:57]
	v_mfma_f32_16x16x32_bf16 v[18:21], v[204:207], v[236:239], v[18:21]
	v_mfma_f32_16x16x32_bf16 v[22:25], v[204:207], v[240:243], v[22:25]
	s_waitcnt lgkmcnt(6)
	v_mfma_f32_16x16x32_bf16 v[58:61], v[208:211], v[228:231], v[58:61]
	v_mfma_f32_16x16x32_bf16 v[62:65], v[208:211], v[232:235], v[62:65]
	v_mfma_f32_16x16x32_bf16 v[26:29], v[208:211], v[236:239], v[26:29]
	v_mfma_f32_16x16x32_bf16 v[30:33], v[208:211], v[240:243], v[30:33]
	s_waitcnt lgkmcnt(0)
	s_barrier
	global_load_dwordx4 v[136:139], v[72:73], off offset:1280
	global_load_dwordx4 v[140:143], v[74:75], off offset:1280
	global_load_dwordx4 v[144:147], v[76:77], off offset:1280
	global_load_dwordx4 v[148:151], v[78:79], off offset:1280
	global_load_dwordx4 v[152:155], v[80:81], off offset:1280
	global_load_dwordx4 v[156:159], v[82:83], off offset:1280
	global_load_dwordx4 v[160:163], v[84:85], off offset:1280
	global_load_dwordx4 v[164:167], v[86:87], off offset:1280
	ds_read_b128 v[212:215], v245 offset:36864
	ds_read_b128 v[196:199], v244
	ds_read_b128 v[216:219], v245 offset:39168
	ds_read_b128 v[220:223], v245 offset:41472
	ds_read_b128 v[224:227], v245 offset:43776
	ds_read_b128 v[200:203], v244 offset:2304
	ds_read_b128 v[204:207], v244 offset:4608
	ds_read_b128 v[208:211], v244 offset:6912
	s_waitcnt lgkmcnt(6)
	v_mfma_f32_16x16x32_bf16 v[34:37], v[196:199], v[212:215], v[34:37]
	ds_read_b128 v[228:231], v245 offset:36928
	s_waitcnt lgkmcnt(6)
	v_mfma_f32_16x16x32_bf16 v[38:41], v[196:199], v[216:219], v[38:41]
	ds_read_b128 v[232:235], v245 offset:39232
	s_waitcnt lgkmcnt(6)
	v_mfma_f32_16x16x32_bf16 v[2:5], v[196:199], v[220:223], v[2:5]
	ds_read_b128 v[236:239], v245 offset:41536
	s_waitcnt lgkmcnt(6)
	v_mfma_f32_16x16x32_bf16 v[6:9], v[196:199], v[224:227], v[6:9]
	ds_read_b128 v[240:243], v245 offset:43840
	ds_read_b128 v[196:199], v244 offset:64
	s_waitcnt lgkmcnt(7)
	v_mfma_f32_16x16x32_bf16 v[42:45], v[200:203], v[212:215], v[42:45]
	v_mfma_f32_16x16x32_bf16 v[46:49], v[200:203], v[216:219], v[46:49]
	v_mfma_f32_16x16x32_bf16 v[10:13], v[200:203], v[220:223], v[10:13]
	v_mfma_f32_16x16x32_bf16 v[14:17], v[200:203], v[224:227], v[14:17]
	ds_read_b128 v[200:203], v244 offset:2368
	s_waitcnt lgkmcnt(7)
	v_mfma_f32_16x16x32_bf16 v[50:53], v[204:207], v[212:215], v[50:53]
	v_mfma_f32_16x16x32_bf16 v[54:57], v[204:207], v[216:219], v[54:57]
	v_mfma_f32_16x16x32_bf16 v[18:21], v[204:207], v[220:223], v[18:21]
	v_mfma_f32_16x16x32_bf16 v[22:25], v[204:207], v[224:227], v[22:25]
	ds_read_b128 v[204:207], v244 offset:4672
	s_waitcnt vmcnt(15)
	ds_write_b128 v95, v[98:101] offset:18432
	s_waitcnt vmcnt(14)
	ds_write_b128 v95, v[102:105] offset:23040
	s_waitcnt lgkmcnt(9)
	v_mfma_f32_16x16x32_bf16 v[58:61], v[208:211], v[212:215], v[58:61]
	v_mfma_f32_16x16x32_bf16 v[62:65], v[208:211], v[216:219], v[62:65]
	v_mfma_f32_16x16x32_bf16 v[26:29], v[208:211], v[220:223], v[26:29]
	v_mfma_f32_16x16x32_bf16 v[30:33], v[208:211], v[224:227], v[30:33]
	ds_read_b128 v[208:211], v244 offset:6976
	s_waitcnt vmcnt(13)
	ds_write_b128 v95, v[106:109] offset:27648
	s_waitcnt vmcnt(12)
	ds_write_b128 v95, v[110:113] offset:32256
	s_waitcnt lgkmcnt(7)
	v_mfma_f32_16x16x32_bf16 v[34:37], v[196:199], v[228:231], v[34:37]
	v_mfma_f32_16x16x32_bf16 v[38:41], v[196:199], v[232:235], v[38:41]
	v_mfma_f32_16x16x32_bf16 v[2:5], v[196:199], v[236:239], v[2:5]
	v_mfma_f32_16x16x32_bf16 v[6:9], v[196:199], v[240:243], v[6:9]
	s_waitcnt vmcnt(11)
	ds_write_b128 v95, v[114:117] offset:55296
	s_waitcnt vmcnt(10)
	ds_write_b128 v95, v[118:121] offset:59904
	s_waitcnt lgkmcnt(8)
	v_mfma_f32_16x16x32_bf16 v[42:45], v[200:203], v[228:231], v[42:45]
	v_mfma_f32_16x16x32_bf16 v[46:49], v[200:203], v[232:235], v[46:49]
	v_mfma_f32_16x16x32_bf16 v[10:13], v[200:203], v[236:239], v[10:13]
	v_mfma_f32_16x16x32_bf16 v[14:17], v[200:203], v[240:243], v[14:17]
	s_waitcnt vmcnt(9)
	ds_write_b128 v95, v[122:125] offset:64512
	s_waitcnt vmcnt(8)
	ds_write_b128 v96, v[126:129] offset:32256
	s_waitcnt lgkmcnt(9)
	v_mfma_f32_16x16x32_bf16 v[50:53], v[204:207], v[228:231], v[50:53]
	v_mfma_f32_16x16x32_bf16 v[54:57], v[204:207], v[232:235], v[54:57]
	v_mfma_f32_16x16x32_bf16 v[18:21], v[204:207], v[236:239], v[18:21]
	v_mfma_f32_16x16x32_bf16 v[22:25], v[204:207], v[240:243], v[22:25]
	s_waitcnt lgkmcnt(6)
	v_mfma_f32_16x16x32_bf16 v[58:61], v[208:211], v[228:231], v[58:61]
	v_mfma_f32_16x16x32_bf16 v[62:65], v[208:211], v[232:235], v[62:65]
	v_mfma_f32_16x16x32_bf16 v[26:29], v[208:211], v[236:239], v[26:29]
	v_mfma_f32_16x16x32_bf16 v[30:33], v[208:211], v[240:243], v[30:33]
	s_waitcnt lgkmcnt(0)
	s_barrier
	global_load_dwordx4 v[98:101], v[72:73], off offset:1408
	global_load_dwordx4 v[102:105], v[74:75], off offset:1408
	global_load_dwordx4 v[106:109], v[76:77], off offset:1408
	global_load_dwordx4 v[110:113], v[78:79], off offset:1408
	global_load_dwordx4 v[114:117], v[80:81], off offset:1408
	global_load_dwordx4 v[118:121], v[82:83], off offset:1408
	global_load_dwordx4 v[122:125], v[84:85], off offset:1408
	global_load_dwordx4 v[126:129], v[86:87], off offset:1408
	ds_read_b128 v[212:215], v245 offset:55296
	ds_read_b128 v[196:199], v244 offset:18432
	ds_read_b128 v[216:219], v245 offset:57600
	ds_read_b128 v[220:223], v245 offset:59904
	ds_read_b128 v[224:227], v245 offset:62208
	ds_read_b128 v[200:203], v244 offset:20736
	ds_read_b128 v[204:207], v244 offset:23040
	ds_read_b128 v[208:211], v244 offset:25344
	s_waitcnt lgkmcnt(6)
	v_mfma_f32_16x16x32_bf16 v[34:37], v[196:199], v[212:215], v[34:37]
	ds_read_b128 v[228:231], v245 offset:55360
	s_waitcnt lgkmcnt(6)
	v_mfma_f32_16x16x32_bf16 v[38:41], v[196:199], v[216:219], v[38:41]
	ds_read_b128 v[232:235], v245 offset:57664
	s_waitcnt lgkmcnt(6)
	v_mfma_f32_16x16x32_bf16 v[2:5], v[196:199], v[220:223], v[2:5]
	ds_read_b128 v[236:239], v245 offset:59968
	s_waitcnt lgkmcnt(6)
	v_mfma_f32_16x16x32_bf16 v[6:9], v[196:199], v[224:227], v[6:9]
	ds_read_b128 v[240:243], v245 offset:62272
	ds_read_b128 v[196:199], v244 offset:18496
	s_waitcnt lgkmcnt(7)
	v_mfma_f32_16x16x32_bf16 v[42:45], v[200:203], v[212:215], v[42:45]
	v_mfma_f32_16x16x32_bf16 v[46:49], v[200:203], v[216:219], v[46:49]
	v_mfma_f32_16x16x32_bf16 v[10:13], v[200:203], v[220:223], v[10:13]
	v_mfma_f32_16x16x32_bf16 v[14:17], v[200:203], v[224:227], v[14:17]
	ds_read_b128 v[200:203], v244 offset:20800
	s_waitcnt lgkmcnt(7)
	v_mfma_f32_16x16x32_bf16 v[50:53], v[204:207], v[212:215], v[50:53]
	v_mfma_f32_16x16x32_bf16 v[54:57], v[204:207], v[216:219], v[54:57]
	v_mfma_f32_16x16x32_bf16 v[18:21], v[204:207], v[220:223], v[18:21]
	v_mfma_f32_16x16x32_bf16 v[22:25], v[204:207], v[224:227], v[22:25]
	ds_read_b128 v[204:207], v244 offset:23104
	s_waitcnt vmcnt(15)
	ds_write_b128 v95, v[136:139]
	s_waitcnt vmcnt(14)
	ds_write_b128 v95, v[140:143] offset:4608
	s_waitcnt lgkmcnt(9)
	v_mfma_f32_16x16x32_bf16 v[58:61], v[208:211], v[212:215], v[58:61]
	v_mfma_f32_16x16x32_bf16 v[62:65], v[208:211], v[216:219], v[62:65]
	v_mfma_f32_16x16x32_bf16 v[26:29], v[208:211], v[220:223], v[26:29]
	v_mfma_f32_16x16x32_bf16 v[30:33], v[208:211], v[224:227], v[30:33]
	ds_read_b128 v[208:211], v244 offset:25408
	s_waitcnt vmcnt(13)
	ds_write_b128 v95, v[144:147] offset:9216
	s_waitcnt vmcnt(12)
	ds_write_b128 v95, v[148:151] offset:13824
	s_waitcnt lgkmcnt(7)
	v_mfma_f32_16x16x32_bf16 v[34:37], v[196:199], v[228:231], v[34:37]
	v_mfma_f32_16x16x32_bf16 v[38:41], v[196:199], v[232:235], v[38:41]
	v_mfma_f32_16x16x32_bf16 v[2:5], v[196:199], v[236:239], v[2:5]
	v_mfma_f32_16x16x32_bf16 v[6:9], v[196:199], v[240:243], v[6:9]
	s_waitcnt vmcnt(11)
	ds_write_b128 v95, v[152:155] offset:36864
	s_waitcnt vmcnt(10)
	ds_write_b128 v95, v[156:159] offset:41472
	s_waitcnt lgkmcnt(8)
	v_mfma_f32_16x16x32_bf16 v[42:45], v[200:203], v[228:231], v[42:45]
	v_mfma_f32_16x16x32_bf16 v[46:49], v[200:203], v[232:235], v[46:49]
	v_mfma_f32_16x16x32_bf16 v[10:13], v[200:203], v[236:239], v[10:13]
	v_mfma_f32_16x16x32_bf16 v[14:17], v[200:203], v[240:243], v[14:17]
	s_waitcnt vmcnt(9)
	ds_write_b128 v95, v[160:163] offset:46080
	s_waitcnt vmcnt(8)
	ds_write_b128 v95, v[164:167] offset:50688
	s_waitcnt lgkmcnt(9)
	v_mfma_f32_16x16x32_bf16 v[50:53], v[204:207], v[228:231], v[50:53]
	v_mfma_f32_16x16x32_bf16 v[54:57], v[204:207], v[232:235], v[54:57]
	v_mfma_f32_16x16x32_bf16 v[18:21], v[204:207], v[236:239], v[18:21]
	v_mfma_f32_16x16x32_bf16 v[22:25], v[204:207], v[240:243], v[22:25]
	s_waitcnt lgkmcnt(6)
	v_mfma_f32_16x16x32_bf16 v[58:61], v[208:211], v[228:231], v[58:61]
	v_mfma_f32_16x16x32_bf16 v[62:65], v[208:211], v[232:235], v[62:65]
	v_mfma_f32_16x16x32_bf16 v[26:29], v[208:211], v[236:239], v[26:29]
	v_mfma_f32_16x16x32_bf16 v[30:33], v[208:211], v[240:243], v[30:33]
	s_waitcnt lgkmcnt(0)
	s_barrier
	global_load_dwordx4 v[136:139], v[72:73], off offset:1536
	global_load_dwordx4 v[140:143], v[74:75], off offset:1536
	global_load_dwordx4 v[144:147], v[76:77], off offset:1536
	global_load_dwordx4 v[148:151], v[78:79], off offset:1536
	global_load_dwordx4 v[152:155], v[80:81], off offset:1536
	global_load_dwordx4 v[156:159], v[82:83], off offset:1536
	global_load_dwordx4 v[160:163], v[84:85], off offset:1536
	global_load_dwordx4 v[164:167], v[86:87], off offset:1536
	ds_read_b128 v[212:215], v245 offset:36864
	ds_read_b128 v[196:199], v244
	ds_read_b128 v[216:219], v245 offset:39168
	ds_read_b128 v[220:223], v245 offset:41472
	ds_read_b128 v[224:227], v245 offset:43776
	ds_read_b128 v[200:203], v244 offset:2304
	ds_read_b128 v[204:207], v244 offset:4608
	ds_read_b128 v[208:211], v244 offset:6912
	s_waitcnt lgkmcnt(6)
	v_mfma_f32_16x16x32_bf16 v[34:37], v[196:199], v[212:215], v[34:37]
	ds_read_b128 v[228:231], v245 offset:36928
	s_waitcnt lgkmcnt(6)
	v_mfma_f32_16x16x32_bf16 v[38:41], v[196:199], v[216:219], v[38:41]
	ds_read_b128 v[232:235], v245 offset:39232
	s_waitcnt lgkmcnt(6)
	v_mfma_f32_16x16x32_bf16 v[2:5], v[196:199], v[220:223], v[2:5]
	ds_read_b128 v[236:239], v245 offset:41536
	s_waitcnt lgkmcnt(6)
	v_mfma_f32_16x16x32_bf16 v[6:9], v[196:199], v[224:227], v[6:9]
	ds_read_b128 v[240:243], v245 offset:43840
	ds_read_b128 v[196:199], v244 offset:64
	s_waitcnt lgkmcnt(7)
	v_mfma_f32_16x16x32_bf16 v[42:45], v[200:203], v[212:215], v[42:45]
	v_mfma_f32_16x16x32_bf16 v[46:49], v[200:203], v[216:219], v[46:49]
	v_mfma_f32_16x16x32_bf16 v[10:13], v[200:203], v[220:223], v[10:13]
	v_mfma_f32_16x16x32_bf16 v[14:17], v[200:203], v[224:227], v[14:17]
	ds_read_b128 v[200:203], v244 offset:2368
	s_waitcnt lgkmcnt(7)
	v_mfma_f32_16x16x32_bf16 v[50:53], v[204:207], v[212:215], v[50:53]
	v_mfma_f32_16x16x32_bf16 v[54:57], v[204:207], v[216:219], v[54:57]
	v_mfma_f32_16x16x32_bf16 v[18:21], v[204:207], v[220:223], v[18:21]
	v_mfma_f32_16x16x32_bf16 v[22:25], v[204:207], v[224:227], v[22:25]
	ds_read_b128 v[204:207], v244 offset:4672
	s_waitcnt vmcnt(15)
	ds_write_b128 v95, v[98:101] offset:18432
	s_waitcnt vmcnt(14)
	ds_write_b128 v95, v[102:105] offset:23040
	s_waitcnt lgkmcnt(9)
	v_mfma_f32_16x16x32_bf16 v[58:61], v[208:211], v[212:215], v[58:61]
	v_mfma_f32_16x16x32_bf16 v[62:65], v[208:211], v[216:219], v[62:65]
	v_mfma_f32_16x16x32_bf16 v[26:29], v[208:211], v[220:223], v[26:29]
	v_mfma_f32_16x16x32_bf16 v[30:33], v[208:211], v[224:227], v[30:33]
	ds_read_b128 v[208:211], v244 offset:6976
	s_waitcnt vmcnt(13)
	ds_write_b128 v95, v[106:109] offset:27648
	s_waitcnt vmcnt(12)
	ds_write_b128 v95, v[110:113] offset:32256
	s_waitcnt lgkmcnt(7)
	v_mfma_f32_16x16x32_bf16 v[34:37], v[196:199], v[228:231], v[34:37]
	v_mfma_f32_16x16x32_bf16 v[38:41], v[196:199], v[232:235], v[38:41]
	v_mfma_f32_16x16x32_bf16 v[2:5], v[196:199], v[236:239], v[2:5]
	v_mfma_f32_16x16x32_bf16 v[6:9], v[196:199], v[240:243], v[6:9]
	s_waitcnt vmcnt(11)
	ds_write_b128 v95, v[114:117] offset:55296
	s_waitcnt vmcnt(10)
	ds_write_b128 v95, v[118:121] offset:59904
	s_waitcnt lgkmcnt(8)
	v_mfma_f32_16x16x32_bf16 v[42:45], v[200:203], v[228:231], v[42:45]
	v_mfma_f32_16x16x32_bf16 v[46:49], v[200:203], v[232:235], v[46:49]
	v_mfma_f32_16x16x32_bf16 v[10:13], v[200:203], v[236:239], v[10:13]
	v_mfma_f32_16x16x32_bf16 v[14:17], v[200:203], v[240:243], v[14:17]
	s_waitcnt vmcnt(9)
	ds_write_b128 v95, v[122:125] offset:64512
	s_waitcnt vmcnt(8)
	ds_write_b128 v96, v[126:129] offset:32256
	s_waitcnt lgkmcnt(9)
	v_mfma_f32_16x16x32_bf16 v[50:53], v[204:207], v[228:231], v[50:53]
	v_mfma_f32_16x16x32_bf16 v[54:57], v[204:207], v[232:235], v[54:57]
	v_mfma_f32_16x16x32_bf16 v[18:21], v[204:207], v[236:239], v[18:21]
	v_mfma_f32_16x16x32_bf16 v[22:25], v[204:207], v[240:243], v[22:25]
	s_waitcnt lgkmcnt(6)
	v_mfma_f32_16x16x32_bf16 v[58:61], v[208:211], v[228:231], v[58:61]
	v_mfma_f32_16x16x32_bf16 v[62:65], v[208:211], v[232:235], v[62:65]
	v_mfma_f32_16x16x32_bf16 v[26:29], v[208:211], v[236:239], v[26:29]
	v_mfma_f32_16x16x32_bf16 v[30:33], v[208:211], v[240:243], v[30:33]
	s_waitcnt lgkmcnt(0)
	s_barrier
	global_load_dwordx4 v[98:101], v[72:73], off offset:1664
	global_load_dwordx4 v[102:105], v[74:75], off offset:1664
	global_load_dwordx4 v[106:109], v[76:77], off offset:1664
	global_load_dwordx4 v[110:113], v[78:79], off offset:1664
	global_load_dwordx4 v[114:117], v[80:81], off offset:1664
	global_load_dwordx4 v[118:121], v[82:83], off offset:1664
	global_load_dwordx4 v[122:125], v[84:85], off offset:1664
	global_load_dwordx4 v[126:129], v[86:87], off offset:1664
	ds_read_b128 v[212:215], v245 offset:55296
	ds_read_b128 v[196:199], v244 offset:18432
	ds_read_b128 v[216:219], v245 offset:57600
	ds_read_b128 v[220:223], v245 offset:59904
	ds_read_b128 v[224:227], v245 offset:62208
	ds_read_b128 v[200:203], v244 offset:20736
	ds_read_b128 v[204:207], v244 offset:23040
	ds_read_b128 v[208:211], v244 offset:25344
	s_waitcnt lgkmcnt(6)
	v_mfma_f32_16x16x32_bf16 v[34:37], v[196:199], v[212:215], v[34:37]
	ds_read_b128 v[228:231], v245 offset:55360
	s_waitcnt lgkmcnt(6)
	v_mfma_f32_16x16x32_bf16 v[38:41], v[196:199], v[216:219], v[38:41]
	ds_read_b128 v[232:235], v245 offset:57664
	s_waitcnt lgkmcnt(6)
	v_mfma_f32_16x16x32_bf16 v[2:5], v[196:199], v[220:223], v[2:5]
	ds_read_b128 v[236:239], v245 offset:59968
	s_waitcnt lgkmcnt(6)
	v_mfma_f32_16x16x32_bf16 v[6:9], v[196:199], v[224:227], v[6:9]
	ds_read_b128 v[240:243], v245 offset:62272
	ds_read_b128 v[196:199], v244 offset:18496
	s_waitcnt lgkmcnt(7)
	v_mfma_f32_16x16x32_bf16 v[42:45], v[200:203], v[212:215], v[42:45]
	v_mfma_f32_16x16x32_bf16 v[46:49], v[200:203], v[216:219], v[46:49]
	v_mfma_f32_16x16x32_bf16 v[10:13], v[200:203], v[220:223], v[10:13]
	v_mfma_f32_16x16x32_bf16 v[14:17], v[200:203], v[224:227], v[14:17]
	ds_read_b128 v[200:203], v244 offset:20800
	s_waitcnt lgkmcnt(7)
	v_mfma_f32_16x16x32_bf16 v[50:53], v[204:207], v[212:215], v[50:53]
	v_mfma_f32_16x16x32_bf16 v[54:57], v[204:207], v[216:219], v[54:57]
	v_mfma_f32_16x16x32_bf16 v[18:21], v[204:207], v[220:223], v[18:21]
	v_mfma_f32_16x16x32_bf16 v[22:25], v[204:207], v[224:227], v[22:25]
	ds_read_b128 v[204:207], v244 offset:23104
	s_waitcnt vmcnt(15)
	ds_write_b128 v95, v[136:139]
	s_waitcnt vmcnt(14)
	ds_write_b128 v95, v[140:143] offset:4608
	s_waitcnt lgkmcnt(9)
	v_mfma_f32_16x16x32_bf16 v[58:61], v[208:211], v[212:215], v[58:61]
	v_mfma_f32_16x16x32_bf16 v[62:65], v[208:211], v[216:219], v[62:65]
	v_mfma_f32_16x16x32_bf16 v[26:29], v[208:211], v[220:223], v[26:29]
	v_mfma_f32_16x16x32_bf16 v[30:33], v[208:211], v[224:227], v[30:33]
	ds_read_b128 v[208:211], v244 offset:25408
	s_waitcnt vmcnt(13)
	ds_write_b128 v95, v[144:147] offset:9216
	s_waitcnt vmcnt(12)
	ds_write_b128 v95, v[148:151] offset:13824
	s_waitcnt lgkmcnt(7)
	v_mfma_f32_16x16x32_bf16 v[34:37], v[196:199], v[228:231], v[34:37]
	v_mfma_f32_16x16x32_bf16 v[38:41], v[196:199], v[232:235], v[38:41]
	v_mfma_f32_16x16x32_bf16 v[2:5], v[196:199], v[236:239], v[2:5]
	v_mfma_f32_16x16x32_bf16 v[6:9], v[196:199], v[240:243], v[6:9]
	s_waitcnt vmcnt(11)
	ds_write_b128 v95, v[152:155] offset:36864
	s_waitcnt vmcnt(10)
	ds_write_b128 v95, v[156:159] offset:41472
	s_waitcnt lgkmcnt(8)
	v_mfma_f32_16x16x32_bf16 v[42:45], v[200:203], v[228:231], v[42:45]
	v_mfma_f32_16x16x32_bf16 v[46:49], v[200:203], v[232:235], v[46:49]
	v_mfma_f32_16x16x32_bf16 v[10:13], v[200:203], v[236:239], v[10:13]
	v_mfma_f32_16x16x32_bf16 v[14:17], v[200:203], v[240:243], v[14:17]
	s_waitcnt vmcnt(9)
	ds_write_b128 v95, v[160:163] offset:46080
	s_waitcnt vmcnt(8)
	ds_write_b128 v95, v[164:167] offset:50688
	s_waitcnt lgkmcnt(9)
	v_mfma_f32_16x16x32_bf16 v[50:53], v[204:207], v[228:231], v[50:53]
	v_mfma_f32_16x16x32_bf16 v[54:57], v[204:207], v[232:235], v[54:57]
	v_mfma_f32_16x16x32_bf16 v[18:21], v[204:207], v[236:239], v[18:21]
	v_mfma_f32_16x16x32_bf16 v[22:25], v[204:207], v[240:243], v[22:25]
	s_waitcnt lgkmcnt(6)
	v_mfma_f32_16x16x32_bf16 v[58:61], v[208:211], v[228:231], v[58:61]
	v_mfma_f32_16x16x32_bf16 v[62:65], v[208:211], v[232:235], v[62:65]
	v_mfma_f32_16x16x32_bf16 v[26:29], v[208:211], v[236:239], v[26:29]
	v_mfma_f32_16x16x32_bf16 v[30:33], v[208:211], v[240:243], v[30:33]
	s_waitcnt lgkmcnt(0)
	s_barrier
	global_load_dwordx4 v[136:139], v[72:73], off offset:1792
	global_load_dwordx4 v[140:143], v[74:75], off offset:1792
	global_load_dwordx4 v[144:147], v[76:77], off offset:1792
	global_load_dwordx4 v[148:151], v[78:79], off offset:1792
	global_load_dwordx4 v[152:155], v[80:81], off offset:1792
	global_load_dwordx4 v[156:159], v[82:83], off offset:1792
	global_load_dwordx4 v[160:163], v[84:85], off offset:1792
	global_load_dwordx4 v[164:167], v[86:87], off offset:1792
	ds_read_b128 v[212:215], v245 offset:36864
	ds_read_b128 v[196:199], v244
	ds_read_b128 v[216:219], v245 offset:39168
	ds_read_b128 v[220:223], v245 offset:41472
	ds_read_b128 v[224:227], v245 offset:43776
	ds_read_b128 v[200:203], v244 offset:2304
	ds_read_b128 v[204:207], v244 offset:4608
	ds_read_b128 v[208:211], v244 offset:6912
	s_waitcnt lgkmcnt(6)
	v_mfma_f32_16x16x32_bf16 v[34:37], v[196:199], v[212:215], v[34:37]
	ds_read_b128 v[228:231], v245 offset:36928
	s_waitcnt lgkmcnt(6)
	v_mfma_f32_16x16x32_bf16 v[38:41], v[196:199], v[216:219], v[38:41]
	ds_read_b128 v[232:235], v245 offset:39232
	s_waitcnt lgkmcnt(6)
	v_mfma_f32_16x16x32_bf16 v[2:5], v[196:199], v[220:223], v[2:5]
	ds_read_b128 v[236:239], v245 offset:41536
	s_waitcnt lgkmcnt(6)
	v_mfma_f32_16x16x32_bf16 v[6:9], v[196:199], v[224:227], v[6:9]
	ds_read_b128 v[240:243], v245 offset:43840
	ds_read_b128 v[196:199], v244 offset:64
	s_waitcnt lgkmcnt(7)
	v_mfma_f32_16x16x32_bf16 v[42:45], v[200:203], v[212:215], v[42:45]
	v_mfma_f32_16x16x32_bf16 v[46:49], v[200:203], v[216:219], v[46:49]
	v_mfma_f32_16x16x32_bf16 v[10:13], v[200:203], v[220:223], v[10:13]
	v_mfma_f32_16x16x32_bf16 v[14:17], v[200:203], v[224:227], v[14:17]
	ds_read_b128 v[200:203], v244 offset:2368
	s_waitcnt lgkmcnt(7)
	v_mfma_f32_16x16x32_bf16 v[50:53], v[204:207], v[212:215], v[50:53]
	v_mfma_f32_16x16x32_bf16 v[54:57], v[204:207], v[216:219], v[54:57]
	v_mfma_f32_16x16x32_bf16 v[18:21], v[204:207], v[220:223], v[18:21]
	v_mfma_f32_16x16x32_bf16 v[22:25], v[204:207], v[224:227], v[22:25]
	ds_read_b128 v[204:207], v244 offset:4672
	s_waitcnt vmcnt(15)
	ds_write_b128 v95, v[98:101] offset:18432
	s_waitcnt vmcnt(14)
	ds_write_b128 v95, v[102:105] offset:23040
	s_waitcnt lgkmcnt(9)
	v_mfma_f32_16x16x32_bf16 v[58:61], v[208:211], v[212:215], v[58:61]
	v_mfma_f32_16x16x32_bf16 v[62:65], v[208:211], v[216:219], v[62:65]
	v_mfma_f32_16x16x32_bf16 v[26:29], v[208:211], v[220:223], v[26:29]
	v_mfma_f32_16x16x32_bf16 v[30:33], v[208:211], v[224:227], v[30:33]
	ds_read_b128 v[208:211], v244 offset:6976
	s_waitcnt vmcnt(13)
	ds_write_b128 v95, v[106:109] offset:27648
	s_waitcnt vmcnt(12)
	ds_write_b128 v95, v[110:113] offset:32256
	s_waitcnt lgkmcnt(7)
	v_mfma_f32_16x16x32_bf16 v[34:37], v[196:199], v[228:231], v[34:37]
	v_mfma_f32_16x16x32_bf16 v[38:41], v[196:199], v[232:235], v[38:41]
	v_mfma_f32_16x16x32_bf16 v[2:5], v[196:199], v[236:239], v[2:5]
	v_mfma_f32_16x16x32_bf16 v[6:9], v[196:199], v[240:243], v[6:9]
	s_waitcnt vmcnt(11)
	ds_write_b128 v95, v[114:117] offset:55296
	s_waitcnt vmcnt(10)
	ds_write_b128 v95, v[118:121] offset:59904
	s_waitcnt lgkmcnt(8)
	v_mfma_f32_16x16x32_bf16 v[42:45], v[200:203], v[228:231], v[42:45]
	v_mfma_f32_16x16x32_bf16 v[46:49], v[200:203], v[232:235], v[46:49]
	v_mfma_f32_16x16x32_bf16 v[10:13], v[200:203], v[236:239], v[10:13]
	v_mfma_f32_16x16x32_bf16 v[14:17], v[200:203], v[240:243], v[14:17]
	s_waitcnt vmcnt(9)
	ds_write_b128 v95, v[122:125] offset:64512
	s_waitcnt vmcnt(8)
	ds_write_b128 v96, v[126:129] offset:32256
	s_waitcnt lgkmcnt(9)
	v_mfma_f32_16x16x32_bf16 v[50:53], v[204:207], v[228:231], v[50:53]
	v_mfma_f32_16x16x32_bf16 v[54:57], v[204:207], v[232:235], v[54:57]
	v_mfma_f32_16x16x32_bf16 v[18:21], v[204:207], v[236:239], v[18:21]
	v_mfma_f32_16x16x32_bf16 v[22:25], v[204:207], v[240:243], v[22:25]
	s_waitcnt lgkmcnt(6)
	v_mfma_f32_16x16x32_bf16 v[58:61], v[208:211], v[228:231], v[58:61]
	v_mfma_f32_16x16x32_bf16 v[62:65], v[208:211], v[232:235], v[62:65]
	v_mfma_f32_16x16x32_bf16 v[26:29], v[208:211], v[236:239], v[26:29]
	v_mfma_f32_16x16x32_bf16 v[30:33], v[208:211], v[240:243], v[30:33]
	s_waitcnt lgkmcnt(0)
	s_barrier
	global_load_dwordx4 v[98:101], v[72:73], off offset:1920
	s_nop 0
	global_load_dwordx4 v[72:75], v[74:75], off offset:1920
	s_nop 0
	global_load_dwordx4 v[102:105], v[76:77], off offset:1920
	s_nop 0
	global_load_dwordx4 v[76:79], v[78:79], off offset:1920
	s_nop 0
	global_load_dwordx4 v[106:109], v[80:81], off offset:1920
	s_nop 0
	global_load_dwordx4 v[80:83], v[82:83], off offset:1920
	s_nop 0
	global_load_dwordx4 v[110:113], v[84:85], off offset:1920
	s_nop 0
	global_load_dwordx4 v[84:87], v[86:87], off offset:1920
	ds_read_b128 v[212:215], v245 offset:55296
	ds_read_b128 v[196:199], v244 offset:18432
	ds_read_b128 v[216:219], v245 offset:57600
	ds_read_b128 v[220:223], v245 offset:59904
	ds_read_b128 v[224:227], v245 offset:62208
	ds_read_b128 v[200:203], v244 offset:20736
	ds_read_b128 v[204:207], v244 offset:23040
	ds_read_b128 v[208:211], v244 offset:25344
	s_waitcnt lgkmcnt(6)
	v_mfma_f32_16x16x32_bf16 v[34:37], v[196:199], v[212:215], v[34:37]
	ds_read_b128 v[228:231], v245 offset:55360
	s_waitcnt lgkmcnt(6)
	v_mfma_f32_16x16x32_bf16 v[38:41], v[196:199], v[216:219], v[38:41]
	ds_read_b128 v[232:235], v245 offset:57664
	s_waitcnt lgkmcnt(6)
	v_mfma_f32_16x16x32_bf16 v[2:5], v[196:199], v[220:223], v[2:5]
	ds_read_b128 v[236:239], v245 offset:59968
	s_waitcnt lgkmcnt(6)
	v_mfma_f32_16x16x32_bf16 v[6:9], v[196:199], v[224:227], v[6:9]
	ds_read_b128 v[240:243], v245 offset:62272
	ds_read_b128 v[196:199], v244 offset:18496
	s_waitcnt lgkmcnt(7)
	v_mfma_f32_16x16x32_bf16 v[42:45], v[200:203], v[212:215], v[42:45]
	v_mfma_f32_16x16x32_bf16 v[46:49], v[200:203], v[216:219], v[46:49]
	v_mfma_f32_16x16x32_bf16 v[10:13], v[200:203], v[220:223], v[10:13]
	v_mfma_f32_16x16x32_bf16 v[14:17], v[200:203], v[224:227], v[14:17]
	ds_read_b128 v[200:203], v244 offset:20800
	s_waitcnt lgkmcnt(7)
	v_mfma_f32_16x16x32_bf16 v[50:53], v[204:207], v[212:215], v[50:53]
	v_mfma_f32_16x16x32_bf16 v[54:57], v[204:207], v[216:219], v[54:57]
	v_mfma_f32_16x16x32_bf16 v[18:21], v[204:207], v[220:223], v[18:21]
	v_mfma_f32_16x16x32_bf16 v[22:25], v[204:207], v[224:227], v[22:25]
	ds_read_b128 v[204:207], v244 offset:23104
	s_waitcnt vmcnt(15)
	ds_write_b128 v95, v[136:139]
	s_waitcnt vmcnt(14)
	ds_write_b128 v95, v[140:143] offset:4608
	s_waitcnt lgkmcnt(9)
	v_mfma_f32_16x16x32_bf16 v[58:61], v[208:211], v[212:215], v[58:61]
	v_mfma_f32_16x16x32_bf16 v[62:65], v[208:211], v[216:219], v[62:65]
	v_mfma_f32_16x16x32_bf16 v[26:29], v[208:211], v[220:223], v[26:29]
	v_mfma_f32_16x16x32_bf16 v[30:33], v[208:211], v[224:227], v[30:33]
	ds_read_b128 v[208:211], v244 offset:25408
	s_waitcnt vmcnt(13)
	ds_write_b128 v95, v[144:147] offset:9216
	s_waitcnt vmcnt(12)
	ds_write_b128 v95, v[148:151] offset:13824
	s_waitcnt lgkmcnt(7)
	v_mfma_f32_16x16x32_bf16 v[34:37], v[196:199], v[228:231], v[34:37]
	v_mfma_f32_16x16x32_bf16 v[38:41], v[196:199], v[232:235], v[38:41]
	v_mfma_f32_16x16x32_bf16 v[2:5], v[196:199], v[236:239], v[2:5]
	v_mfma_f32_16x16x32_bf16 v[6:9], v[196:199], v[240:243], v[6:9]
	s_waitcnt vmcnt(11)
	ds_write_b128 v95, v[152:155] offset:36864
	s_waitcnt vmcnt(10)
	ds_write_b128 v95, v[156:159] offset:41472
	s_waitcnt lgkmcnt(8)
	v_mfma_f32_16x16x32_bf16 v[42:45], v[200:203], v[228:231], v[42:45]
	v_mfma_f32_16x16x32_bf16 v[46:49], v[200:203], v[232:235], v[46:49]
	v_mfma_f32_16x16x32_bf16 v[10:13], v[200:203], v[236:239], v[10:13]
	v_mfma_f32_16x16x32_bf16 v[14:17], v[200:203], v[240:243], v[14:17]
	s_waitcnt vmcnt(9)
	ds_write_b128 v95, v[160:163] offset:46080
	s_waitcnt vmcnt(8)
	ds_write_b128 v95, v[164:167] offset:50688
	s_waitcnt lgkmcnt(9)
	v_mfma_f32_16x16x32_bf16 v[50:53], v[204:207], v[228:231], v[50:53]
	v_mfma_f32_16x16x32_bf16 v[54:57], v[204:207], v[232:235], v[54:57]
	v_mfma_f32_16x16x32_bf16 v[18:21], v[204:207], v[236:239], v[18:21]
	v_mfma_f32_16x16x32_bf16 v[22:25], v[204:207], v[240:243], v[22:25]
	s_waitcnt lgkmcnt(6)
	v_mfma_f32_16x16x32_bf16 v[58:61], v[208:211], v[228:231], v[58:61]
	v_mfma_f32_16x16x32_bf16 v[62:65], v[208:211], v[232:235], v[62:65]
	v_mfma_f32_16x16x32_bf16 v[26:29], v[208:211], v[236:239], v[26:29]
	v_mfma_f32_16x16x32_bf16 v[30:33], v[208:211], v[240:243], v[30:33]
	s_waitcnt lgkmcnt(0)
	s_barrier
	ds_read_b128 v[212:215], v245 offset:36864
	ds_read_b128 v[196:199], v244
	ds_read_b128 v[216:219], v245 offset:39168
	ds_read_b128 v[220:223], v245 offset:41472
	ds_read_b128 v[224:227], v245 offset:43776
	ds_read_b128 v[200:203], v244 offset:2304
	ds_read_b128 v[204:207], v244 offset:4608
	ds_read_b128 v[208:211], v244 offset:6912
	s_waitcnt lgkmcnt(6)
	v_mfma_f32_16x16x32_bf16 v[34:37], v[196:199], v[212:215], v[34:37]
	ds_read_b128 v[228:231], v245 offset:36928
	s_waitcnt lgkmcnt(6)
	v_mfma_f32_16x16x32_bf16 v[38:41], v[196:199], v[216:219], v[38:41]
	ds_read_b128 v[232:235], v245 offset:39232
	s_waitcnt lgkmcnt(6)
	v_mfma_f32_16x16x32_bf16 v[2:5], v[196:199], v[220:223], v[2:5]
	ds_read_b128 v[236:239], v245 offset:41536
	s_waitcnt lgkmcnt(6)
	v_mfma_f32_16x16x32_bf16 v[6:9], v[196:199], v[224:227], v[6:9]
	ds_read_b128 v[240:243], v245 offset:43840
	ds_read_b128 v[196:199], v244 offset:64
	s_waitcnt lgkmcnt(7)
	v_mfma_f32_16x16x32_bf16 v[42:45], v[200:203], v[212:215], v[42:45]
	v_mfma_f32_16x16x32_bf16 v[46:49], v[200:203], v[216:219], v[46:49]
	v_mfma_f32_16x16x32_bf16 v[10:13], v[200:203], v[220:223], v[10:13]
	v_mfma_f32_16x16x32_bf16 v[14:17], v[200:203], v[224:227], v[14:17]
	ds_read_b128 v[200:203], v244 offset:2368
	s_waitcnt lgkmcnt(7)
	v_mfma_f32_16x16x32_bf16 v[50:53], v[204:207], v[212:215], v[50:53]
	v_mfma_f32_16x16x32_bf16 v[54:57], v[204:207], v[216:219], v[54:57]
	v_mfma_f32_16x16x32_bf16 v[18:21], v[204:207], v[220:223], v[18:21]
	v_mfma_f32_16x16x32_bf16 v[22:25], v[204:207], v[224:227], v[22:25]
	ds_read_b128 v[204:207], v244 offset:4672
	s_waitcnt vmcnt(7)
	ds_write_b128 v95, v[98:101] offset:18432
	s_waitcnt vmcnt(6)
	ds_write_b128 v95, v[72:75] offset:23040
	s_waitcnt lgkmcnt(9)
	v_mfma_f32_16x16x32_bf16 v[58:61], v[208:211], v[212:215], v[58:61]
	v_mfma_f32_16x16x32_bf16 v[62:65], v[208:211], v[216:219], v[62:65]
	v_mfma_f32_16x16x32_bf16 v[26:29], v[208:211], v[220:223], v[26:29]
	v_mfma_f32_16x16x32_bf16 v[30:33], v[208:211], v[224:227], v[30:33]
	ds_read_b128 v[208:211], v244 offset:6976
	s_waitcnt vmcnt(5)
	ds_write_b128 v95, v[102:105] offset:27648
	s_waitcnt vmcnt(4)
	ds_write_b128 v95, v[76:79] offset:32256
	s_waitcnt lgkmcnt(7)
	v_mfma_f32_16x16x32_bf16 v[34:37], v[196:199], v[228:231], v[34:37]
	v_mfma_f32_16x16x32_bf16 v[38:41], v[196:199], v[232:235], v[38:41]
	v_mfma_f32_16x16x32_bf16 v[2:5], v[196:199], v[236:239], v[2:5]
	v_mfma_f32_16x16x32_bf16 v[6:9], v[196:199], v[240:243], v[6:9]
	s_waitcnt vmcnt(3)
	ds_write_b128 v95, v[106:109] offset:55296
	s_waitcnt vmcnt(2)
	ds_write_b128 v95, v[80:83] offset:59904
	s_waitcnt lgkmcnt(8)
	v_mfma_f32_16x16x32_bf16 v[42:45], v[200:203], v[228:231], v[42:45]
	v_mfma_f32_16x16x32_bf16 v[46:49], v[200:203], v[232:235], v[46:49]
	v_mfma_f32_16x16x32_bf16 v[10:13], v[200:203], v[236:239], v[10:13]
	v_mfma_f32_16x16x32_bf16 v[14:17], v[200:203], v[240:243], v[14:17]
	s_waitcnt vmcnt(1)
	ds_write_b128 v95, v[110:113] offset:64512
	s_waitcnt vmcnt(0)
	ds_write_b128 v96, v[84:87] offset:32256
	s_waitcnt lgkmcnt(9)
	v_mfma_f32_16x16x32_bf16 v[50:53], v[204:207], v[228:231], v[50:53]
	v_mfma_f32_16x16x32_bf16 v[54:57], v[204:207], v[232:235], v[54:57]
	v_mfma_f32_16x16x32_bf16 v[18:21], v[204:207], v[236:239], v[18:21]
	v_mfma_f32_16x16x32_bf16 v[22:25], v[204:207], v[240:243], v[22:25]
	s_waitcnt lgkmcnt(6)
	v_mfma_f32_16x16x32_bf16 v[58:61], v[208:211], v[228:231], v[58:61]
	v_mfma_f32_16x16x32_bf16 v[62:65], v[208:211], v[232:235], v[62:65]
	v_mfma_f32_16x16x32_bf16 v[26:29], v[208:211], v[236:239], v[26:29]
	v_mfma_f32_16x16x32_bf16 v[30:33], v[208:211], v[240:243], v[30:33]
	s_waitcnt lgkmcnt(0)
	s_barrier
	ds_read_b128 v[212:215], v245 offset:55296
	ds_read_b128 v[196:199], v244 offset:18432
	ds_read_b128 v[216:219], v245 offset:57600
	ds_read_b128 v[220:223], v245 offset:59904
	ds_read_b128 v[224:227], v245 offset:62208
	ds_read_b128 v[200:203], v244 offset:20736
	ds_read_b128 v[204:207], v244 offset:23040
	ds_read_b128 v[208:211], v244 offset:25344
	s_waitcnt lgkmcnt(6)
	v_mfma_f32_16x16x32_bf16 v[34:37], v[196:199], v[212:215], v[34:37]
	ds_read_b128 v[228:231], v245 offset:55360
	s_waitcnt lgkmcnt(6)
	v_mfma_f32_16x16x32_bf16 v[38:41], v[196:199], v[216:219], v[38:41]
	ds_read_b128 v[232:235], v245 offset:57664
	s_waitcnt lgkmcnt(6)
	v_mfma_f32_16x16x32_bf16 v[2:5], v[196:199], v[220:223], v[2:5]
	ds_read_b128 v[236:239], v245 offset:59968
	s_waitcnt lgkmcnt(6)
	v_mfma_f32_16x16x32_bf16 v[6:9], v[196:199], v[224:227], v[6:9]
	ds_read_b128 v[240:243], v245 offset:62272
	ds_read_b128 v[196:199], v244 offset:18496
	s_waitcnt lgkmcnt(7)
	v_mfma_f32_16x16x32_bf16 v[42:45], v[200:203], v[212:215], v[42:45]
	v_mfma_f32_16x16x32_bf16 v[46:49], v[200:203], v[216:219], v[46:49]
	v_mfma_f32_16x16x32_bf16 v[10:13], v[200:203], v[220:223], v[10:13]
	v_mfma_f32_16x16x32_bf16 v[14:17], v[200:203], v[224:227], v[14:17]
	ds_read_b128 v[200:203], v244 offset:20800
	s_waitcnt lgkmcnt(7)
	v_mfma_f32_16x16x32_bf16 v[50:53], v[204:207], v[212:215], v[50:53]
	v_mfma_f32_16x16x32_bf16 v[54:57], v[204:207], v[216:219], v[54:57]
	v_mfma_f32_16x16x32_bf16 v[18:21], v[204:207], v[220:223], v[18:21]
	v_mfma_f32_16x16x32_bf16 v[22:25], v[204:207], v[224:227], v[22:25]
	ds_read_b128 v[204:207], v244 offset:23104
	s_waitcnt lgkmcnt(7)
	v_mfma_f32_16x16x32_bf16 v[58:61], v[208:211], v[212:215], v[58:61]
	v_mfma_f32_16x16x32_bf16 v[62:65], v[208:211], v[216:219], v[62:65]
	v_mfma_f32_16x16x32_bf16 v[26:29], v[208:211], v[220:223], v[26:29]
	v_mfma_f32_16x16x32_bf16 v[30:33], v[208:211], v[224:227], v[30:33]
	ds_read_b128 v[208:211], v244 offset:25408
	s_waitcnt lgkmcnt(3)
	v_mfma_f32_16x16x32_bf16 v[34:37], v[196:199], v[228:231], v[34:37]
	v_mfma_f32_16x16x32_bf16 v[38:41], v[196:199], v[232:235], v[38:41]
	v_mfma_f32_16x16x32_bf16 v[2:5], v[196:199], v[236:239], v[2:5]
	v_mfma_f32_16x16x32_bf16 v[6:9], v[196:199], v[240:243], v[6:9]
	s_waitcnt lgkmcnt(2)
	v_mfma_f32_16x16x32_bf16 v[42:45], v[200:203], v[228:231], v[42:45]
	v_mfma_f32_16x16x32_bf16 v[46:49], v[200:203], v[232:235], v[46:49]
	v_mfma_f32_16x16x32_bf16 v[10:13], v[200:203], v[236:239], v[10:13]
	v_mfma_f32_16x16x32_bf16 v[14:17], v[200:203], v[240:243], v[14:17]
	s_waitcnt lgkmcnt(1)
	v_mfma_f32_16x16x32_bf16 v[50:53], v[204:207], v[228:231], v[50:53]
	v_mfma_f32_16x16x32_bf16 v[54:57], v[204:207], v[232:235], v[54:57]
	v_mfma_f32_16x16x32_bf16 v[18:21], v[204:207], v[236:239], v[18:21]
	v_mfma_f32_16x16x32_bf16 v[22:25], v[204:207], v[240:243], v[22:25]
	s_waitcnt lgkmcnt(0)
	v_mfma_f32_16x16x32_bf16 v[58:61], v[208:211], v[228:231], v[58:61]
	v_mfma_f32_16x16x32_bf16 v[62:65], v[208:211], v[232:235], v[62:65]
	v_mfma_f32_16x16x32_bf16 v[26:29], v[208:211], v[236:239], v[26:29]
	v_mfma_f32_16x16x32_bf16 v[30:33], v[208:211], v[240:243], v[30:33]
	v_or_b32_e32 v66, s3, v88
	s_addk_i32 s3, 0xf000
	s_lshr_b32 s3, s3, 12
	s_cmp_lt_u32 s0, 32
	s_cselect_b64 vcc, -1, 0
	s_and_b64 s[4:5], vcc, exec
	s_mul_i32 s0, s3, 0xc00
	s_cselect_b32 s5, s17, s19
	s_cselect_b32 s4, s16, s18
	s_addk_i32 s0, 0xc00
	s_and_b64 s[12:13], vcc, exec
	s_cselect_b32 s0, 0, s0
	v_add_u32_e32 v72, 0xfffff000, v66
	v_cndmask_b32_e32 v72, v72, v66, vcc
	v_mov_b32_e32 v73, v67
	v_lshlrev_b64 v[72:73], 12, v[72:73]
	v_lshl_add_u64 v[78:79], s[4:5], 0, v[72:73]
	v_add_lshl_u32 v72, s2, v97, 2
	s_lshl_b64 s[2:3], s[0:1], 2
	s_add_u32 s0, s82, s2
	s_addc_u32 s3, s83, s3
	v_mov_b32_e32 v73, v67
	s_add_u32 s2, s0, 0xe958000
	v_lshl_add_u64 v[148:149], v[78:79], 0, v[72:73]
	s_addc_u32 s3, s3, 0
	v_or_b32_e32 v156, 0xe0, v72
	v_or_b32_e32 v157, 32, v72
	v_or_b32_e32 v158, 64, v72
	v_or_b32_e32 v159, 0x60, v72
	v_or_b32_e32 v160, 0x80, v72
	v_or_b32_e32 v161, 0xa0, v72
	v_or_b32_e32 v162, 0xc0, v72
	s_waitcnt lgkmcnt(0)
	s_barrier
	s_nop 7
	v_permlane16_swap_b32_e32 v34, v38
	v_permlane16_swap_b32_e32 v35, v39
	v_permlane16_swap_b32_e32 v36, v40
	v_permlane16_swap_b32_e32 v37, v41
	v_permlane16_swap_b32_e32 v42, v46
	v_permlane16_swap_b32_e32 v43, v47
	v_permlane16_swap_b32_e32 v44, v48
	v_permlane16_swap_b32_e32 v45, v49
	v_permlane16_swap_b32_e32 v2, v6
	v_permlane16_swap_b32_e32 v3, v7
	v_permlane16_swap_b32_e32 v4, v8
	v_permlane16_swap_b32_e32 v5, v9
	v_permlane16_swap_b32_e32 v10, v14
	v_permlane16_swap_b32_e32 v11, v15
	v_permlane16_swap_b32_e32 v12, v16
	v_permlane16_swap_b32_e32 v13, v17
	v_permlane16_swap_b32_e32 v50, v54
	v_permlane16_swap_b32_e32 v51, v55
	v_permlane16_swap_b32_e32 v52, v56
	v_permlane16_swap_b32_e32 v53, v57
	v_permlane16_swap_b32_e32 v58, v62
	v_permlane16_swap_b32_e32 v59, v63
	v_permlane16_swap_b32_e32 v60, v64
	v_permlane16_swap_b32_e32 v61, v65
	v_permlane16_swap_b32_e32 v18, v22
	v_permlane16_swap_b32_e32 v19, v23
	v_permlane16_swap_b32_e32 v20, v24
	v_permlane16_swap_b32_e32 v21, v25
	v_permlane16_swap_b32_e32 v26, v30
	v_permlane16_swap_b32_e32 v27, v31
	v_permlane16_swap_b32_e32 v28, v32
	v_permlane16_swap_b32_e32 v29, v33
	v_permlane32_swap_b32_e32 v34, v38
	v_permlane32_swap_b32_e32 v35, v39
	v_permlane32_swap_b32_e32 v36, v40
	v_permlane32_swap_b32_e32 v37, v41
	v_permlane32_swap_b32_e32 v42, v46
	v_permlane32_swap_b32_e32 v43, v47
	v_permlane32_swap_b32_e32 v44, v48
	v_permlane32_swap_b32_e32 v45, v49
	v_permlane32_swap_b32_e32 v2, v6
	v_permlane32_swap_b32_e32 v3, v7
	v_permlane32_swap_b32_e32 v4, v8
	v_permlane32_swap_b32_e32 v5, v9
	v_permlane32_swap_b32_e32 v10, v14
	v_permlane32_swap_b32_e32 v11, v15
	v_permlane32_swap_b32_e32 v12, v16
	v_permlane32_swap_b32_e32 v13, v17
	v_permlane32_swap_b32_e32 v50, v54
	v_permlane32_swap_b32_e32 v51, v55
	v_permlane32_swap_b32_e32 v52, v56
	v_permlane32_swap_b32_e32 v53, v57
	v_permlane32_swap_b32_e32 v58, v62
	v_permlane32_swap_b32_e32 v59, v63
	v_permlane32_swap_b32_e32 v60, v64
	v_permlane32_swap_b32_e32 v61, v65
	v_permlane32_swap_b32_e32 v18, v22
	v_permlane32_swap_b32_e32 v19, v23
	v_permlane32_swap_b32_e32 v20, v24
	v_permlane32_swap_b32_e32 v21, v25
	v_permlane32_swap_b32_e32 v26, v30
	v_permlane32_swap_b32_e32 v27, v31
	v_permlane32_swap_b32_e32 v28, v32
	v_permlane32_swap_b32_e32 v29, v33
	global_load_dwordx4 v[102:105], v[148:149], off offset:224
	s_add_i32 s11, s11, 1
	s_mul_i32 s0, s11, s7
	s_add_i32 s10, s10, s7
	global_load_dwordx4 v[84:87], v156, s[2:3]
	global_load_dwordx4 v[78:81], v[148:149], off offset:192
	v_lshlrev_b64 v[82:83], 12, v[66:67]
	v_lshl_add_u64 v[82:83], s[80:81], 0, v[82:83]
	v_lshl_add_u64 v[82:83], v[82:83], 0, v[72:73]
	s_waitcnt vmcnt(1)
	v_pk_fma_f32 v[64:65], v[64:65], v[86:87], v[104:105]
	global_load_dwordx4 v[74:77], v162, s[2:3]
	global_load_dwordx4 v[98:101], v[148:149], off offset:160
	global_load_dwordx4 v[106:109], v161, s[2:3]
	global_load_dwordx4 v[110:113], v[148:149], off offset:128
	global_load_dwordx4 v[114:117], v160, s[2:3]
	global_load_dwordx4 v[118:121], v[148:149], off offset:96
	global_load_dwordx4 v[122:125], v159, s[2:3]
	global_load_dwordx4 v[126:129], v[148:149], off offset:64
	global_load_dwordx4 v[136:139], v158, s[2:3]
	global_load_dwordx4 v[140:143], v[148:149], off offset:32
	global_load_dwordx4 v[144:147], v157, s[2:3]
	v_or_b32_e32 v86, 32, v66
	global_load_dwordx4 v[148:151], v[148:149], off
	v_pk_fma_f32 v[62:63], v[62:63], v[84:85], v[102:103]
	global_load_dwordx4 v[152:155], v72, s[2:3]
	v_mov_b32_e32 v87, v67
	global_store_dwordx4 v[82:83], v[62:65], off offset:224
	s_waitcnt vmcnt(13)
	v_pk_fma_f32 v[58:59], v[58:59], v[74:75], v[78:79]
	v_pk_fma_f32 v[60:61], v[60:61], v[76:77], v[80:81]
	s_waitcnt vmcnt(11)
	v_pk_fma_f32 v[54:55], v[54:55], v[106:107], v[98:99]
	v_pk_fma_f32 v[56:57], v[56:57], v[108:109], v[100:101]
	s_waitcnt vmcnt(9)
	v_pk_fma_f32 v[50:51], v[50:51], v[114:115], v[110:111]
	v_pk_fma_f32 v[52:53], v[52:53], v[116:117], v[112:113]
	s_waitcnt vmcnt(7)
	v_pk_fma_f32 v[46:47], v[46:47], v[122:123], v[118:119]
	v_pk_fma_f32 v[48:49], v[48:49], v[124:125], v[120:121]
	s_waitcnt vmcnt(5)
	v_pk_fma_f32 v[42:43], v[42:43], v[136:137], v[126:127]
	v_pk_fma_f32 v[44:45], v[44:45], v[138:139], v[128:129]
	s_waitcnt vmcnt(3)
	v_pk_fma_f32 v[38:39], v[38:39], v[144:145], v[140:141]
	v_pk_fma_f32 v[40:41], v[40:41], v[146:147], v[142:143]
	global_store_dwordx4 v[82:83], v[38:41], off offset:32
	global_store_dwordx4 v[82:83], v[42:45], off offset:64
	s_waitcnt vmcnt(3)
	v_pk_fma_f32 v[34:35], v[34:35], v[152:153], v[148:149]
	v_pk_fma_f32 v[36:37], v[36:37], v[154:155], v[150:151]
	global_store_dwordx4 v[82:83], v[34:37], off
	global_store_dwordx4 v[82:83], v[46:49], off offset:96
	global_store_dwordx4 v[82:83], v[50:53], off offset:128
	v_add_u32_e32 v34, 0xfffff020, v66
	v_cndmask_b32_e32 v66, v34, v86, vcc
	v_lshlrev_b64 v[34:35], 12, v[66:67]
	v_lshl_add_u64 v[34:35], s[4:5], 0, v[34:35]
	global_store_dwordx4 v[82:83], v[54:57], off offset:160
	global_store_dwordx4 v[82:83], v[58:61], off offset:192
	v_lshl_add_u64 v[118:119], v[34:35], 0, v[72:73]
	global_load_dwordx4 v[34:37], v[118:119], off offset:224
	global_load_dwordx4 v[38:41], v156, s[2:3]
	global_load_dwordx4 v[42:45], v[118:119], off offset:192
	global_load_dwordx4 v[46:49], v162, s[2:3]
	global_load_dwordx4 v[50:53], v[118:119], off offset:160
	global_load_dwordx4 v[54:57], v161, s[2:3]
	global_load_dwordx4 v[58:61], v[118:119], off offset:128
	global_load_dwordx4 v[62:65], v160, s[2:3]
	global_load_dwordx4 v[74:77], v[118:119], off offset:96
	global_load_dwordx4 v[78:81], v159, s[2:3]
	global_load_dwordx4 v[82:85], v[118:119], off offset:64
	global_load_dwordx4 v[98:101], v158, s[2:3]
	global_load_dwordx4 v[102:105], v[118:119], off offset:32
	global_load_dwordx4 v[106:109], v157, s[2:3]
	global_load_dwordx4 v[110:113], v[118:119], off
	global_load_dwordx4 v[114:117], v72, s[2:3]
	v_lshlrev_b64 v[86:87], 12, v[86:87]
	v_lshl_add_u64 v[86:87], s[80:81], 0, v[86:87]
	s_add_i32 s2, s0, s6
	v_lshl_add_u64 v[72:73], v[86:87], 0, v[72:73]
	s_cmpk_lt_u32 s10, 0x60
	s_waitcnt vmcnt(14)
	v_pk_fma_f32 v[30:31], v[30:31], v[38:39], v[34:35]
	v_pk_fma_f32 v[32:33], v[32:33], v[40:41], v[36:37]
	s_waitcnt vmcnt(12)
	v_pk_fma_f32 v[26:27], v[26:27], v[46:47], v[42:43]
	v_pk_fma_f32 v[28:29], v[28:29], v[48:49], v[44:45]
	s_waitcnt vmcnt(10)
	v_pk_fma_f32 v[22:23], v[22:23], v[54:55], v[50:51]
	v_pk_fma_f32 v[24:25], v[24:25], v[56:57], v[52:53]
	s_waitcnt vmcnt(8)
	v_pk_fma_f32 v[18:19], v[18:19], v[62:63], v[58:59]
	v_pk_fma_f32 v[20:21], v[20:21], v[64:65], v[60:61]
	s_waitcnt vmcnt(6)
	v_pk_fma_f32 v[14:15], v[14:15], v[78:79], v[74:75]
	v_pk_fma_f32 v[16:17], v[16:17], v[80:81], v[76:77]
	s_waitcnt vmcnt(4)
	v_pk_fma_f32 v[10:11], v[10:11], v[98:99], v[82:83]
	v_pk_fma_f32 v[12:13], v[12:13], v[100:101], v[84:85]
	s_waitcnt vmcnt(2)
	v_pk_fma_f32 v[6:7], v[6:7], v[106:107], v[102:103]
	v_pk_fma_f32 v[8:9], v[8:9], v[108:109], v[104:105]
	s_waitcnt vmcnt(0)
	v_pk_fma_f32 v[2:3], v[2:3], v[114:115], v[110:111]
	v_pk_fma_f32 v[4:5], v[4:5], v[116:117], v[112:113]
	global_store_dwordx4 v[72:73], v[2:5], off
	global_store_dwordx4 v[72:73], v[6:9], off offset:32
	global_store_dwordx4 v[72:73], v[10:13], off offset:64
	global_store_dwordx4 v[72:73], v[14:17], off offset:96
	global_store_dwordx4 v[72:73], v[18:21], off offset:128
	global_store_dwordx4 v[72:73], v[22:25], off offset:160
	global_store_dwordx4 v[72:73], v[26:29], off offset:192
	global_store_dwordx4 v[72:73], v[30:33], off offset:224
	s_cbranch_scc1 .LBB0_979

.LBB0_1717:
	s_cmp_gt_i32 s52, 12
	s_cselect_b64 s[0:1], -1, 0
	s_cmp_lt_i32 s53, 13
	s_cselect_b64 s[2:3], -1, 0
	s_or_b64 s[0:1], s[0:1], s[2:3]
	s_and_b64 vcc, exec, s[0:1]
	s_cbranch_vccnz .LBB0_1789
	v_readlane_b32 s0, v248, 0
	s_cmpk_gt_u32 s0, 0x17f
	s_cbranch_scc1 .LBB0_1721
	v_lshlrev_b32_e32 v2, 4, v1
	v_and_b32_e32 v74, 0x70, v2
	v_mov_b32_e32 v75, 0
	v_lshl_add_u64 v[2:3], s[82:83], 0, v[74:75]
	s_mov_b64 s[6:7], 0xb080000
	v_lshl_add_u64 v[76:77], v[2:3], 0, s[6:7]
	s_mov_b64 s[6:7], 0xc900000
	v_lshl_add_u64 v[78:79], v[2:3], 0, s[6:7]
	v_lshrrev_b32_e32 v2, 1, v1
	v_readlane_b32 s4, v248, 0
	v_and_b32_e32 v97, 0x1c0, v2
	s_lshr_b32 s2, s4, 3
	s_lshr_b32 s3, s50, 3
	v_lshrrev_b32_e32 v93, 3, v1
	v_and_or_b32 v3, v1, 31, v97
	v_and_b32_e32 v2, 16, v2
	s_movk_i32 s5, 0x90
	s_add_u32 s0, s82, 0x4800000
	v_mad_u32_u24 v98, v3, s5, v2
	v_mul_u32_u24_e32 v3, 0x48, v93
	s_addc_u32 s1, s83, 0
	v_lshl_add_u32 v100, v3, 1, v74
	v_lshrrev_b32_e32 v246, 3, v1
	v_and_b32_e32 v246, 15, v246
	v_add_u32_e32 v246, 4, v246
	v_bfe_u32 v246, v246, 3, 1
	v_and_b32_e32 v249, 1, v1
	v_lshlrev_b32_e32 v249, 1, v249
	v_sub_u32_e32 v249, 1, v249
	v_mul_i32_i24_e32 v246, v246, v249
	v_lshlrev_b32_e32 v246, 4, v246
	v_add_u32_e32 v100, v246, v100
	v_lshlrev_b32_e32 v74, 1, v97
	v_and_b32_e32 v92, 0x5f, v1
	s_and_b32 s4, s4, 7
	v_lshl_add_u64 v[4:5], s[0:1], 0, v[74:75]
	v_mov_b32_e32 v3, v75
	s_mul_i32 s4, s4, 12
	v_add_u32_e32 v94, 32, v93
	v_add_u32_e32 v95, 64, v93
	v_add_u32_e32 v96, 0x60, v93
	v_mad_u32_u24 v99, v92, s5, v2
	v_add_u32_e32 v101, 0x9000, v100
	v_lshl_add_u64 v[80:81], v[4:5], 0, v[2:3]
	v_lshl_add_u64 v[82:83], s[0:1], 0, v[2:3]
	s_mov_b32 s1, 0
	s_mov_b32 s5, s2
	s_mov_b32 s0, s2
	s_mov_b32 s6, 0
.LBB0_1720:
	s_lshr_b32 s8, s0, 2
	s_lshl_b32 s0, s0, 7
	s_and_b32 s7, s0, 0x180
	v_or_b32_e32 v2, s7, v93
	v_lshlrev_b32_e32 v74, 10, v2
	s_add_i32 s8, s8, s4
	v_lshl_add_u64 v[66:67], v[76:77], 0, v[74:75]
	v_add_lshl_u32 v74, s7, v94, 10
	s_lshl_b32 s0, s8, 7
	v_lshl_add_u64 v[68:69], v[76:77], 0, v[74:75]
	v_add_lshl_u32 v74, s7, v95, 10
	v_lshl_add_u64 v[70:71], v[76:77], 0, v[74:75]
	v_add_lshl_u32 v74, s7, v96, 10
	v_or_b32_e32 v2, s0, v93
	v_lshl_add_u64 v[72:73], v[76:77], 0, v[74:75]
	v_lshlrev_b32_e32 v74, 10, v2
	v_lshl_add_u64 v[84:85], v[78:79], 0, v[74:75]
	v_add_lshl_u32 v74, s0, v94, 10
	v_lshl_add_u64 v[86:87], v[78:79], 0, v[74:75]
	v_add_lshl_u32 v74, s0, v95, 10
	v_lshl_add_u64 v[88:89], v[78:79], 0, v[74:75]
	v_add_lshl_u32 v74, s0, v96, 10
	v_lshl_add_u64 v[90:91], v[78:79], 0, v[74:75]
	global_load_dwordx4 v[2:5], v[66:67], off
	global_load_dwordx4 v[6:9], v[68:69], off
	global_load_dwordx4 v[10:13], v[70:71], off
	global_load_dwordx4 v[14:17], v[72:73], off
	global_load_dwordx4 v[18:21], v[84:85], off
	global_load_dwordx4 v[22:25], v[86:87], off
	global_load_dwordx4 v[26:29], v[88:89], off
	global_load_dwordx4 v[30:33], v[90:91], off
	global_load_dwordx4 v[102:105], v[66:67], off offset:128
	global_load_dwordx4 v[106:109], v[68:69], off offset:128
	global_load_dwordx4 v[110:113], v[70:71], off offset:128
	global_load_dwordx4 v[114:117], v[72:73], off offset:128
	global_load_dwordx4 v[118:121], v[84:85], off offset:128
	global_load_dwordx4 v[122:125], v[86:87], off offset:128
	global_load_dwordx4 v[126:129], v[88:89], off offset:128
	global_load_dwordx4 v[132:135], v[90:91], off offset:128
	s_waitcnt vmcnt(15)
	ds_write_b128 v100, v[2:5]
	s_waitcnt vmcnt(14)
	ds_write_b128 v100, v[6:9] offset:4608
	s_waitcnt vmcnt(13)
	ds_write_b128 v100, v[10:13] offset:9216
	s_waitcnt vmcnt(12)
	ds_write_b128 v100, v[14:17] offset:13824
	s_waitcnt vmcnt(11)
	ds_write_b128 v100, v[18:21] offset:36864
	s_waitcnt vmcnt(10)
	ds_write_b128 v100, v[22:25] offset:41472
	s_waitcnt vmcnt(9)
	ds_write_b128 v100, v[26:29] offset:46080
	s_waitcnt vmcnt(8)
	ds_write_b128 v100, v[30:33] offset:50688
	s_waitcnt lgkmcnt(0)
	s_barrier
	global_load_dwordx4 v[136:139], v[66:67], off offset:256
	global_load_dwordx4 v[140:143], v[68:69], off offset:256
	global_load_dwordx4 v[144:147], v[70:71], off offset:256
	global_load_dwordx4 v[148:151], v[72:73], off offset:256
	global_load_dwordx4 v[152:155], v[84:85], off offset:256
	global_load_dwordx4 v[156:159], v[86:87], off offset:256
	global_load_dwordx4 v[160:163], v[88:89], off offset:256
	global_load_dwordx4 v[164:167], v[90:91], off offset:256
	v_and_b32_e32 v246, 15, v1
	v_add_u32_e32 v246, 4, v246
	v_bfe_u32 v246, v246, 3, 1
	v_bfe_u32 v249, v1, 4, 2
	v_xor_b32_e32 v246, v246, v249
	v_bfe_u32 v249, v1, 5, 1
	v_sub_u32_e32 v246, v246, v249
	v_lshlrev_b32_e32 v246, 4, v246
	v_bfe_u32 v249, v1, 4, 1
	v_mul_u32_u24_e32 v249, 0x900, v249
	v_sub_u32_e32 v246, v246, v249
	v_add_u32_e32 v244, v246, v98
	v_add_u32_e32 v245, v246, v99
	ds_read_b128 v[212:215], v245 offset:36864
	ds_read_b128 v[196:199], v244
	ds_read_b128 v[216:219], v245 offset:39168
	ds_read_b128 v[220:223], v245 offset:41472
	ds_read_b128 v[224:227], v245 offset:43776
	ds_read_b128 v[200:203], v244 offset:2304
	ds_read_b128 v[204:207], v244 offset:4608
	ds_read_b128 v[208:211], v244 offset:6912
	s_waitcnt lgkmcnt(6)
	v_mfma_f32_16x16x32_bf16 v[50:53], v[196:199], v[212:215], 0
	ds_read_b128 v[228:231], v245 offset:36928
	s_waitcnt lgkmcnt(6)
	v_mfma_f32_16x16x32_bf16 v[54:57], v[196:199], v[216:219], 0
	ds_read_b128 v[232:235], v245 offset:39232
	s_waitcnt lgkmcnt(6)
	v_mfma_f32_16x16x32_bf16 v[18:21], v[196:199], v[220:223], 0
	ds_read_b128 v[236:239], v245 offset:41536
	s_waitcnt lgkmcnt(6)
	v_mfma_f32_16x16x32_bf16 v[22:25], v[196:199], v[224:227], 0
	ds_read_b128 v[240:243], v245 offset:43840
	ds_read_b128 v[196:199], v244 offset:64
	s_waitcnt lgkmcnt(7)
	v_mfma_f32_16x16x32_bf16 v[58:61], v[200:203], v[212:215], 0
	v_mfma_f32_16x16x32_bf16 v[62:65], v[200:203], v[216:219], 0
	v_mfma_f32_16x16x32_bf16 v[26:29], v[200:203], v[220:223], 0
	v_mfma_f32_16x16x32_bf16 v[30:33], v[200:203], v[224:227], 0
	ds_read_b128 v[200:203], v244 offset:2368
	s_waitcnt lgkmcnt(7)
	v_mfma_f32_16x16x32_bf16 v[34:37], v[204:207], v[212:215], 0
	v_mfma_f32_16x16x32_bf16 v[38:41], v[204:207], v[216:219], 0
	v_mfma_f32_16x16x32_bf16 v[2:5], v[204:207], v[220:223], 0
	v_mfma_f32_16x16x32_bf16 v[6:9], v[204:207], v[224:227], 0
	ds_read_b128 v[204:207], v244 offset:4672
	s_waitcnt vmcnt(15)
	ds_write_b128 v100, v[102:105] offset:18432
	s_waitcnt vmcnt(14)
	ds_write_b128 v100, v[106:109] offset:23040
	s_waitcnt lgkmcnt(9)
	v_mfma_f32_16x16x32_bf16 v[42:45], v[208:211], v[212:215], 0
	v_mfma_f32_16x16x32_bf16 v[46:49], v[208:211], v[216:219], 0
	v_mfma_f32_16x16x32_bf16 v[10:13], v[208:211], v[220:223], 0
	v_mfma_f32_16x16x32_bf16 v[14:17], v[208:211], v[224:227], 0
	ds_read_b128 v[208:211], v244 offset:6976
	s_waitcnt vmcnt(13)
	ds_write_b128 v100, v[110:113] offset:27648
	s_waitcnt vmcnt(12)
	ds_write_b128 v100, v[114:117] offset:32256
	s_waitcnt lgkmcnt(7)
	v_mfma_f32_16x16x32_bf16 v[50:53], v[196:199], v[228:231], v[50:53]
	v_mfma_f32_16x16x32_bf16 v[54:57], v[196:199], v[232:235], v[54:57]
	v_mfma_f32_16x16x32_bf16 v[18:21], v[196:199], v[236:239], v[18:21]
	v_mfma_f32_16x16x32_bf16 v[22:25], v[196:199], v[240:243], v[22:25]
	s_waitcnt vmcnt(11)
	ds_write_b128 v100, v[118:121] offset:55296
	s_waitcnt vmcnt(10)
	ds_write_b128 v100, v[122:125] offset:59904
	s_waitcnt lgkmcnt(8)
	v_mfma_f32_16x16x32_bf16 v[58:61], v[200:203], v[228:231], v[58:61]
	v_mfma_f32_16x16x32_bf16 v[62:65], v[200:203], v[232:235], v[62:65]
	v_mfma_f32_16x16x32_bf16 v[26:29], v[200:203], v[236:239], v[26:29]
	v_mfma_f32_16x16x32_bf16 v[30:33], v[200:203], v[240:243], v[30:33]
	s_waitcnt vmcnt(9)
	ds_write_b128 v100, v[126:129] offset:64512
	s_waitcnt vmcnt(8)
	ds_write_b128 v101, v[132:135] offset:32256
	s_waitcnt lgkmcnt(9)
	v_mfma_f32_16x16x32_bf16 v[34:37], v[204:207], v[228:231], v[34:37]
	v_mfma_f32_16x16x32_bf16 v[38:41], v[204:207], v[232:235], v[38:41]
	v_mfma_f32_16x16x32_bf16 v[2:5], v[204:207], v[236:239], v[2:5]
	v_mfma_f32_16x16x32_bf16 v[6:9], v[204:207], v[240:243], v[6:9]
	s_waitcnt lgkmcnt(6)
	v_mfma_f32_16x16x32_bf16 v[42:45], v[208:211], v[228:231], v[42:45]
	v_mfma_f32_16x16x32_bf16 v[46:49], v[208:211], v[232:235], v[46:49]
	v_mfma_f32_16x16x32_bf16 v[10:13], v[208:211], v[236:239], v[10:13]
	v_mfma_f32_16x16x32_bf16 v[14:17], v[208:211], v[240:243], v[14:17]
	s_waitcnt lgkmcnt(0)
	s_barrier
	global_load_dwordx4 v[102:105], v[66:67], off offset:384
	global_load_dwordx4 v[106:109], v[68:69], off offset:384
	global_load_dwordx4 v[110:113], v[70:71], off offset:384
	global_load_dwordx4 v[114:117], v[72:73], off offset:384
	global_load_dwordx4 v[118:121], v[84:85], off offset:384
	global_load_dwordx4 v[122:125], v[86:87], off offset:384
	global_load_dwordx4 v[126:129], v[88:89], off offset:384
	global_load_dwordx4 v[132:135], v[90:91], off offset:384
	ds_read_b128 v[212:215], v245 offset:55296
	ds_read_b128 v[196:199], v244 offset:18432
	ds_read_b128 v[216:219], v245 offset:57600
	ds_read_b128 v[220:223], v245 offset:59904
	ds_read_b128 v[224:227], v245 offset:62208
	ds_read_b128 v[200:203], v244 offset:20736
	ds_read_b128 v[204:207], v244 offset:23040
	ds_read_b128 v[208:211], v244 offset:25344
	s_waitcnt lgkmcnt(6)
	v_mfma_f32_16x16x32_bf16 v[50:53], v[196:199], v[212:215], v[50:53]
	ds_read_b128 v[228:231], v245 offset:55360
	s_waitcnt lgkmcnt(6)
	v_mfma_f32_16x16x32_bf16 v[54:57], v[196:199], v[216:219], v[54:57]
	ds_read_b128 v[232:235], v245 offset:57664
	s_waitcnt lgkmcnt(6)
	v_mfma_f32_16x16x32_bf16 v[18:21], v[196:199], v[220:223], v[18:21]
	ds_read_b128 v[236:239], v245 offset:59968
	s_waitcnt lgkmcnt(6)
	v_mfma_f32_16x16x32_bf16 v[22:25], v[196:199], v[224:227], v[22:25]
	ds_read_b128 v[240:243], v245 offset:62272
	ds_read_b128 v[196:199], v244 offset:18496
	s_waitcnt lgkmcnt(7)
	v_mfma_f32_16x16x32_bf16 v[58:61], v[200:203], v[212:215], v[58:61]
	v_mfma_f32_16x16x32_bf16 v[62:65], v[200:203], v[216:219], v[62:65]
	v_mfma_f32_16x16x32_bf16 v[26:29], v[200:203], v[220:223], v[26:29]
	v_mfma_f32_16x16x32_bf16 v[30:33], v[200:203], v[224:227], v[30:33]
	ds_read_b128 v[200:203], v244 offset:20800
	s_waitcnt lgkmcnt(7)
	v_mfma_f32_16x16x32_bf16 v[34:37], v[204:207], v[212:215], v[34:37]
	v_mfma_f32_16x16x32_bf16 v[38:41], v[204:207], v[216:219], v[38:41]
	v_mfma_f32_16x16x32_bf16 v[2:5], v[204:207], v[220:223], v[2:5]
	v_mfma_f32_16x16x32_bf16 v[6:9], v[204:207], v[224:227], v[6:9]
	ds_read_b128 v[204:207], v244 offset:23104
	s_waitcnt vmcnt(15)
	ds_write_b128 v100, v[136:139]
	s_waitcnt vmcnt(14)
	ds_write_b128 v100, v[140:143] offset:4608
	s_waitcnt lgkmcnt(9)
	v_mfma_f32_16x16x32_bf16 v[42:45], v[208:211], v[212:215], v[42:45]
	v_mfma_f32_16x16x32_bf16 v[46:49], v[208:211], v[216:219], v[46:49]
	v_mfma_f32_16x16x32_bf16 v[10:13], v[208:211], v[220:223], v[10:13]
	v_mfma_f32_16x16x32_bf16 v[14:17], v[208:211], v[224:227], v[14:17]
	ds_read_b128 v[208:211], v244 offset:25408
	s_waitcnt vmcnt(13)
	ds_write_b128 v100, v[144:147] offset:9216
	s_waitcnt vmcnt(12)
	ds_write_b128 v100, v[148:151] offset:13824
	s_waitcnt lgkmcnt(7)
	v_mfma_f32_16x16x32_bf16 v[50:53], v[196:199], v[228:231], v[50:53]
	v_mfma_f32_16x16x32_bf16 v[54:57], v[196:199], v[232:235], v[54:57]
	v_mfma_f32_16x16x32_bf16 v[18:21], v[196:199], v[236:239], v[18:21]
	v_mfma_f32_16x16x32_bf16 v[22:25], v[196:199], v[240:243], v[22:25]
	s_waitcnt vmcnt(11)
	ds_write_b128 v100, v[152:155] offset:36864
	s_waitcnt vmcnt(10)
	ds_write_b128 v100, v[156:159] offset:41472
	s_waitcnt lgkmcnt(8)
	v_mfma_f32_16x16x32_bf16 v[58:61], v[200:203], v[228:231], v[58:61]
	v_mfma_f32_16x16x32_bf16 v[62:65], v[200:203], v[232:235], v[62:65]
	v_mfma_f32_16x16x32_bf16 v[26:29], v[200:203], v[236:239], v[26:29]
	v_mfma_f32_16x16x32_bf16 v[30:33], v[200:203], v[240:243], v[30:33]
	s_waitcnt vmcnt(9)
	ds_write_b128 v100, v[160:163] offset:46080
	s_waitcnt vmcnt(8)
	ds_write_b128 v100, v[164:167] offset:50688
	s_waitcnt lgkmcnt(9)
	v_mfma_f32_16x16x32_bf16 v[34:37], v[204:207], v[228:231], v[34:37]
	v_mfma_f32_16x16x32_bf16 v[38:41], v[204:207], v[232:235], v[38:41]
	v_mfma_f32_16x16x32_bf16 v[2:5], v[204:207], v[236:239], v[2:5]
	v_mfma_f32_16x16x32_bf16 v[6:9], v[204:207], v[240:243], v[6:9]
	s_waitcnt lgkmcnt(6)
	v_mfma_f32_16x16x32_bf16 v[42:45], v[208:211], v[228:231], v[42:45]
	v_mfma_f32_16x16x32_bf16 v[46:49], v[208:211], v[232:235], v[46:49]
	v_mfma_f32_16x16x32_bf16 v[10:13], v[208:211], v[236:239], v[10:13]
	v_mfma_f32_16x16x32_bf16 v[14:17], v[208:211], v[240:243], v[14:17]
	s_waitcnt lgkmcnt(0)
	s_barrier
	global_load_dwordx4 v[136:139], v[66:67], off offset:512
	global_load_dwordx4 v[140:143], v[68:69], off offset:512
	global_load_dwordx4 v[144:147], v[70:71], off offset:512
	global_load_dwordx4 v[148:151], v[72:73], off offset:512
	global_load_dwordx4 v[152:155], v[84:85], off offset:512
	global_load_dwordx4 v[156:159], v[86:87], off offset:512
	global_load_dwordx4 v[160:163], v[88:89], off offset:512
	global_load_dwordx4 v[164:167], v[90:91], off offset:512
	ds_read_b128 v[212:215], v245 offset:36864
	ds_read_b128 v[196:199], v244
	ds_read_b128 v[216:219], v245 offset:39168
	ds_read_b128 v[220:223], v245 offset:41472
	ds_read_b128 v[224:227], v245 offset:43776
	ds_read_b128 v[200:203], v244 offset:2304
	ds_read_b128 v[204:207], v244 offset:4608
	ds_read_b128 v[208:211], v244 offset:6912
	s_waitcnt lgkmcnt(6)
	v_mfma_f32_16x16x32_bf16 v[50:53], v[196:199], v[212:215], v[50:53]
	ds_read_b128 v[228:231], v245 offset:36928
	s_waitcnt lgkmcnt(6)
	v_mfma_f32_16x16x32_bf16 v[54:57], v[196:199], v[216:219], v[54:57]
	ds_read_b128 v[232:235], v245 offset:39232
	s_waitcnt lgkmcnt(6)
	v_mfma_f32_16x16x32_bf16 v[18:21], v[196:199], v[220:223], v[18:21]
	ds_read_b128 v[236:239], v245 offset:41536
	s_waitcnt lgkmcnt(6)
	v_mfma_f32_16x16x32_bf16 v[22:25], v[196:199], v[224:227], v[22:25]
	ds_read_b128 v[240:243], v245 offset:43840
	ds_read_b128 v[196:199], v244 offset:64
	s_waitcnt lgkmcnt(7)
	v_mfma_f32_16x16x32_bf16 v[58:61], v[200:203], v[212:215], v[58:61]
	v_mfma_f32_16x16x32_bf16 v[62:65], v[200:203], v[216:219], v[62:65]
	v_mfma_f32_16x16x32_bf16 v[26:29], v[200:203], v[220:223], v[26:29]
	v_mfma_f32_16x16x32_bf16 v[30:33], v[200:203], v[224:227], v[30:33]
	ds_read_b128 v[200:203], v244 offset:2368
	s_waitcnt lgkmcnt(7)
	v_mfma_f32_16x16x32_bf16 v[34:37], v[204:207], v[212:215], v[34:37]
	v_mfma_f32_16x16x32_bf16 v[38:41], v[204:207], v[216:219], v[38:41]
	v_mfma_f32_16x16x32_bf16 v[2:5], v[204:207], v[220:223], v[2:5]
	v_mfma_f32_16x16x32_bf16 v[6:9], v[204:207], v[224:227], v[6:9]
	ds_read_b128 v[204:207], v244 offset:4672
	s_waitcnt vmcnt(15)
	ds_write_b128 v100, v[102:105] offset:18432
	s_waitcnt vmcnt(14)
	ds_write_b128 v100, v[106:109] offset:23040
	s_waitcnt lgkmcnt(9)
	v_mfma_f32_16x16x32_bf16 v[42:45], v[208:211], v[212:215], v[42:45]
	v_mfma_f32_16x16x32_bf16 v[46:49], v[208:211], v[216:219], v[46:49]
	v_mfma_f32_16x16x32_bf16 v[10:13], v[208:211], v[220:223], v[10:13]
	v_mfma_f32_16x16x32_bf16 v[14:17], v[208:211], v[224:227], v[14:17]
	ds_read_b128 v[208:211], v244 offset:6976
	s_waitcnt vmcnt(13)
	ds_write_b128 v100, v[110:113] offset:27648
	s_waitcnt vmcnt(12)
	ds_write_b128 v100, v[114:117] offset:32256
	s_waitcnt lgkmcnt(7)
	v_mfma_f32_16x16x32_bf16 v[50:53], v[196:199], v[228:231], v[50:53]
	v_mfma_f32_16x16x32_bf16 v[54:57], v[196:199], v[232:235], v[54:57]
	v_mfma_f32_16x16x32_bf16 v[18:21], v[196:199], v[236:239], v[18:21]
	v_mfma_f32_16x16x32_bf16 v[22:25], v[196:199], v[240:243], v[22:25]
	s_waitcnt vmcnt(11)
	ds_write_b128 v100, v[118:121] offset:55296
	s_waitcnt vmcnt(10)
	ds_write_b128 v100, v[122:125] offset:59904
	s_waitcnt lgkmcnt(8)
	v_mfma_f32_16x16x32_bf16 v[58:61], v[200:203], v[228:231], v[58:61]
	v_mfma_f32_16x16x32_bf16 v[62:65], v[200:203], v[232:235], v[62:65]
	v_mfma_f32_16x16x32_bf16 v[26:29], v[200:203], v[236:239], v[26:29]
	v_mfma_f32_16x16x32_bf16 v[30:33], v[200:203], v[240:243], v[30:33]
	s_waitcnt vmcnt(9)
	ds_write_b128 v100, v[126:129] offset:64512
	s_waitcnt vmcnt(8)
	ds_write_b128 v101, v[132:135] offset:32256
	s_waitcnt lgkmcnt(9)
	v_mfma_f32_16x16x32_bf16 v[34:37], v[204:207], v[228:231], v[34:37]
	v_mfma_f32_16x16x32_bf16 v[38:41], v[204:207], v[232:235], v[38:41]
	v_mfma_f32_16x16x32_bf16 v[2:5], v[204:207], v[236:239], v[2:5]
	v_mfma_f32_16x16x32_bf16 v[6:9], v[204:207], v[240:243], v[6:9]
	s_waitcnt lgkmcnt(6)
	v_mfma_f32_16x16x32_bf16 v[42:45], v[208:211], v[228:231], v[42:45]
	v_mfma_f32_16x16x32_bf16 v[46:49], v[208:211], v[232:235], v[46:49]
	v_mfma_f32_16x16x32_bf16 v[10:13], v[208:211], v[236:239], v[10:13]
	v_mfma_f32_16x16x32_bf16 v[14:17], v[208:211], v[240:243], v[14:17]
	s_waitcnt lgkmcnt(0)
	s_barrier
	global_load_dwordx4 v[102:105], v[66:67], off offset:640
	global_load_dwordx4 v[106:109], v[68:69], off offset:640
	global_load_dwordx4 v[110:113], v[70:71], off offset:640
	global_load_dwordx4 v[114:117], v[72:73], off offset:640
	global_load_dwordx4 v[118:121], v[84:85], off offset:640
	global_load_dwordx4 v[122:125], v[86:87], off offset:640
	global_load_dwordx4 v[126:129], v[88:89], off offset:640
	global_load_dwordx4 v[132:135], v[90:91], off offset:640
	ds_read_b128 v[212:215], v245 offset:55296
	ds_read_b128 v[196:199], v244 offset:18432
	ds_read_b128 v[216:219], v245 offset:57600
	ds_read_b128 v[220:223], v245 offset:59904
	ds_read_b128 v[224:227], v245 offset:62208
	ds_read_b128 v[200:203], v244 offset:20736
	ds_read_b128 v[204:207], v244 offset:23040
	ds_read_b128 v[208:211], v244 offset:25344
	s_waitcnt lgkmcnt(6)
	v_mfma_f32_16x16x32_bf16 v[50:53], v[196:199], v[212:215], v[50:53]
	ds_read_b128 v[228:231], v245 offset:55360
	s_waitcnt lgkmcnt(6)
	v_mfma_f32_16x16x32_bf16 v[54:57], v[196:199], v[216:219], v[54:57]
	ds_read_b128 v[232:235], v245 offset:57664
	s_waitcnt lgkmcnt(6)
	v_mfma_f32_16x16x32_bf16 v[18:21], v[196:199], v[220:223], v[18:21]
	ds_read_b128 v[236:239], v245 offset:59968
	s_waitcnt lgkmcnt(6)
	v_mfma_f32_16x16x32_bf16 v[22:25], v[196:199], v[224:227], v[22:25]
	ds_read_b128 v[240:243], v245 offset:62272
	ds_read_b128 v[196:199], v244 offset:18496
	s_waitcnt lgkmcnt(7)
	v_mfma_f32_16x16x32_bf16 v[58:61], v[200:203], v[212:215], v[58:61]
	v_mfma_f32_16x16x32_bf16 v[62:65], v[200:203], v[216:219], v[62:65]
	v_mfma_f32_16x16x32_bf16 v[26:29], v[200:203], v[220:223], v[26:29]
	v_mfma_f32_16x16x32_bf16 v[30:33], v[200:203], v[224:227], v[30:33]
	ds_read_b128 v[200:203], v244 offset:20800
	s_waitcnt lgkmcnt(7)
	v_mfma_f32_16x16x32_bf16 v[34:37], v[204:207], v[212:215], v[34:37]
	v_mfma_f32_16x16x32_bf16 v[38:41], v[204:207], v[216:219], v[38:41]
	v_mfma_f32_16x16x32_bf16 v[2:5], v[204:207], v[220:223], v[2:5]
	v_mfma_f32_16x16x32_bf16 v[6:9], v[204:207], v[224:227], v[6:9]
	ds_read_b128 v[204:207], v244 offset:23104
	s_waitcnt vmcnt(15)
	ds_write_b128 v100, v[136:139]
	s_waitcnt vmcnt(14)
	ds_write_b128 v100, v[140:143] offset:4608
	s_waitcnt lgkmcnt(9)
	v_mfma_f32_16x16x32_bf16 v[42:45], v[208:211], v[212:215], v[42:45]
	v_mfma_f32_16x16x32_bf16 v[46:49], v[208:211], v[216:219], v[46:49]
	v_mfma_f32_16x16x32_bf16 v[10:13], v[208:211], v[220:223], v[10:13]
	v_mfma_f32_16x16x32_bf16 v[14:17], v[208:211], v[224:227], v[14:17]
	ds_read_b128 v[208:211], v244 offset:25408
	s_waitcnt vmcnt(13)
	ds_write_b128 v100, v[144:147] offset:9216
	s_waitcnt vmcnt(12)
	ds_write_b128 v100, v[148:151] offset:13824
	s_waitcnt lgkmcnt(7)
	v_mfma_f32_16x16x32_bf16 v[50:53], v[196:199], v[228:231], v[50:53]
	v_mfma_f32_16x16x32_bf16 v[54:57], v[196:199], v[232:235], v[54:57]
	v_mfma_f32_16x16x32_bf16 v[18:21], v[196:199], v[236:239], v[18:21]
	v_mfma_f32_16x16x32_bf16 v[22:25], v[196:199], v[240:243], v[22:25]
	s_waitcnt vmcnt(11)
	ds_write_b128 v100, v[152:155] offset:36864
	s_waitcnt vmcnt(10)
	ds_write_b128 v100, v[156:159] offset:41472
	s_waitcnt lgkmcnt(8)
	v_mfma_f32_16x16x32_bf16 v[58:61], v[200:203], v[228:231], v[58:61]
	v_mfma_f32_16x16x32_bf16 v[62:65], v[200:203], v[232:235], v[62:65]
	v_mfma_f32_16x16x32_bf16 v[26:29], v[200:203], v[236:239], v[26:29]
	v_mfma_f32_16x16x32_bf16 v[30:33], v[200:203], v[240:243], v[30:33]
	s_waitcnt vmcnt(9)
	ds_write_b128 v100, v[160:163] offset:46080
	s_waitcnt vmcnt(8)
	ds_write_b128 v100, v[164:167] offset:50688
	s_waitcnt lgkmcnt(9)
	v_mfma_f32_16x16x32_bf16 v[34:37], v[204:207], v[228:231], v[34:37]
	v_mfma_f32_16x16x32_bf16 v[38:41], v[204:207], v[232:235], v[38:41]
	v_mfma_f32_16x16x32_bf16 v[2:5], v[204:207], v[236:239], v[2:5]
	v_mfma_f32_16x16x32_bf16 v[6:9], v[204:207], v[240:243], v[6:9]
	s_waitcnt lgkmcnt(6)
	v_mfma_f32_16x16x32_bf16 v[42:45], v[208:211], v[228:231], v[42:45]
	v_mfma_f32_16x16x32_bf16 v[46:49], v[208:211], v[232:235], v[46:49]
	v_mfma_f32_16x16x32_bf16 v[10:13], v[208:211], v[236:239], v[10:13]
	v_mfma_f32_16x16x32_bf16 v[14:17], v[208:211], v[240:243], v[14:17]
	s_waitcnt lgkmcnt(0)
	s_barrier
	global_load_dwordx4 v[136:139], v[66:67], off offset:768
	global_load_dwordx4 v[140:143], v[68:69], off offset:768
	global_load_dwordx4 v[144:147], v[70:71], off offset:768
	global_load_dwordx4 v[148:151], v[72:73], off offset:768
	global_load_dwordx4 v[152:155], v[84:85], off offset:768
	global_load_dwordx4 v[156:159], v[86:87], off offset:768
	global_load_dwordx4 v[160:163], v[88:89], off offset:768
	global_load_dwordx4 v[164:167], v[90:91], off offset:768
	ds_read_b128 v[212:215], v245 offset:36864
	ds_read_b128 v[196:199], v244
	ds_read_b128 v[216:219], v245 offset:39168
	ds_read_b128 v[220:223], v245 offset:41472
	ds_read_b128 v[224:227], v245 offset:43776
	ds_read_b128 v[200:203], v244 offset:2304
	ds_read_b128 v[204:207], v244 offset:4608
	ds_read_b128 v[208:211], v244 offset:6912
	s_waitcnt lgkmcnt(6)
	v_mfma_f32_16x16x32_bf16 v[50:53], v[196:199], v[212:215], v[50:53]
	ds_read_b128 v[228:231], v245 offset:36928
	s_waitcnt lgkmcnt(6)
	v_mfma_f32_16x16x32_bf16 v[54:57], v[196:199], v[216:219], v[54:57]
	ds_read_b128 v[232:235], v245 offset:39232
	s_waitcnt lgkmcnt(6)
	v_mfma_f32_16x16x32_bf16 v[18:21], v[196:199], v[220:223], v[18:21]
	ds_read_b128 v[236:239], v245 offset:41536
	s_waitcnt lgkmcnt(6)
	v_mfma_f32_16x16x32_bf16 v[22:25], v[196:199], v[224:227], v[22:25]
	ds_read_b128 v[240:243], v245 offset:43840
	ds_read_b128 v[196:199], v244 offset:64
	s_waitcnt lgkmcnt(7)
	v_mfma_f32_16x16x32_bf16 v[58:61], v[200:203], v[212:215], v[58:61]
	v_mfma_f32_16x16x32_bf16 v[62:65], v[200:203], v[216:219], v[62:65]
	v_mfma_f32_16x16x32_bf16 v[26:29], v[200:203], v[220:223], v[26:29]
	v_mfma_f32_16x16x32_bf16 v[30:33], v[200:203], v[224:227], v[30:33]
	ds_read_b128 v[200:203], v244 offset:2368
	s_waitcnt lgkmcnt(7)
	v_mfma_f32_16x16x32_bf16 v[34:37], v[204:207], v[212:215], v[34:37]
	v_mfma_f32_16x16x32_bf16 v[38:41], v[204:207], v[216:219], v[38:41]
	v_mfma_f32_16x16x32_bf16 v[2:5], v[204:207], v[220:223], v[2:5]
	v_mfma_f32_16x16x32_bf16 v[6:9], v[204:207], v[224:227], v[6:9]
	ds_read_b128 v[204:207], v244 offset:4672
	s_waitcnt vmcnt(15)
	ds_write_b128 v100, v[102:105] offset:18432
	s_waitcnt vmcnt(14)
	ds_write_b128 v100, v[106:109] offset:23040
	s_waitcnt lgkmcnt(9)
	v_mfma_f32_16x16x32_bf16 v[42:45], v[208:211], v[212:215], v[42:45]
	v_mfma_f32_16x16x32_bf16 v[46:49], v[208:211], v[216:219], v[46:49]
	v_mfma_f32_16x16x32_bf16 v[10:13], v[208:211], v[220:223], v[10:13]
	v_mfma_f32_16x16x32_bf16 v[14:17], v[208:211], v[224:227], v[14:17]
	ds_read_b128 v[208:211], v244 offset:6976
	s_waitcnt vmcnt(13)
	ds_write_b128 v100, v[110:113] offset:27648
	s_waitcnt vmcnt(12)
	ds_write_b128 v100, v[114:117] offset:32256
	s_waitcnt lgkmcnt(7)
	v_mfma_f32_16x16x32_bf16 v[50:53], v[196:199], v[228:231], v[50:53]
	v_mfma_f32_16x16x32_bf16 v[54:57], v[196:199], v[232:235], v[54:57]
	v_mfma_f32_16x16x32_bf16 v[18:21], v[196:199], v[236:239], v[18:21]
	v_mfma_f32_16x16x32_bf16 v[22:25], v[196:199], v[240:243], v[22:25]
	s_waitcnt vmcnt(11)
	ds_write_b128 v100, v[118:121] offset:55296
	s_waitcnt vmcnt(10)
	ds_write_b128 v100, v[122:125] offset:59904
	s_waitcnt lgkmcnt(8)
	v_mfma_f32_16x16x32_bf16 v[58:61], v[200:203], v[228:231], v[58:61]
	v_mfma_f32_16x16x32_bf16 v[62:65], v[200:203], v[232:235], v[62:65]
	v_mfma_f32_16x16x32_bf16 v[26:29], v[200:203], v[236:239], v[26:29]
	v_mfma_f32_16x16x32_bf16 v[30:33], v[200:203], v[240:243], v[30:33]
	s_waitcnt vmcnt(9)
	ds_write_b128 v100, v[126:129] offset:64512
	s_waitcnt vmcnt(8)
	ds_write_b128 v101, v[132:135] offset:32256
	s_waitcnt lgkmcnt(9)
	v_mfma_f32_16x16x32_bf16 v[34:37], v[204:207], v[228:231], v[34:37]
	v_mfma_f32_16x16x32_bf16 v[38:41], v[204:207], v[232:235], v[38:41]
	v_mfma_f32_16x16x32_bf16 v[2:5], v[204:207], v[236:239], v[2:5]
	v_mfma_f32_16x16x32_bf16 v[6:9], v[204:207], v[240:243], v[6:9]
	s_waitcnt lgkmcnt(6)
	v_mfma_f32_16x16x32_bf16 v[42:45], v[208:211], v[228:231], v[42:45]
	v_mfma_f32_16x16x32_bf16 v[46:49], v[208:211], v[232:235], v[46:49]
	v_mfma_f32_16x16x32_bf16 v[10:13], v[208:211], v[236:239], v[10:13]
	v_mfma_f32_16x16x32_bf16 v[14:17], v[208:211], v[240:243], v[14:17]
	s_waitcnt lgkmcnt(0)
	s_barrier
	global_load_dwordx4 v[102:105], v[66:67], off offset:896
	s_nop 0
	global_load_dwordx4 v[66:69], v[68:69], off offset:896
	s_nop 0
	global_load_dwordx4 v[106:109], v[70:71], off offset:896
	s_nop 0
	global_load_dwordx4 v[70:73], v[72:73], off offset:896
	s_nop 0
	global_load_dwordx4 v[110:113], v[84:85], off offset:896
	s_nop 0
	global_load_dwordx4 v[84:87], v[86:87], off offset:896
	s_nop 0
	global_load_dwordx4 v[114:117], v[88:89], off offset:896
	s_nop 0
	global_load_dwordx4 v[88:91], v[90:91], off offset:896
	ds_read_b128 v[212:215], v245 offset:55296
	ds_read_b128 v[196:199], v244 offset:18432
	ds_read_b128 v[216:219], v245 offset:57600
	ds_read_b128 v[220:223], v245 offset:59904
	ds_read_b128 v[224:227], v245 offset:62208
	ds_read_b128 v[200:203], v244 offset:20736
	ds_read_b128 v[204:207], v244 offset:23040
	ds_read_b128 v[208:211], v244 offset:25344
	s_waitcnt lgkmcnt(6)
	v_mfma_f32_16x16x32_bf16 v[50:53], v[196:199], v[212:215], v[50:53]
	ds_read_b128 v[228:231], v245 offset:55360
	s_waitcnt lgkmcnt(6)
	v_mfma_f32_16x16x32_bf16 v[54:57], v[196:199], v[216:219], v[54:57]
	ds_read_b128 v[232:235], v245 offset:57664
	s_waitcnt lgkmcnt(6)
	v_mfma_f32_16x16x32_bf16 v[18:21], v[196:199], v[220:223], v[18:21]
	ds_read_b128 v[236:239], v245 offset:59968
	s_waitcnt lgkmcnt(6)
	v_mfma_f32_16x16x32_bf16 v[22:25], v[196:199], v[224:227], v[22:25]
	ds_read_b128 v[240:243], v245 offset:62272
	ds_read_b128 v[196:199], v244 offset:18496
	s_waitcnt lgkmcnt(7)
	v_mfma_f32_16x16x32_bf16 v[58:61], v[200:203], v[212:215], v[58:61]
	v_mfma_f32_16x16x32_bf16 v[62:65], v[200:203], v[216:219], v[62:65]
	v_mfma_f32_16x16x32_bf16 v[26:29], v[200:203], v[220:223], v[26:29]
	v_mfma_f32_16x16x32_bf16 v[30:33], v[200:203], v[224:227], v[30:33]
	ds_read_b128 v[200:203], v244 offset:20800
	s_waitcnt lgkmcnt(7)
	v_mfma_f32_16x16x32_bf16 v[34:37], v[204:207], v[212:215], v[34:37]
	v_mfma_f32_16x16x32_bf16 v[38:41], v[204:207], v[216:219], v[38:41]
	v_mfma_f32_16x16x32_bf16 v[2:5], v[204:207], v[220:223], v[2:5]
	v_mfma_f32_16x16x32_bf16 v[6:9], v[204:207], v[224:227], v[6:9]
	ds_read_b128 v[204:207], v244 offset:23104
	s_waitcnt vmcnt(15)
	ds_write_b128 v100, v[136:139]
	s_waitcnt vmcnt(14)
	ds_write_b128 v100, v[140:143] offset:4608
	s_waitcnt lgkmcnt(9)
	v_mfma_f32_16x16x32_bf16 v[42:45], v[208:211], v[212:215], v[42:45]
	v_mfma_f32_16x16x32_bf16 v[46:49], v[208:211], v[216:219], v[46:49]
	v_mfma_f32_16x16x32_bf16 v[10:13], v[208:211], v[220:223], v[10:13]
	v_mfma_f32_16x16x32_bf16 v[14:17], v[208:211], v[224:227], v[14:17]
	ds_read_b128 v[208:211], v244 offset:25408
	s_waitcnt vmcnt(13)
	ds_write_b128 v100, v[144:147] offset:9216
	s_waitcnt vmcnt(12)
	ds_write_b128 v100, v[148:151] offset:13824
	s_waitcnt lgkmcnt(7)
	v_mfma_f32_16x16x32_bf16 v[50:53], v[196:199], v[228:231], v[50:53]
	v_mfma_f32_16x16x32_bf16 v[54:57], v[196:199], v[232:235], v[54:57]
	v_mfma_f32_16x16x32_bf16 v[18:21], v[196:199], v[236:239], v[18:21]
	v_mfma_f32_16x16x32_bf16 v[22:25], v[196:199], v[240:243], v[22:25]
	s_waitcnt vmcnt(11)
	ds_write_b128 v100, v[152:155] offset:36864
	s_waitcnt vmcnt(10)
	ds_write_b128 v100, v[156:159] offset:41472
	s_waitcnt lgkmcnt(8)
	v_mfma_f32_16x16x32_bf16 v[58:61], v[200:203], v[228:231], v[58:61]
	v_mfma_f32_16x16x32_bf16 v[62:65], v[200:203], v[232:235], v[62:65]
	v_mfma_f32_16x16x32_bf16 v[26:29], v[200:203], v[236:239], v[26:29]
	v_mfma_f32_16x16x32_bf16 v[30:33], v[200:203], v[240:243], v[30:33]
	s_waitcnt vmcnt(9)
	ds_write_b128 v100, v[160:163] offset:46080
	s_waitcnt vmcnt(8)
	ds_write_b128 v100, v[164:167] offset:50688
	s_waitcnt lgkmcnt(9)
	v_mfma_f32_16x16x32_bf16 v[34:37], v[204:207], v[228:231], v[34:37]
	v_mfma_f32_16x16x32_bf16 v[38:41], v[204:207], v[232:235], v[38:41]
	v_mfma_f32_16x16x32_bf16 v[2:5], v[204:207], v[236:239], v[2:5]
	v_mfma_f32_16x16x32_bf16 v[6:9], v[204:207], v[240:243], v[6:9]
	s_waitcnt lgkmcnt(6)
	v_mfma_f32_16x16x32_bf16 v[42:45], v[208:211], v[228:231], v[42:45]
	v_mfma_f32_16x16x32_bf16 v[46:49], v[208:211], v[232:235], v[46:49]
	v_mfma_f32_16x16x32_bf16 v[10:13], v[208:211], v[236:239], v[10:13]
	v_mfma_f32_16x16x32_bf16 v[14:17], v[208:211], v[240:243], v[14:17]
	s_waitcnt lgkmcnt(0)
	s_barrier
	ds_read_b128 v[212:215], v245 offset:36864
	ds_read_b128 v[196:199], v244
	ds_read_b128 v[216:219], v245 offset:39168
	ds_read_b128 v[220:223], v245 offset:41472
	ds_read_b128 v[224:227], v245 offset:43776
	ds_read_b128 v[200:203], v244 offset:2304
	ds_read_b128 v[204:207], v244 offset:4608
	ds_read_b128 v[208:211], v244 offset:6912
	s_waitcnt lgkmcnt(6)
	v_mfma_f32_16x16x32_bf16 v[50:53], v[196:199], v[212:215], v[50:53]
	ds_read_b128 v[228:231], v245 offset:36928
	s_waitcnt lgkmcnt(6)
	v_mfma_f32_16x16x32_bf16 v[54:57], v[196:199], v[216:219], v[54:57]
	ds_read_b128 v[232:235], v245 offset:39232
	s_waitcnt lgkmcnt(6)
	v_mfma_f32_16x16x32_bf16 v[18:21], v[196:199], v[220:223], v[18:21]
	ds_read_b128 v[236:239], v245 offset:41536
	s_waitcnt lgkmcnt(6)
	v_mfma_f32_16x16x32_bf16 v[22:25], v[196:199], v[224:227], v[22:25]
	ds_read_b128 v[240:243], v245 offset:43840
	ds_read_b128 v[196:199], v244 offset:64
	s_waitcnt lgkmcnt(7)
	v_mfma_f32_16x16x32_bf16 v[58:61], v[200:203], v[212:215], v[58:61]
	v_mfma_f32_16x16x32_bf16 v[62:65], v[200:203], v[216:219], v[62:65]
	v_mfma_f32_16x16x32_bf16 v[26:29], v[200:203], v[220:223], v[26:29]
	v_mfma_f32_16x16x32_bf16 v[30:33], v[200:203], v[224:227], v[30:33]
	ds_read_b128 v[200:203], v244 offset:2368
	s_waitcnt lgkmcnt(7)
	v_mfma_f32_16x16x32_bf16 v[34:37], v[204:207], v[212:215], v[34:37]
	v_mfma_f32_16x16x32_bf16 v[38:41], v[204:207], v[216:219], v[38:41]
	v_mfma_f32_16x16x32_bf16 v[2:5], v[204:207], v[220:223], v[2:5]
	v_mfma_f32_16x16x32_bf16 v[6:9], v[204:207], v[224:227], v[6:9]
	ds_read_b128 v[204:207], v244 offset:4672
	s_waitcnt vmcnt(7)
	ds_write_b128 v100, v[102:105] offset:18432
	s_waitcnt vmcnt(6)
	ds_write_b128 v100, v[66:69] offset:23040
	s_waitcnt lgkmcnt(9)
	v_mfma_f32_16x16x32_bf16 v[42:45], v[208:211], v[212:215], v[42:45]
	v_mfma_f32_16x16x32_bf16 v[46:49], v[208:211], v[216:219], v[46:49]
	v_mfma_f32_16x16x32_bf16 v[10:13], v[208:211], v[220:223], v[10:13]
	v_mfma_f32_16x16x32_bf16 v[14:17], v[208:211], v[224:227], v[14:17]
	ds_read_b128 v[208:211], v244 offset:6976
	s_waitcnt vmcnt(5)
	ds_write_b128 v100, v[106:109] offset:27648
	s_waitcnt vmcnt(4)
	ds_write_b128 v100, v[70:73] offset:32256
	s_waitcnt lgkmcnt(7)
	v_mfma_f32_16x16x32_bf16 v[50:53], v[196:199], v[228:231], v[50:53]
	v_mfma_f32_16x16x32_bf16 v[54:57], v[196:199], v[232:235], v[54:57]
	v_mfma_f32_16x16x32_bf16 v[18:21], v[196:199], v[236:239], v[18:21]
	v_mfma_f32_16x16x32_bf16 v[22:25], v[196:199], v[240:243], v[22:25]
	s_waitcnt vmcnt(3)
	ds_write_b128 v100, v[110:113] offset:55296
	s_waitcnt vmcnt(2)
	ds_write_b128 v100, v[84:87] offset:59904
	s_waitcnt lgkmcnt(8)
	v_mfma_f32_16x16x32_bf16 v[58:61], v[200:203], v[228:231], v[58:61]
	v_mfma_f32_16x16x32_bf16 v[62:65], v[200:203], v[232:235], v[62:65]
	v_mfma_f32_16x16x32_bf16 v[26:29], v[200:203], v[236:239], v[26:29]
	v_mfma_f32_16x16x32_bf16 v[30:33], v[200:203], v[240:243], v[30:33]
	s_waitcnt vmcnt(1)
	ds_write_b128 v100, v[114:117] offset:64512
	s_waitcnt vmcnt(0)
	ds_write_b128 v101, v[88:91] offset:32256
	s_waitcnt lgkmcnt(9)
	v_mfma_f32_16x16x32_bf16 v[34:37], v[204:207], v[228:231], v[34:37]
	v_mfma_f32_16x16x32_bf16 v[38:41], v[204:207], v[232:235], v[38:41]
	v_mfma_f32_16x16x32_bf16 v[2:5], v[204:207], v[236:239], v[2:5]
	v_mfma_f32_16x16x32_bf16 v[6:9], v[204:207], v[240:243], v[6:9]
	s_waitcnt lgkmcnt(6)
	v_mfma_f32_16x16x32_bf16 v[42:45], v[208:211], v[228:231], v[42:45]
	v_mfma_f32_16x16x32_bf16 v[46:49], v[208:211], v[232:235], v[46:49]
	v_mfma_f32_16x16x32_bf16 v[10:13], v[208:211], v[236:239], v[10:13]
	v_mfma_f32_16x16x32_bf16 v[14:17], v[208:211], v[240:243], v[14:17]
	s_waitcnt lgkmcnt(0)
	s_barrier
	ds_read_b128 v[212:215], v245 offset:55296
	ds_read_b128 v[196:199], v244 offset:18432
	ds_read_b128 v[216:219], v245 offset:57600
	ds_read_b128 v[220:223], v245 offset:59904
	ds_read_b128 v[224:227], v245 offset:62208
	ds_read_b128 v[200:203], v244 offset:20736
	ds_read_b128 v[204:207], v244 offset:23040
	ds_read_b128 v[208:211], v244 offset:25344
	s_waitcnt lgkmcnt(6)
	v_mfma_f32_16x16x32_bf16 v[50:53], v[196:199], v[212:215], v[50:53]
	ds_read_b128 v[228:231], v245 offset:55360
	s_waitcnt lgkmcnt(6)
	v_mfma_f32_16x16x32_bf16 v[54:57], v[196:199], v[216:219], v[54:57]
	ds_read_b128 v[232:235], v245 offset:57664
	s_waitcnt lgkmcnt(6)
	v_mfma_f32_16x16x32_bf16 v[18:21], v[196:199], v[220:223], v[18:21]
	ds_read_b128 v[236:239], v245 offset:59968
	s_waitcnt lgkmcnt(6)
	v_mfma_f32_16x16x32_bf16 v[22:25], v[196:199], v[224:227], v[22:25]
	ds_read_b128 v[240:243], v245 offset:62272
	ds_read_b128 v[196:199], v244 offset:18496
	s_waitcnt lgkmcnt(7)
	v_mfma_f32_16x16x32_bf16 v[58:61], v[200:203], v[212:215], v[58:61]
	v_mfma_f32_16x16x32_bf16 v[62:65], v[200:203], v[216:219], v[62:65]
	v_mfma_f32_16x16x32_bf16 v[26:29], v[200:203], v[220:223], v[26:29]
	v_mfma_f32_16x16x32_bf16 v[30:33], v[200:203], v[224:227], v[30:33]
	ds_read_b128 v[200:203], v244 offset:20800
	s_waitcnt lgkmcnt(7)
	v_mfma_f32_16x16x32_bf16 v[34:37], v[204:207], v[212:215], v[34:37]
	v_mfma_f32_16x16x32_bf16 v[38:41], v[204:207], v[216:219], v[38:41]
	v_mfma_f32_16x16x32_bf16 v[2:5], v[204:207], v[220:223], v[2:5]
	v_mfma_f32_16x16x32_bf16 v[6:9], v[204:207], v[224:227], v[6:9]
	ds_read_b128 v[204:207], v244 offset:23104
	s_waitcnt lgkmcnt(7)
	v_mfma_f32_16x16x32_bf16 v[42:45], v[208:211], v[212:215], v[42:45]
	v_mfma_f32_16x16x32_bf16 v[46:49], v[208:211], v[216:219], v[46:49]
	v_mfma_f32_16x16x32_bf16 v[10:13], v[208:211], v[220:223], v[10:13]
	v_mfma_f32_16x16x32_bf16 v[14:17], v[208:211], v[224:227], v[14:17]
	ds_read_b128 v[208:211], v244 offset:25408
	s_waitcnt lgkmcnt(3)
	v_mfma_f32_16x16x32_bf16 v[50:53], v[196:199], v[228:231], v[50:53]
	v_mfma_f32_16x16x32_bf16 v[54:57], v[196:199], v[232:235], v[54:57]
	v_mfma_f32_16x16x32_bf16 v[18:21], v[196:199], v[236:239], v[18:21]
	v_mfma_f32_16x16x32_bf16 v[22:25], v[196:199], v[240:243], v[22:25]
	s_waitcnt lgkmcnt(2)
	v_mfma_f32_16x16x32_bf16 v[58:61], v[200:203], v[228:231], v[58:61]
	v_mfma_f32_16x16x32_bf16 v[62:65], v[200:203], v[232:235], v[62:65]
	v_mfma_f32_16x16x32_bf16 v[26:29], v[200:203], v[236:239], v[26:29]
	v_mfma_f32_16x16x32_bf16 v[30:33], v[200:203], v[240:243], v[30:33]
	s_waitcnt lgkmcnt(1)
	v_mfma_f32_16x16x32_bf16 v[34:37], v[204:207], v[228:231], v[34:37]
	v_mfma_f32_16x16x32_bf16 v[38:41], v[204:207], v[232:235], v[38:41]
	v_mfma_f32_16x16x32_bf16 v[2:5], v[204:207], v[236:239], v[2:5]
	v_mfma_f32_16x16x32_bf16 v[6:9], v[204:207], v[240:243], v[6:9]
	s_waitcnt lgkmcnt(0)
	v_mfma_f32_16x16x32_bf16 v[42:45], v[208:211], v[228:231], v[42:45]
	v_mfma_f32_16x16x32_bf16 v[46:49], v[208:211], v[232:235], v[46:49]
	v_mfma_f32_16x16x32_bf16 v[10:13], v[208:211], v[236:239], v[10:13]
	v_mfma_f32_16x16x32_bf16 v[14:17], v[208:211], v[240:243], v[14:17]
	s_add_i32 s6, s6, 1
	s_add_i32 s5, s5, s3
	v_or_b32_e32 v70, s0, v92
	s_lshl_b32 s0, s7, 1
	v_lshl_add_u64 v[110:111], v[80:81], 0, s[0:1]
	v_lshlrev_b32_e32 v74, 10, v70
	v_lshl_add_u64 v[112:113], v[110:111], 0, v[74:75]
	s_waitcnt lgkmcnt(0)
	s_barrier
	s_nop 7
	v_permlane16_swap_b32_e32 v50, v54
	v_permlane16_swap_b32_e32 v51, v55
	v_permlane16_swap_b32_e32 v52, v56
	v_permlane16_swap_b32_e32 v53, v57
	v_permlane16_swap_b32_e32 v58, v62
	v_permlane16_swap_b32_e32 v59, v63
	v_permlane16_swap_b32_e32 v60, v64
	v_permlane16_swap_b32_e32 v61, v65
	v_permlane16_swap_b32_e32 v18, v22
	v_permlane16_swap_b32_e32 v19, v23
	v_permlane16_swap_b32_e32 v20, v24
	v_permlane16_swap_b32_e32 v21, v25
	v_permlane16_swap_b32_e32 v26, v30
	v_permlane16_swap_b32_e32 v27, v31
	v_permlane16_swap_b32_e32 v28, v32
	v_permlane16_swap_b32_e32 v29, v33
	v_permlane16_swap_b32_e32 v34, v38
	v_permlane16_swap_b32_e32 v35, v39
	v_permlane16_swap_b32_e32 v36, v40
	v_permlane16_swap_b32_e32 v37, v41
	v_permlane16_swap_b32_e32 v42, v46
	v_permlane16_swap_b32_e32 v43, v47
	v_permlane16_swap_b32_e32 v44, v48
	v_permlane16_swap_b32_e32 v45, v49
	v_permlane16_swap_b32_e32 v2, v6
	v_permlane16_swap_b32_e32 v3, v7
	v_permlane16_swap_b32_e32 v4, v8
	v_permlane16_swap_b32_e32 v5, v9
	v_permlane16_swap_b32_e32 v10, v14
	v_permlane16_swap_b32_e32 v11, v15
	v_permlane16_swap_b32_e32 v12, v16
	v_permlane16_swap_b32_e32 v13, v17
	v_permlane32_swap_b32_e32 v50, v54
	v_permlane32_swap_b32_e32 v51, v55
	v_permlane32_swap_b32_e32 v52, v56
	v_permlane32_swap_b32_e32 v53, v57
	v_permlane32_swap_b32_e32 v58, v62
	v_permlane32_swap_b32_e32 v59, v63
	v_permlane32_swap_b32_e32 v60, v64
	v_permlane32_swap_b32_e32 v61, v65
	v_permlane32_swap_b32_e32 v18, v22
	v_permlane32_swap_b32_e32 v19, v23
	v_permlane32_swap_b32_e32 v20, v24
	v_permlane32_swap_b32_e32 v21, v25
	v_permlane32_swap_b32_e32 v26, v30
	v_permlane32_swap_b32_e32 v27, v31
	v_permlane32_swap_b32_e32 v28, v32
	v_permlane32_swap_b32_e32 v29, v33
	v_permlane32_swap_b32_e32 v34, v38
	v_permlane32_swap_b32_e32 v35, v39
	v_permlane32_swap_b32_e32 v36, v40
	v_permlane32_swap_b32_e32 v37, v41
	v_permlane32_swap_b32_e32 v42, v46
	v_permlane32_swap_b32_e32 v43, v47
	v_permlane32_swap_b32_e32 v44, v48
	v_permlane32_swap_b32_e32 v45, v49
	v_permlane32_swap_b32_e32 v2, v6
	v_permlane32_swap_b32_e32 v3, v7
	v_permlane32_swap_b32_e32 v4, v8
	v_permlane32_swap_b32_e32 v5, v9
	v_permlane32_swap_b32_e32 v10, v14
	v_permlane32_swap_b32_e32 v11, v15
	v_permlane32_swap_b32_e32 v12, v16
	v_permlane32_swap_b32_e32 v13, v17
	global_load_dwordx4 v[106:109], v[112:113], off
	s_mul_i32 s0, s6, s3
	s_add_i32 s0, s0, s2
	s_cmp_lt_u32 s5, 48
	global_load_dwordx4 v[88:91], v[112:113], off offset:32
	global_load_dwordx4 v[70:73], v[112:113], off offset:64
	s_waitcnt vmcnt(2)
	v_mov_b32_e32 v86, v108
	global_load_dwordx4 v[66:69], v[112:113], off offset:96
	v_permlane32_swap_b32_e32 v106, v86
	v_mov_b32_e32 v102, v109
	s_nop 1
	v_permlane32_swap_b32_e32 v107, v102
	s_waitcnt vmcnt(2)
	v_mov_b32_e32 v108, v90
	v_mov_b32_e32 v109, v91
	s_nop 0
	v_permlane32_swap_b32_e32 v88, v108
	v_permlane32_swap_b32_e32 v89, v109
	s_waitcnt vmcnt(1)
	v_mov_b32_e32 v112, v72
	v_mov_b32_e32 v113, v73
	v_lshlrev_b32_e32 v72, 16, v106
	v_and_b32_e32 v73, 0xffff0000, v106
	v_pk_mul_f32 v[72:73], v[50:51], v[72:73]
	v_lshlrev_b32_e32 v50, 16, v107
	v_and_b32_e32 v51, 0xffff0000, v107
	v_pk_mul_f32 v[84:85], v[52:53], v[50:51]
	v_lshlrev_b32_e32 v50, 16, v86
	v_and_b32_e32 v51, 0xffff0000, v86
	v_pk_mul_f32 v[86:87], v[54:55], v[50:51]
	v_lshlrev_b32_e32 v54, 16, v102
	v_and_b32_e32 v55, 0xffff0000, v102
	v_pk_mul_f32 v[102:103], v[56:57], v[54:55]
	v_cvt_pk_bf16_f32 v55, v84, v85
	v_cvt_pk_bf16_f32 v56, v86, v87
	v_cvt_pk_bf16_f32 v57, v102, v103
	v_cvt_pk_bf16_f32 v54, v72, v73
	v_add_lshl_u32 v72, s7, v97, 1
	v_mov_b32_e32 v73, v75
	v_permlane32_swap_b32_e32 v54, v56
	v_permlane32_swap_b32_e32 v55, v57
	v_lshlrev_b32_e32 v106, 16, v88
	v_and_b32_e32 v107, 0xffff0000, v88
	v_lshlrev_b32_e32 v88, 16, v89
	v_and_b32_e32 v89, 0xffff0000, v89
	v_pk_mul_f32 v[60:61], v[60:61], v[88:89]
	v_lshlrev_b32_e32 v88, 16, v108
	v_and_b32_e32 v89, 0xffff0000, v108
	v_pk_mul_f32 v[62:63], v[62:63], v[88:89]
	v_lshlrev_b32_e32 v88, 16, v109
	v_and_b32_e32 v89, 0xffff0000, v109
	v_pk_mul_f32 v[58:59], v[58:59], v[106:107]
	v_pk_mul_f32 v[64:65], v[64:65], v[88:89]
	v_cvt_pk_bf16_f32 v58, v58, v59
	v_cvt_pk_bf16_f32 v59, v60, v61
	v_cvt_pk_bf16_f32 v60, v62, v63
	v_cvt_pk_bf16_f32 v61, v64, v65
	v_permlane32_swap_b32_e32 v70, v112
	v_permlane32_swap_b32_e32 v58, v60
	v_permlane32_swap_b32_e32 v59, v61
	v_permlane32_swap_b32_e32 v71, v113
	s_waitcnt vmcnt(0)
	v_mov_b32_e32 v114, v68
	v_mov_b32_e32 v115, v69
	v_lshl_add_u64 v[68:69], v[82:83], 0, v[74:75]
	v_or_b32_e32 v74, 0x8000, v74
	v_lshl_add_u64 v[90:91], v[110:111], 0, v[74:75]
	global_load_dwordx4 v[50:53], v[90:91], off
	global_load_dwordx4 v[84:87], v[90:91], off offset:32
	global_load_dwordx4 v[102:105], v[90:91], off offset:64
	v_lshl_add_u64 v[68:69], v[68:69], 0, v[72:73]
	global_store_dwordx4 v[68:69], v[54:57], off
	global_load_dwordx4 v[54:57], v[90:91], off offset:96
	v_permlane32_swap_b32_e32 v66, v114
	global_store_dwordx4 v[68:69], v[58:61], off offset:32
	v_permlane32_swap_b32_e32 v67, v115
	s_nop 0
	v_lshlrev_b32_e32 v58, 16, v70
	v_and_b32_e32 v59, 0xffff0000, v70
	v_pk_mul_f32 v[34:35], v[34:35], v[58:59]
	v_lshlrev_b32_e32 v58, 16, v71
	v_and_b32_e32 v59, 0xffff0000, v71
	v_pk_mul_f32 v[36:37], v[36:37], v[58:59]
	v_lshlrev_b32_e32 v58, 16, v112
	v_and_b32_e32 v59, 0xffff0000, v112
	v_pk_mul_f32 v[38:39], v[38:39], v[58:59]
	v_lshlrev_b32_e32 v58, 16, v113
	v_and_b32_e32 v59, 0xffff0000, v113
	v_pk_mul_f32 v[40:41], v[40:41], v[58:59]
	v_cvt_pk_bf16_f32 v34, v34, v35
	v_cvt_pk_bf16_f32 v35, v36, v37
	v_cvt_pk_bf16_f32 v36, v38, v39
	v_cvt_pk_bf16_f32 v37, v40, v41
	s_nop 0
	v_permlane32_swap_b32_e32 v34, v36
	v_permlane32_swap_b32_e32 v35, v37
	global_store_dwordx4 v[68:69], v[34:37], off offset:64
	v_lshlrev_b32_e32 v38, 16, v114
	v_and_b32_e32 v39, 0xffff0000, v114
	v_lshlrev_b32_e32 v34, 16, v66
	v_and_b32_e32 v35, 0xffff0000, v66
	v_lshlrev_b32_e32 v36, 16, v67
	v_and_b32_e32 v37, 0xffff0000, v67
	v_lshlrev_b32_e32 v40, 16, v115
	v_and_b32_e32 v41, 0xffff0000, v115
	v_pk_mul_f32 v[34:35], v[42:43], v[34:35]
	v_pk_mul_f32 v[36:37], v[44:45], v[36:37]
	v_pk_mul_f32 v[38:39], v[46:47], v[38:39]
	v_pk_mul_f32 v[40:41], v[48:49], v[40:41]
	v_cvt_pk_bf16_f32 v34, v34, v35
	v_cvt_pk_bf16_f32 v35, v36, v37
	v_cvt_pk_bf16_f32 v36, v38, v39
	v_cvt_pk_bf16_f32 v37, v40, v41
	s_nop 0
	v_permlane32_swap_b32_e32 v34, v36
	v_permlane32_swap_b32_e32 v35, v37
	global_store_dwordx4 v[68:69], v[34:37], off offset:96
	s_waitcnt vmcnt(7)
	v_mov_b32_e32 v38, v52
	s_nop 1
	v_permlane32_swap_b32_e32 v50, v38
	v_mov_b32_e32 v39, v53
	s_nop 1
	v_permlane32_swap_b32_e32 v51, v39
	v_lshlrev_b32_e32 v36, 16, v50
	v_and_b32_e32 v37, 0xffff0000, v50
	v_pk_mul_f32 v[18:19], v[18:19], v[36:37]
	v_lshlrev_b32_e32 v36, 16, v51
	v_and_b32_e32 v37, 0xffff0000, v51
	v_pk_mul_f32 v[20:21], v[20:21], v[36:37]
	v_lshlrev_b32_e32 v36, 16, v38
	v_and_b32_e32 v37, 0xffff0000, v38
	v_pk_mul_f32 v[22:23], v[22:23], v[36:37]
	v_lshlrev_b32_e32 v36, 16, v39
	v_and_b32_e32 v37, 0xffff0000, v39
	v_pk_mul_f32 v[24:25], v[24:25], v[36:37]
	s_waitcnt vmcnt(6)
	v_mov_b32_e32 v40, v86
	v_lshl_add_u64 v[34:35], v[82:83], 0, v[74:75]
	v_cvt_pk_bf16_f32 v18, v18, v19
	v_cvt_pk_bf16_f32 v19, v20, v21
	v_cvt_pk_bf16_f32 v20, v22, v23
	v_cvt_pk_bf16_f32 v21, v24, v25
	v_permlane32_swap_b32_e32 v84, v40
	v_mov_b32_e32 v41, v87
	v_permlane32_swap_b32_e32 v18, v20
	v_permlane32_swap_b32_e32 v19, v21
	v_lshl_add_u64 v[22:23], v[34:35], 0, v[72:73]
	v_permlane32_swap_b32_e32 v85, v41
	global_store_dwordx4 v[22:23], v[18:21], off
	v_lshlrev_b32_e32 v24, 16, v40
	v_and_b32_e32 v25, 0xffff0000, v40
	v_lshlrev_b32_e32 v18, 16, v84
	v_and_b32_e32 v19, 0xffff0000, v84
	v_pk_mul_f32 v[18:19], v[26:27], v[18:19]
	v_lshlrev_b32_e32 v20, 16, v85
	v_and_b32_e32 v21, 0xffff0000, v85
	v_lshlrev_b32_e32 v26, 16, v41
	v_and_b32_e32 v27, 0xffff0000, v41
	v_pk_mul_f32 v[20:21], v[28:29], v[20:21]
	v_pk_mul_f32 v[24:25], v[30:31], v[24:25]
	v_pk_mul_f32 v[26:27], v[32:33], v[26:27]
	s_waitcnt vmcnt(6)
	v_mov_b32_e32 v42, v104
	v_cvt_pk_bf16_f32 v18, v18, v19
	v_cvt_pk_bf16_f32 v19, v20, v21
	v_cvt_pk_bf16_f32 v20, v24, v25
	v_cvt_pk_bf16_f32 v21, v26, v27
	v_permlane32_swap_b32_e32 v102, v42
	v_mov_b32_e32 v43, v105
	v_permlane32_swap_b32_e32 v18, v20
	v_permlane32_swap_b32_e32 v19, v21
	v_permlane32_swap_b32_e32 v103, v43
	global_store_dwordx4 v[22:23], v[18:21], off offset:32
	s_waitcnt vmcnt(5)
	v_mov_b32_e32 v44, v56
	v_mov_b32_e32 v45, v57
	v_lshlrev_b32_e32 v18, 16, v102
	v_and_b32_e32 v19, 0xffff0000, v102
	v_pk_mul_f32 v[2:3], v[2:3], v[18:19]
	v_lshlrev_b32_e32 v18, 16, v103
	v_and_b32_e32 v19, 0xffff0000, v103
	v_pk_mul_f32 v[4:5], v[4:5], v[18:19]
	v_lshlrev_b32_e32 v18, 16, v42
	v_and_b32_e32 v19, 0xffff0000, v42
	v_pk_mul_f32 v[6:7], v[6:7], v[18:19]
	v_lshlrev_b32_e32 v18, 16, v43
	v_and_b32_e32 v19, 0xffff0000, v43
	v_pk_mul_f32 v[8:9], v[8:9], v[18:19]
	v_cvt_pk_bf16_f32 v2, v2, v3
	v_cvt_pk_bf16_f32 v3, v4, v5
	v_cvt_pk_bf16_f32 v4, v6, v7
	v_cvt_pk_bf16_f32 v5, v8, v9
	v_permlane32_swap_b32_e32 v54, v44
	v_permlane32_swap_b32_e32 v55, v45
	v_permlane32_swap_b32_e32 v2, v4
	v_permlane32_swap_b32_e32 v3, v5
	global_store_dwordx4 v[22:23], v[2:5], off offset:64
	v_lshlrev_b32_e32 v6, 16, v44
	v_and_b32_e32 v7, 0xffff0000, v44
	v_lshlrev_b32_e32 v2, 16, v54
	v_and_b32_e32 v3, 0xffff0000, v54
	v_lshlrev_b32_e32 v4, 16, v55
	v_and_b32_e32 v5, 0xffff0000, v55
	v_lshlrev_b32_e32 v8, 16, v45
	v_and_b32_e32 v9, 0xffff0000, v45
	v_pk_mul_f32 v[2:3], v[10:11], v[2:3]
	v_pk_mul_f32 v[4:5], v[12:13], v[4:5]
	v_pk_mul_f32 v[6:7], v[14:15], v[6:7]
	v_pk_mul_f32 v[8:9], v[16:17], v[8:9]
	v_cvt_pk_bf16_f32 v2, v2, v3
	v_cvt_pk_bf16_f32 v3, v4, v5
	v_cvt_pk_bf16_f32 v4, v6, v7
	v_cvt_pk_bf16_f32 v5, v8, v9
	s_nop 0
	v_permlane32_swap_b32_e32 v2, v4
	v_permlane32_swap_b32_e32 v3, v5
	global_store_dwordx4 v[22:23], v[2:5], off offset:96
	s_cbranch_scc1 .LBB0_1720

.LBB0_1868:
	s_cmp_gt_i32 s52, 14
	s_cselect_b64 s[0:1], -1, 0
	s_cmp_lt_i32 s53, 15
	s_cselect_b64 s[2:3], -1, 0
	s_or_b64 s[0:1], s[0:1], s[2:3]
	s_and_b64 vcc, exec, s[0:1]
	s_cbranch_vccnz .LBB0_1940
	v_readlane_b32 s0, v248, 0
	s_cmpk_gt_u32 s0, 0x2ff
	s_cbranch_scc1 .LBB0_1872
	v_readlane_b32 s1, v248, 0
	v_lshlrev_b32_e32 v2, 4, v1
	s_lshl_b32 s0, s1, 2
	v_and_b32_e32 v66, 0x70, v2
	v_mov_b32_e32 v67, 0
	s_lshr_b32 s6, s1, 3
	s_and_b32 s8, s0, 4
	s_bfe_u32 s9, s1, 0x20001
	v_lshl_add_u64 v[2:3], s[82:83], 0, v[66:67]
	s_mov_b64 s[0:1], 0xae00000
	v_lshl_add_u64 v[68:69], v[2:3], 0, s[0:1]
	s_mov_b64 s[0:1], 0x3000000
	v_lshl_add_u64 v[70:71], v[2:3], 0, s[0:1]
	v_lshrrev_b32_e32 v2, 1, v1
	v_and_b32_e32 v3, 0x1c0, v2
	v_and_b32_e32 v88, 0x5f, v1
	v_lshrrev_b32_e32 v89, 3, v1
	v_and_or_b32 v4, v1, 31, v3
	v_and_b32_e32 v2, 16, v2
	s_movk_i32 s0, 0x90
	v_mad_u32_u24 v93, v4, s0, v2
	v_mad_u32_u24 v94, v88, s0, v2
	v_mul_u32_u24_e32 v2, 0x48, v89
	v_lshl_add_u32 v95, v2, 1, v66
	v_lshrrev_b32_e32 v246, 3, v1
	v_and_b32_e32 v246, 15, v246
	v_add_u32_e32 v246, 4, v246
	v_bfe_u32 v246, v246, 3, 1
	v_and_b32_e32 v249, 1, v1
	v_lshlrev_b32_e32 v249, 1, v249
	v_sub_u32_e32 v249, 1, v249
	v_mul_i32_i24_e32 v246, v246, v249
	v_lshlrev_b32_e32 v246, 4, v246
	v_add_u32_e32 v95, v246, v95
	s_lshr_b32 s7, s50, 3
	s_mul_i32 s9, s9, 24
	v_add_u32_e32 v90, 32, v89
	v_add_u32_e32 v91, 64, v89
	v_add_u32_e32 v92, 0x60, v89
	v_add_u32_e32 v96, 0x9000, v95
	v_and_or_b32 v97, v89, 4, v3
	s_mov_b32 s1, 0
	s_mov_b64 s[2:3], 0x20000
	s_mov_b32 s10, s6
	s_mov_b32 s4, s6
	s_mov_b32 s11, 0
.LBB0_1871:
	s_lshr_b32 s0, s4, 2
	s_and_b32 s4, s4, 3
	s_or_b32 s4, s4, s8
	s_lshl_b32 s4, s4, 7
	v_or_b32_e32 v2, s4, v89
	v_lshlrev_b32_e32 v66, 11, v2
	s_add_i32 s0, s0, s9
	v_lshl_add_u64 v[72:73], v[68:69], 0, v[66:67]
	v_add_lshl_u32 v66, s4, v90, 11
	s_lshl_b32 s5, s0, 7
	v_lshl_add_u64 v[74:75], v[68:69], 0, v[66:67]
	v_add_lshl_u32 v66, s4, v91, 11
	v_lshl_add_u64 v[76:77], v[68:69], 0, v[66:67]
	v_add_lshl_u32 v66, s4, v92, 11
	v_or_b32_e32 v2, s5, v89
	v_lshl_add_u64 v[78:79], v[68:69], 0, v[66:67]
	v_lshlrev_b32_e32 v66, 11, v2
	v_lshl_add_u64 v[80:81], v[70:71], 0, v[66:67]
	v_add_lshl_u32 v66, s5, v90, 11
	v_lshl_add_u64 v[82:83], v[70:71], 0, v[66:67]
	v_add_lshl_u32 v66, s5, v91, 11
	v_lshl_add_u64 v[84:85], v[70:71], 0, v[66:67]
	v_add_lshl_u32 v66, s5, v92, 11
	v_lshl_add_u64 v[86:87], v[70:71], 0, v[66:67]
	global_load_dwordx4 v[2:5], v[72:73], off
	global_load_dwordx4 v[6:9], v[74:75], off
	global_load_dwordx4 v[10:13], v[76:77], off
	global_load_dwordx4 v[14:17], v[78:79], off
	global_load_dwordx4 v[18:21], v[80:81], off
	global_load_dwordx4 v[22:25], v[82:83], off
	global_load_dwordx4 v[26:29], v[84:85], off
	global_load_dwordx4 v[30:33], v[86:87], off
	global_load_dwordx4 v[98:101], v[72:73], off offset:128
	global_load_dwordx4 v[102:105], v[74:75], off offset:128
	global_load_dwordx4 v[106:109], v[76:77], off offset:128
	global_load_dwordx4 v[110:113], v[78:79], off offset:128
	global_load_dwordx4 v[114:117], v[80:81], off offset:128
	global_load_dwordx4 v[118:121], v[82:83], off offset:128
	global_load_dwordx4 v[122:125], v[84:85], off offset:128
	global_load_dwordx4 v[126:129], v[86:87], off offset:128
	s_waitcnt vmcnt(15)
	ds_write_b128 v95, v[2:5]
	s_waitcnt vmcnt(14)
	ds_write_b128 v95, v[6:9] offset:4608
	s_waitcnt vmcnt(13)
	ds_write_b128 v95, v[10:13] offset:9216
	s_waitcnt vmcnt(12)
	ds_write_b128 v95, v[14:17] offset:13824
	s_waitcnt vmcnt(11)
	ds_write_b128 v95, v[18:21] offset:36864
	s_waitcnt vmcnt(10)
	ds_write_b128 v95, v[22:25] offset:41472
	s_waitcnt vmcnt(9)
	ds_write_b128 v95, v[26:29] offset:46080
	s_waitcnt vmcnt(8)
	ds_write_b128 v95, v[30:33] offset:50688
	s_waitcnt lgkmcnt(0)
	s_barrier
	global_load_dwordx4 v[132:135], v[72:73], off offset:256
	global_load_dwordx4 v[136:139], v[74:75], off offset:256
	global_load_dwordx4 v[140:143], v[76:77], off offset:256
	global_load_dwordx4 v[144:147], v[78:79], off offset:256
	global_load_dwordx4 v[148:151], v[80:81], off offset:256
	global_load_dwordx4 v[152:155], v[82:83], off offset:256
	global_load_dwordx4 v[156:159], v[84:85], off offset:256
	global_load_dwordx4 v[160:163], v[86:87], off offset:256
	v_and_b32_e32 v246, 15, v1
	v_add_u32_e32 v246, 4, v246
	v_bfe_u32 v246, v246, 3, 1
	v_bfe_u32 v249, v1, 4, 2
	v_xor_b32_e32 v246, v246, v249
	v_bfe_u32 v249, v1, 5, 1
	v_sub_u32_e32 v246, v246, v249
	v_lshlrev_b32_e32 v246, 4, v246
	v_bfe_u32 v249, v1, 4, 1
	v_mul_u32_u24_e32 v249, 0x900, v249
	v_sub_u32_e32 v246, v246, v249
	v_add_u32_e32 v244, v246, v93
	v_add_u32_e32 v245, v246, v94
	ds_read_b128 v[212:215], v245 offset:36864
	ds_read_b128 v[196:199], v244
	ds_read_b128 v[216:219], v245 offset:39168
	ds_read_b128 v[220:223], v245 offset:41472
	ds_read_b128 v[224:227], v245 offset:43776
	ds_read_b128 v[200:203], v244 offset:2304
	ds_read_b128 v[204:207], v244 offset:4608
	ds_read_b128 v[208:211], v244 offset:6912
	s_waitcnt lgkmcnt(6)
	v_mfma_f32_16x16x32_bf16 v[34:37], v[196:199], v[212:215], 0
	ds_read_b128 v[228:231], v245 offset:36928
	s_waitcnt lgkmcnt(6)
	v_mfma_f32_16x16x32_bf16 v[38:41], v[196:199], v[216:219], 0
	ds_read_b128 v[232:235], v245 offset:39232
	s_waitcnt lgkmcnt(6)
	v_mfma_f32_16x16x32_bf16 v[2:5], v[196:199], v[220:223], 0
	ds_read_b128 v[236:239], v245 offset:41536
	s_waitcnt lgkmcnt(6)
	v_mfma_f32_16x16x32_bf16 v[6:9], v[196:199], v[224:227], 0
	ds_read_b128 v[240:243], v245 offset:43840
	ds_read_b128 v[196:199], v244 offset:64
	s_waitcnt lgkmcnt(7)
	v_mfma_f32_16x16x32_bf16 v[42:45], v[200:203], v[212:215], 0
	v_mfma_f32_16x16x32_bf16 v[46:49], v[200:203], v[216:219], 0
	v_mfma_f32_16x16x32_bf16 v[10:13], v[200:203], v[220:223], 0
	v_mfma_f32_16x16x32_bf16 v[14:17], v[200:203], v[224:227], 0
	ds_read_b128 v[200:203], v244 offset:2368
	s_waitcnt lgkmcnt(7)
	v_mfma_f32_16x16x32_bf16 v[50:53], v[204:207], v[212:215], 0
	v_mfma_f32_16x16x32_bf16 v[54:57], v[204:207], v[216:219], 0
	v_mfma_f32_16x16x32_bf16 v[18:21], v[204:207], v[220:223], 0
	v_mfma_f32_16x16x32_bf16 v[22:25], v[204:207], v[224:227], 0
	ds_read_b128 v[204:207], v244 offset:4672
	s_waitcnt vmcnt(15)
	ds_write_b128 v95, v[98:101] offset:18432
	s_waitcnt vmcnt(14)
	ds_write_b128 v95, v[102:105] offset:23040
	s_waitcnt lgkmcnt(9)
	v_mfma_f32_16x16x32_bf16 v[58:61], v[208:211], v[212:215], 0
	v_mfma_f32_16x16x32_bf16 v[62:65], v[208:211], v[216:219], 0
	v_mfma_f32_16x16x32_bf16 v[26:29], v[208:211], v[220:223], 0
	v_mfma_f32_16x16x32_bf16 v[30:33], v[208:211], v[224:227], 0
	ds_read_b128 v[208:211], v244 offset:6976
	s_waitcnt vmcnt(13)
	ds_write_b128 v95, v[106:109] offset:27648
	s_waitcnt vmcnt(12)
	ds_write_b128 v95, v[110:113] offset:32256
	s_waitcnt lgkmcnt(7)
	v_mfma_f32_16x16x32_bf16 v[34:37], v[196:199], v[228:231], v[34:37]
	v_mfma_f32_16x16x32_bf16 v[38:41], v[196:199], v[232:235], v[38:41]
	v_mfma_f32_16x16x32_bf16 v[2:5], v[196:199], v[236:239], v[2:5]
	v_mfma_f32_16x16x32_bf16 v[6:9], v[196:199], v[240:243], v[6:9]
	s_waitcnt vmcnt(11)
	ds_write_b128 v95, v[114:117] offset:55296
	s_waitcnt vmcnt(10)
	ds_write_b128 v95, v[118:121] offset:59904
	s_waitcnt lgkmcnt(8)
	v_mfma_f32_16x16x32_bf16 v[42:45], v[200:203], v[228:231], v[42:45]
	v_mfma_f32_16x16x32_bf16 v[46:49], v[200:203], v[232:235], v[46:49]
	v_mfma_f32_16x16x32_bf16 v[10:13], v[200:203], v[236:239], v[10:13]
	v_mfma_f32_16x16x32_bf16 v[14:17], v[200:203], v[240:243], v[14:17]
	s_waitcnt vmcnt(9)
	ds_write_b128 v95, v[122:125] offset:64512
	s_waitcnt vmcnt(8)
	ds_write_b128 v96, v[126:129] offset:32256
	s_waitcnt lgkmcnt(9)
	v_mfma_f32_16x16x32_bf16 v[50:53], v[204:207], v[228:231], v[50:53]
	v_mfma_f32_16x16x32_bf16 v[54:57], v[204:207], v[232:235], v[54:57]
	v_mfma_f32_16x16x32_bf16 v[18:21], v[204:207], v[236:239], v[18:21]
	v_mfma_f32_16x16x32_bf16 v[22:25], v[204:207], v[240:243], v[22:25]
	s_waitcnt lgkmcnt(6)
	v_mfma_f32_16x16x32_bf16 v[58:61], v[208:211], v[228:231], v[58:61]
	v_mfma_f32_16x16x32_bf16 v[62:65], v[208:211], v[232:235], v[62:65]
	v_mfma_f32_16x16x32_bf16 v[26:29], v[208:211], v[236:239], v[26:29]
	v_mfma_f32_16x16x32_bf16 v[30:33], v[208:211], v[240:243], v[30:33]
	s_waitcnt lgkmcnt(0)
	s_barrier
	global_load_dwordx4 v[98:101], v[72:73], off offset:384
	global_load_dwordx4 v[102:105], v[74:75], off offset:384
	global_load_dwordx4 v[106:109], v[76:77], off offset:384
	global_load_dwordx4 v[110:113], v[78:79], off offset:384
	global_load_dwordx4 v[114:117], v[80:81], off offset:384
	global_load_dwordx4 v[118:121], v[82:83], off offset:384
	global_load_dwordx4 v[122:125], v[84:85], off offset:384
	global_load_dwordx4 v[126:129], v[86:87], off offset:384
	ds_read_b128 v[212:215], v245 offset:55296
	ds_read_b128 v[196:199], v244 offset:18432
	ds_read_b128 v[216:219], v245 offset:57600
	ds_read_b128 v[220:223], v245 offset:59904
	ds_read_b128 v[224:227], v245 offset:62208
	ds_read_b128 v[200:203], v244 offset:20736
	ds_read_b128 v[204:207], v244 offset:23040
	ds_read_b128 v[208:211], v244 offset:25344
	s_waitcnt lgkmcnt(6)
	v_mfma_f32_16x16x32_bf16 v[34:37], v[196:199], v[212:215], v[34:37]
	ds_read_b128 v[228:231], v245 offset:55360
	s_waitcnt lgkmcnt(6)
	v_mfma_f32_16x16x32_bf16 v[38:41], v[196:199], v[216:219], v[38:41]
	ds_read_b128 v[232:235], v245 offset:57664
	s_waitcnt lgkmcnt(6)
	v_mfma_f32_16x16x32_bf16 v[2:5], v[196:199], v[220:223], v[2:5]
	ds_read_b128 v[236:239], v245 offset:59968
	s_waitcnt lgkmcnt(6)
	v_mfma_f32_16x16x32_bf16 v[6:9], v[196:199], v[224:227], v[6:9]
	ds_read_b128 v[240:243], v245 offset:62272
	ds_read_b128 v[196:199], v244 offset:18496
	s_waitcnt lgkmcnt(7)
	v_mfma_f32_16x16x32_bf16 v[42:45], v[200:203], v[212:215], v[42:45]
	v_mfma_f32_16x16x32_bf16 v[46:49], v[200:203], v[216:219], v[46:49]
	v_mfma_f32_16x16x32_bf16 v[10:13], v[200:203], v[220:223], v[10:13]
	v_mfma_f32_16x16x32_bf16 v[14:17], v[200:203], v[224:227], v[14:17]
	ds_read_b128 v[200:203], v244 offset:20800
	s_waitcnt lgkmcnt(7)
	v_mfma_f32_16x16x32_bf16 v[50:53], v[204:207], v[212:215], v[50:53]
	v_mfma_f32_16x16x32_bf16 v[54:57], v[204:207], v[216:219], v[54:57]
	v_mfma_f32_16x16x32_bf16 v[18:21], v[204:207], v[220:223], v[18:21]
	v_mfma_f32_16x16x32_bf16 v[22:25], v[204:207], v[224:227], v[22:25]
	ds_read_b128 v[204:207], v244 offset:23104
	s_waitcnt vmcnt(15)
	ds_write_b128 v95, v[132:135]
	s_waitcnt vmcnt(14)
	ds_write_b128 v95, v[136:139] offset:4608
	s_waitcnt lgkmcnt(9)
	v_mfma_f32_16x16x32_bf16 v[58:61], v[208:211], v[212:215], v[58:61]
	v_mfma_f32_16x16x32_bf16 v[62:65], v[208:211], v[216:219], v[62:65]
	v_mfma_f32_16x16x32_bf16 v[26:29], v[208:211], v[220:223], v[26:29]
	v_mfma_f32_16x16x32_bf16 v[30:33], v[208:211], v[224:227], v[30:33]
	ds_read_b128 v[208:211], v244 offset:25408
	s_waitcnt vmcnt(13)
	ds_write_b128 v95, v[140:143] offset:9216
	s_waitcnt vmcnt(12)
	ds_write_b128 v95, v[144:147] offset:13824
	s_waitcnt lgkmcnt(7)
	v_mfma_f32_16x16x32_bf16 v[34:37], v[196:199], v[228:231], v[34:37]
	v_mfma_f32_16x16x32_bf16 v[38:41], v[196:199], v[232:235], v[38:41]
	v_mfma_f32_16x16x32_bf16 v[2:5], v[196:199], v[236:239], v[2:5]
	v_mfma_f32_16x16x32_bf16 v[6:9], v[196:199], v[240:243], v[6:9]
	s_waitcnt vmcnt(11)
	ds_write_b128 v95, v[148:151] offset:36864
	s_waitcnt vmcnt(10)
	ds_write_b128 v95, v[152:155] offset:41472
	s_waitcnt lgkmcnt(8)
	v_mfma_f32_16x16x32_bf16 v[42:45], v[200:203], v[228:231], v[42:45]
	v_mfma_f32_16x16x32_bf16 v[46:49], v[200:203], v[232:235], v[46:49]
	v_mfma_f32_16x16x32_bf16 v[10:13], v[200:203], v[236:239], v[10:13]
	v_mfma_f32_16x16x32_bf16 v[14:17], v[200:203], v[240:243], v[14:17]
	s_waitcnt vmcnt(9)
	ds_write_b128 v95, v[156:159] offset:46080
	s_waitcnt vmcnt(8)
	ds_write_b128 v95, v[160:163] offset:50688
	s_waitcnt lgkmcnt(9)
	v_mfma_f32_16x16x32_bf16 v[50:53], v[204:207], v[228:231], v[50:53]
	v_mfma_f32_16x16x32_bf16 v[54:57], v[204:207], v[232:235], v[54:57]
	v_mfma_f32_16x16x32_bf16 v[18:21], v[204:207], v[236:239], v[18:21]
	v_mfma_f32_16x16x32_bf16 v[22:25], v[204:207], v[240:243], v[22:25]
	s_waitcnt lgkmcnt(6)
	v_mfma_f32_16x16x32_bf16 v[58:61], v[208:211], v[228:231], v[58:61]
	v_mfma_f32_16x16x32_bf16 v[62:65], v[208:211], v[232:235], v[62:65]
	v_mfma_f32_16x16x32_bf16 v[26:29], v[208:211], v[236:239], v[26:29]
	v_mfma_f32_16x16x32_bf16 v[30:33], v[208:211], v[240:243], v[30:33]
	s_waitcnt lgkmcnt(0)
	s_barrier
	global_load_dwordx4 v[132:135], v[72:73], off offset:512
	global_load_dwordx4 v[136:139], v[74:75], off offset:512
	global_load_dwordx4 v[140:143], v[76:77], off offset:512
	global_load_dwordx4 v[144:147], v[78:79], off offset:512
	global_load_dwordx4 v[148:151], v[80:81], off offset:512
	global_load_dwordx4 v[152:155], v[82:83], off offset:512
	global_load_dwordx4 v[156:159], v[84:85], off offset:512
	global_load_dwordx4 v[160:163], v[86:87], off offset:512
	ds_read_b128 v[212:215], v245 offset:36864
	ds_read_b128 v[196:199], v244
	ds_read_b128 v[216:219], v245 offset:39168
	ds_read_b128 v[220:223], v245 offset:41472
	ds_read_b128 v[224:227], v245 offset:43776
	ds_read_b128 v[200:203], v244 offset:2304
	ds_read_b128 v[204:207], v244 offset:4608
	ds_read_b128 v[208:211], v244 offset:6912
	s_waitcnt lgkmcnt(6)
	v_mfma_f32_16x16x32_bf16 v[34:37], v[196:199], v[212:215], v[34:37]
	ds_read_b128 v[228:231], v245 offset:36928
	s_waitcnt lgkmcnt(6)
	v_mfma_f32_16x16x32_bf16 v[38:41], v[196:199], v[216:219], v[38:41]
	ds_read_b128 v[232:235], v245 offset:39232
	s_waitcnt lgkmcnt(6)
	v_mfma_f32_16x16x32_bf16 v[2:5], v[196:199], v[220:223], v[2:5]
	ds_read_b128 v[236:239], v245 offset:41536
	s_waitcnt lgkmcnt(6)
	v_mfma_f32_16x16x32_bf16 v[6:9], v[196:199], v[224:227], v[6:9]
	ds_read_b128 v[240:243], v245 offset:43840
	ds_read_b128 v[196:199], v244 offset:64
	s_waitcnt lgkmcnt(7)
	v_mfma_f32_16x16x32_bf16 v[42:45], v[200:203], v[212:215], v[42:45]
	v_mfma_f32_16x16x32_bf16 v[46:49], v[200:203], v[216:219], v[46:49]
	v_mfma_f32_16x16x32_bf16 v[10:13], v[200:203], v[220:223], v[10:13]
	v_mfma_f32_16x16x32_bf16 v[14:17], v[200:203], v[224:227], v[14:17]
	ds_read_b128 v[200:203], v244 offset:2368
	s_waitcnt lgkmcnt(7)
	v_mfma_f32_16x16x32_bf16 v[50:53], v[204:207], v[212:215], v[50:53]
	v_mfma_f32_16x16x32_bf16 v[54:57], v[204:207], v[216:219], v[54:57]
	v_mfma_f32_16x16x32_bf16 v[18:21], v[204:207], v[220:223], v[18:21]
	v_mfma_f32_16x16x32_bf16 v[22:25], v[204:207], v[224:227], v[22:25]
	ds_read_b128 v[204:207], v244 offset:4672
	s_waitcnt vmcnt(15)
	ds_write_b128 v95, v[98:101] offset:18432
	s_waitcnt vmcnt(14)
	ds_write_b128 v95, v[102:105] offset:23040
	s_waitcnt lgkmcnt(9)
	v_mfma_f32_16x16x32_bf16 v[58:61], v[208:211], v[212:215], v[58:61]
	v_mfma_f32_16x16x32_bf16 v[62:65], v[208:211], v[216:219], v[62:65]
	v_mfma_f32_16x16x32_bf16 v[26:29], v[208:211], v[220:223], v[26:29]
	v_mfma_f32_16x16x32_bf16 v[30:33], v[208:211], v[224:227], v[30:33]
	ds_read_b128 v[208:211], v244 offset:6976
	s_waitcnt vmcnt(13)
	ds_write_b128 v95, v[106:109] offset:27648
	s_waitcnt vmcnt(12)
	ds_write_b128 v95, v[110:113] offset:32256
	s_waitcnt lgkmcnt(7)
	v_mfma_f32_16x16x32_bf16 v[34:37], v[196:199], v[228:231], v[34:37]
	v_mfma_f32_16x16x32_bf16 v[38:41], v[196:199], v[232:235], v[38:41]
	v_mfma_f32_16x16x32_bf16 v[2:5], v[196:199], v[236:239], v[2:5]
	v_mfma_f32_16x16x32_bf16 v[6:9], v[196:199], v[240:243], v[6:9]
	s_waitcnt vmcnt(11)
	ds_write_b128 v95, v[114:117] offset:55296
	s_waitcnt vmcnt(10)
	ds_write_b128 v95, v[118:121] offset:59904
	s_waitcnt lgkmcnt(8)
	v_mfma_f32_16x16x32_bf16 v[42:45], v[200:203], v[228:231], v[42:45]
	v_mfma_f32_16x16x32_bf16 v[46:49], v[200:203], v[232:235], v[46:49]
	v_mfma_f32_16x16x32_bf16 v[10:13], v[200:203], v[236:239], v[10:13]
	v_mfma_f32_16x16x32_bf16 v[14:17], v[200:203], v[240:243], v[14:17]
	s_waitcnt vmcnt(9)
	ds_write_b128 v95, v[122:125] offset:64512
	s_waitcnt vmcnt(8)
	ds_write_b128 v96, v[126:129] offset:32256
	s_waitcnt lgkmcnt(9)
	v_mfma_f32_16x16x32_bf16 v[50:53], v[204:207], v[228:231], v[50:53]
	v_mfma_f32_16x16x32_bf16 v[54:57], v[204:207], v[232:235], v[54:57]
	v_mfma_f32_16x16x32_bf16 v[18:21], v[204:207], v[236:239], v[18:21]
	v_mfma_f32_16x16x32_bf16 v[22:25], v[204:207], v[240:243], v[22:25]
	s_waitcnt lgkmcnt(6)
	v_mfma_f32_16x16x32_bf16 v[58:61], v[208:211], v[228:231], v[58:61]
	v_mfma_f32_16x16x32_bf16 v[62:65], v[208:211], v[232:235], v[62:65]
	v_mfma_f32_16x16x32_bf16 v[26:29], v[208:211], v[236:239], v[26:29]
	v_mfma_f32_16x16x32_bf16 v[30:33], v[208:211], v[240:243], v[30:33]
	s_waitcnt lgkmcnt(0)
	s_barrier
	global_load_dwordx4 v[98:101], v[72:73], off offset:640
	global_load_dwordx4 v[102:105], v[74:75], off offset:640
	global_load_dwordx4 v[106:109], v[76:77], off offset:640
	global_load_dwordx4 v[110:113], v[78:79], off offset:640
	global_load_dwordx4 v[114:117], v[80:81], off offset:640
	global_load_dwordx4 v[118:121], v[82:83], off offset:640
	global_load_dwordx4 v[122:125], v[84:85], off offset:640
	global_load_dwordx4 v[126:129], v[86:87], off offset:640
	ds_read_b128 v[212:215], v245 offset:55296
	ds_read_b128 v[196:199], v244 offset:18432
	ds_read_b128 v[216:219], v245 offset:57600
	ds_read_b128 v[220:223], v245 offset:59904
	ds_read_b128 v[224:227], v245 offset:62208
	ds_read_b128 v[200:203], v244 offset:20736
	ds_read_b128 v[204:207], v244 offset:23040
	ds_read_b128 v[208:211], v244 offset:25344
	s_waitcnt lgkmcnt(6)
	v_mfma_f32_16x16x32_bf16 v[34:37], v[196:199], v[212:215], v[34:37]
	ds_read_b128 v[228:231], v245 offset:55360
	s_waitcnt lgkmcnt(6)
	v_mfma_f32_16x16x32_bf16 v[38:41], v[196:199], v[216:219], v[38:41]
	ds_read_b128 v[232:235], v245 offset:57664
	s_waitcnt lgkmcnt(6)
	v_mfma_f32_16x16x32_bf16 v[2:5], v[196:199], v[220:223], v[2:5]
	ds_read_b128 v[236:239], v245 offset:59968
	s_waitcnt lgkmcnt(6)
	v_mfma_f32_16x16x32_bf16 v[6:9], v[196:199], v[224:227], v[6:9]
	ds_read_b128 v[240:243], v245 offset:62272
	ds_read_b128 v[196:199], v244 offset:18496
	s_waitcnt lgkmcnt(7)
	v_mfma_f32_16x16x32_bf16 v[42:45], v[200:203], v[212:215], v[42:45]
	v_mfma_f32_16x16x32_bf16 v[46:49], v[200:203], v[216:219], v[46:49]
	v_mfma_f32_16x16x32_bf16 v[10:13], v[200:203], v[220:223], v[10:13]
	v_mfma_f32_16x16x32_bf16 v[14:17], v[200:203], v[224:227], v[14:17]
	ds_read_b128 v[200:203], v244 offset:20800
	s_waitcnt lgkmcnt(7)
	v_mfma_f32_16x16x32_bf16 v[50:53], v[204:207], v[212:215], v[50:53]
	v_mfma_f32_16x16x32_bf16 v[54:57], v[204:207], v[216:219], v[54:57]
	v_mfma_f32_16x16x32_bf16 v[18:21], v[204:207], v[220:223], v[18:21]
	v_mfma_f32_16x16x32_bf16 v[22:25], v[204:207], v[224:227], v[22:25]
	ds_read_b128 v[204:207], v244 offset:23104
	s_waitcnt vmcnt(15)
	ds_write_b128 v95, v[132:135]
	s_waitcnt vmcnt(14)
	ds_write_b128 v95, v[136:139] offset:4608
	s_waitcnt lgkmcnt(9)
	v_mfma_f32_16x16x32_bf16 v[58:61], v[208:211], v[212:215], v[58:61]
	v_mfma_f32_16x16x32_bf16 v[62:65], v[208:211], v[216:219], v[62:65]
	v_mfma_f32_16x16x32_bf16 v[26:29], v[208:211], v[220:223], v[26:29]
	v_mfma_f32_16x16x32_bf16 v[30:33], v[208:211], v[224:227], v[30:33]
	ds_read_b128 v[208:211], v244 offset:25408
	s_waitcnt vmcnt(13)
	ds_write_b128 v95, v[140:143] offset:9216
	s_waitcnt vmcnt(12)
	ds_write_b128 v95, v[144:147] offset:13824
	s_waitcnt lgkmcnt(7)
	v_mfma_f32_16x16x32_bf16 v[34:37], v[196:199], v[228:231], v[34:37]
	v_mfma_f32_16x16x32_bf16 v[38:41], v[196:199], v[232:235], v[38:41]
	v_mfma_f32_16x16x32_bf16 v[2:5], v[196:199], v[236:239], v[2:5]
	v_mfma_f32_16x16x32_bf16 v[6:9], v[196:199], v[240:243], v[6:9]
	s_waitcnt vmcnt(11)
	ds_write_b128 v95, v[148:151] offset:36864
	s_waitcnt vmcnt(10)
	ds_write_b128 v95, v[152:155] offset:41472
	s_waitcnt lgkmcnt(8)
	v_mfma_f32_16x16x32_bf16 v[42:45], v[200:203], v[228:231], v[42:45]
	v_mfma_f32_16x16x32_bf16 v[46:49], v[200:203], v[232:235], v[46:49]
	v_mfma_f32_16x16x32_bf16 v[10:13], v[200:203], v[236:239], v[10:13]
	v_mfma_f32_16x16x32_bf16 v[14:17], v[200:203], v[240:243], v[14:17]
	s_waitcnt vmcnt(9)
	ds_write_b128 v95, v[156:159] offset:46080
	s_waitcnt vmcnt(8)
	ds_write_b128 v95, v[160:163] offset:50688
	s_waitcnt lgkmcnt(9)
	v_mfma_f32_16x16x32_bf16 v[50:53], v[204:207], v[228:231], v[50:53]
	v_mfma_f32_16x16x32_bf16 v[54:57], v[204:207], v[232:235], v[54:57]
	v_mfma_f32_16x16x32_bf16 v[18:21], v[204:207], v[236:239], v[18:21]
	v_mfma_f32_16x16x32_bf16 v[22:25], v[204:207], v[240:243], v[22:25]
	s_waitcnt lgkmcnt(6)
	v_mfma_f32_16x16x32_bf16 v[58:61], v[208:211], v[228:231], v[58:61]
	v_mfma_f32_16x16x32_bf16 v[62:65], v[208:211], v[232:235], v[62:65]
	v_mfma_f32_16x16x32_bf16 v[26:29], v[208:211], v[236:239], v[26:29]
	v_mfma_f32_16x16x32_bf16 v[30:33], v[208:211], v[240:243], v[30:33]
	s_waitcnt lgkmcnt(0)
	s_barrier
	global_load_dwordx4 v[132:135], v[72:73], off offset:768
	global_load_dwordx4 v[136:139], v[74:75], off offset:768
	global_load_dwordx4 v[140:143], v[76:77], off offset:768
	global_load_dwordx4 v[144:147], v[78:79], off offset:768
	global_load_dwordx4 v[148:151], v[80:81], off offset:768
	global_load_dwordx4 v[152:155], v[82:83], off offset:768
	global_load_dwordx4 v[156:159], v[84:85], off offset:768
	global_load_dwordx4 v[160:163], v[86:87], off offset:768
	ds_read_b128 v[212:215], v245 offset:36864
	ds_read_b128 v[196:199], v244
	ds_read_b128 v[216:219], v245 offset:39168
	ds_read_b128 v[220:223], v245 offset:41472
	ds_read_b128 v[224:227], v245 offset:43776
	ds_read_b128 v[200:203], v244 offset:2304
	ds_read_b128 v[204:207], v244 offset:4608
	ds_read_b128 v[208:211], v244 offset:6912
	s_waitcnt lgkmcnt(6)
	v_mfma_f32_16x16x32_bf16 v[34:37], v[196:199], v[212:215], v[34:37]
	ds_read_b128 v[228:231], v245 offset:36928
	s_waitcnt lgkmcnt(6)
	v_mfma_f32_16x16x32_bf16 v[38:41], v[196:199], v[216:219], v[38:41]
	ds_read_b128 v[232:235], v245 offset:39232
	s_waitcnt lgkmcnt(6)
	v_mfma_f32_16x16x32_bf16 v[2:5], v[196:199], v[220:223], v[2:5]
	ds_read_b128 v[236:239], v245 offset:41536
	s_waitcnt lgkmcnt(6)
	v_mfma_f32_16x16x32_bf16 v[6:9], v[196:199], v[224:227], v[6:9]
	ds_read_b128 v[240:243], v245 offset:43840
	ds_read_b128 v[196:199], v244 offset:64
	s_waitcnt lgkmcnt(7)
	v_mfma_f32_16x16x32_bf16 v[42:45], v[200:203], v[212:215], v[42:45]
	v_mfma_f32_16x16x32_bf16 v[46:49], v[200:203], v[216:219], v[46:49]
	v_mfma_f32_16x16x32_bf16 v[10:13], v[200:203], v[220:223], v[10:13]
	v_mfma_f32_16x16x32_bf16 v[14:17], v[200:203], v[224:227], v[14:17]
	ds_read_b128 v[200:203], v244 offset:2368
	s_waitcnt lgkmcnt(7)
	v_mfma_f32_16x16x32_bf16 v[50:53], v[204:207], v[212:215], v[50:53]
	v_mfma_f32_16x16x32_bf16 v[54:57], v[204:207], v[216:219], v[54:57]
	v_mfma_f32_16x16x32_bf16 v[18:21], v[204:207], v[220:223], v[18:21]
	v_mfma_f32_16x16x32_bf16 v[22:25], v[204:207], v[224:227], v[22:25]
	ds_read_b128 v[204:207], v244 offset:4672
	s_waitcnt vmcnt(15)
	ds_write_b128 v95, v[98:101] offset:18432
	s_waitcnt vmcnt(14)
	ds_write_b128 v95, v[102:105] offset:23040
	s_waitcnt lgkmcnt(9)
	v_mfma_f32_16x16x32_bf16 v[58:61], v[208:211], v[212:215], v[58:61]
	v_mfma_f32_16x16x32_bf16 v[62:65], v[208:211], v[216:219], v[62:65]
	v_mfma_f32_16x16x32_bf16 v[26:29], v[208:211], v[220:223], v[26:29]
	v_mfma_f32_16x16x32_bf16 v[30:33], v[208:211], v[224:227], v[30:33]
	ds_read_b128 v[208:211], v244 offset:6976
	s_waitcnt vmcnt(13)
	ds_write_b128 v95, v[106:109] offset:27648
	s_waitcnt vmcnt(12)
	ds_write_b128 v95, v[110:113] offset:32256
	s_waitcnt lgkmcnt(7)
	v_mfma_f32_16x16x32_bf16 v[34:37], v[196:199], v[228:231], v[34:37]
	v_mfma_f32_16x16x32_bf16 v[38:41], v[196:199], v[232:235], v[38:41]
	v_mfma_f32_16x16x32_bf16 v[2:5], v[196:199], v[236:239], v[2:5]
	v_mfma_f32_16x16x32_bf16 v[6:9], v[196:199], v[240:243], v[6:9]
	s_waitcnt vmcnt(11)
	ds_write_b128 v95, v[114:117] offset:55296
	s_waitcnt vmcnt(10)
	ds_write_b128 v95, v[118:121] offset:59904
	s_waitcnt lgkmcnt(8)
	v_mfma_f32_16x16x32_bf16 v[42:45], v[200:203], v[228:231], v[42:45]
	v_mfma_f32_16x16x32_bf16 v[46:49], v[200:203], v[232:235], v[46:49]
	v_mfma_f32_16x16x32_bf16 v[10:13], v[200:203], v[236:239], v[10:13]
	v_mfma_f32_16x16x32_bf16 v[14:17], v[200:203], v[240:243], v[14:17]
	s_waitcnt vmcnt(9)
	ds_write_b128 v95, v[122:125] offset:64512
	s_waitcnt vmcnt(8)
	ds_write_b128 v96, v[126:129] offset:32256
	s_waitcnt lgkmcnt(9)
	v_mfma_f32_16x16x32_bf16 v[50:53], v[204:207], v[228:231], v[50:53]
	v_mfma_f32_16x16x32_bf16 v[54:57], v[204:207], v[232:235], v[54:57]
	v_mfma_f32_16x16x32_bf16 v[18:21], v[204:207], v[236:239], v[18:21]
	v_mfma_f32_16x16x32_bf16 v[22:25], v[204:207], v[240:243], v[22:25]
	s_waitcnt lgkmcnt(6)
	v_mfma_f32_16x16x32_bf16 v[58:61], v[208:211], v[228:231], v[58:61]
	v_mfma_f32_16x16x32_bf16 v[62:65], v[208:211], v[232:235], v[62:65]
	v_mfma_f32_16x16x32_bf16 v[26:29], v[208:211], v[236:239], v[26:29]
	v_mfma_f32_16x16x32_bf16 v[30:33], v[208:211], v[240:243], v[30:33]
	s_waitcnt lgkmcnt(0)
	s_barrier
	global_load_dwordx4 v[98:101], v[72:73], off offset:896
	global_load_dwordx4 v[102:105], v[74:75], off offset:896
	global_load_dwordx4 v[106:109], v[76:77], off offset:896
	global_load_dwordx4 v[110:113], v[78:79], off offset:896
	global_load_dwordx4 v[114:117], v[80:81], off offset:896
	global_load_dwordx4 v[118:121], v[82:83], off offset:896
	global_load_dwordx4 v[122:125], v[84:85], off offset:896
	global_load_dwordx4 v[126:129], v[86:87], off offset:896
	ds_read_b128 v[212:215], v245 offset:55296
	ds_read_b128 v[196:199], v244 offset:18432
	ds_read_b128 v[216:219], v245 offset:57600
	ds_read_b128 v[220:223], v245 offset:59904
	ds_read_b128 v[224:227], v245 offset:62208
	ds_read_b128 v[200:203], v244 offset:20736
	ds_read_b128 v[204:207], v244 offset:23040
	ds_read_b128 v[208:211], v244 offset:25344
	s_waitcnt lgkmcnt(6)
	v_mfma_f32_16x16x32_bf16 v[34:37], v[196:199], v[212:215], v[34:37]
	ds_read_b128 v[228:231], v245 offset:55360
	s_waitcnt lgkmcnt(6)
	v_mfma_f32_16x16x32_bf16 v[38:41], v[196:199], v[216:219], v[38:41]
	ds_read_b128 v[232:235], v245 offset:57664
	s_waitcnt lgkmcnt(6)
	v_mfma_f32_16x16x32_bf16 v[2:5], v[196:199], v[220:223], v[2:5]
	ds_read_b128 v[236:239], v245 offset:59968
	s_waitcnt lgkmcnt(6)
	v_mfma_f32_16x16x32_bf16 v[6:9], v[196:199], v[224:227], v[6:9]
	ds_read_b128 v[240:243], v245 offset:62272
	ds_read_b128 v[196:199], v244 offset:18496
	s_waitcnt lgkmcnt(7)
	v_mfma_f32_16x16x32_bf16 v[42:45], v[200:203], v[212:215], v[42:45]
	v_mfma_f32_16x16x32_bf16 v[46:49], v[200:203], v[216:219], v[46:49]
	v_mfma_f32_16x16x32_bf16 v[10:13], v[200:203], v[220:223], v[10:13]
	v_mfma_f32_16x16x32_bf16 v[14:17], v[200:203], v[224:227], v[14:17]
	ds_read_b128 v[200:203], v244 offset:20800
	s_waitcnt lgkmcnt(7)
	v_mfma_f32_16x16x32_bf16 v[50:53], v[204:207], v[212:215], v[50:53]
	v_mfma_f32_16x16x32_bf16 v[54:57], v[204:207], v[216:219], v[54:57]
	v_mfma_f32_16x16x32_bf16 v[18:21], v[204:207], v[220:223], v[18:21]
	v_mfma_f32_16x16x32_bf16 v[22:25], v[204:207], v[224:227], v[22:25]
	ds_read_b128 v[204:207], v244 offset:23104
	s_waitcnt vmcnt(15)
	ds_write_b128 v95, v[132:135]
	s_waitcnt vmcnt(14)
	ds_write_b128 v95, v[136:139] offset:4608
	s_waitcnt lgkmcnt(9)
	v_mfma_f32_16x16x32_bf16 v[58:61], v[208:211], v[212:215], v[58:61]
	v_mfma_f32_16x16x32_bf16 v[62:65], v[208:211], v[216:219], v[62:65]
	v_mfma_f32_16x16x32_bf16 v[26:29], v[208:211], v[220:223], v[26:29]
	v_mfma_f32_16x16x32_bf16 v[30:33], v[208:211], v[224:227], v[30:33]
	ds_read_b128 v[208:211], v244 offset:25408
	s_waitcnt vmcnt(13)
	ds_write_b128 v95, v[140:143] offset:9216
	s_waitcnt vmcnt(12)
	ds_write_b128 v95, v[144:147] offset:13824
	s_waitcnt lgkmcnt(7)
	v_mfma_f32_16x16x32_bf16 v[34:37], v[196:199], v[228:231], v[34:37]
	v_mfma_f32_16x16x32_bf16 v[38:41], v[196:199], v[232:235], v[38:41]
	v_mfma_f32_16x16x32_bf16 v[2:5], v[196:199], v[236:239], v[2:5]
	v_mfma_f32_16x16x32_bf16 v[6:9], v[196:199], v[240:243], v[6:9]
	s_waitcnt vmcnt(11)
	ds_write_b128 v95, v[148:151] offset:36864
	s_waitcnt vmcnt(10)
	ds_write_b128 v95, v[152:155] offset:41472
	s_waitcnt lgkmcnt(8)
	v_mfma_f32_16x16x32_bf16 v[42:45], v[200:203], v[228:231], v[42:45]
	v_mfma_f32_16x16x32_bf16 v[46:49], v[200:203], v[232:235], v[46:49]
	v_mfma_f32_16x16x32_bf16 v[10:13], v[200:203], v[236:239], v[10:13]
	v_mfma_f32_16x16x32_bf16 v[14:17], v[200:203], v[240:243], v[14:17]
	s_waitcnt vmcnt(9)
	ds_write_b128 v95, v[156:159] offset:46080
	s_waitcnt vmcnt(8)
	ds_write_b128 v95, v[160:163] offset:50688
	s_waitcnt lgkmcnt(9)
	v_mfma_f32_16x16x32_bf16 v[50:53], v[204:207], v[228:231], v[50:53]
	v_mfma_f32_16x16x32_bf16 v[54:57], v[204:207], v[232:235], v[54:57]
	v_mfma_f32_16x16x32_bf16 v[18:21], v[204:207], v[236:239], v[18:21]
	v_mfma_f32_16x16x32_bf16 v[22:25], v[204:207], v[240:243], v[22:25]
	s_waitcnt lgkmcnt(6)
	v_mfma_f32_16x16x32_bf16 v[58:61], v[208:211], v[228:231], v[58:61]
	v_mfma_f32_16x16x32_bf16 v[62:65], v[208:211], v[232:235], v[62:65]
	v_mfma_f32_16x16x32_bf16 v[26:29], v[208:211], v[236:239], v[26:29]
	v_mfma_f32_16x16x32_bf16 v[30:33], v[208:211], v[240:243], v[30:33]
	s_waitcnt lgkmcnt(0)
	s_barrier
	global_load_dwordx4 v[132:135], v[72:73], off offset:1024
	global_load_dwordx4 v[136:139], v[74:75], off offset:1024
	global_load_dwordx4 v[140:143], v[76:77], off offset:1024
	global_load_dwordx4 v[144:147], v[78:79], off offset:1024
	global_load_dwordx4 v[148:151], v[80:81], off offset:1024
	global_load_dwordx4 v[152:155], v[82:83], off offset:1024
	global_load_dwordx4 v[156:159], v[84:85], off offset:1024
	global_load_dwordx4 v[160:163], v[86:87], off offset:1024
	ds_read_b128 v[212:215], v245 offset:36864
	ds_read_b128 v[196:199], v244
	ds_read_b128 v[216:219], v245 offset:39168
	ds_read_b128 v[220:223], v245 offset:41472
	ds_read_b128 v[224:227], v245 offset:43776
	ds_read_b128 v[200:203], v244 offset:2304
	ds_read_b128 v[204:207], v244 offset:4608
	ds_read_b128 v[208:211], v244 offset:6912
	s_waitcnt lgkmcnt(6)
	v_mfma_f32_16x16x32_bf16 v[34:37], v[196:199], v[212:215], v[34:37]
	ds_read_b128 v[228:231], v245 offset:36928
	s_waitcnt lgkmcnt(6)
	v_mfma_f32_16x16x32_bf16 v[38:41], v[196:199], v[216:219], v[38:41]
	ds_read_b128 v[232:235], v245 offset:39232
	s_waitcnt lgkmcnt(6)
	v_mfma_f32_16x16x32_bf16 v[2:5], v[196:199], v[220:223], v[2:5]
	ds_read_b128 v[236:239], v245 offset:41536
	s_waitcnt lgkmcnt(6)
	v_mfma_f32_16x16x32_bf16 v[6:9], v[196:199], v[224:227], v[6:9]
	ds_read_b128 v[240:243], v245 offset:43840
	ds_read_b128 v[196:199], v244 offset:64
	s_waitcnt lgkmcnt(7)
	v_mfma_f32_16x16x32_bf16 v[42:45], v[200:203], v[212:215], v[42:45]
	v_mfma_f32_16x16x32_bf16 v[46:49], v[200:203], v[216:219], v[46:49]
	v_mfma_f32_16x16x32_bf16 v[10:13], v[200:203], v[220:223], v[10:13]
	v_mfma_f32_16x16x32_bf16 v[14:17], v[200:203], v[224:227], v[14:17]
	ds_read_b128 v[200:203], v244 offset:2368
	s_waitcnt lgkmcnt(7)
	v_mfma_f32_16x16x32_bf16 v[50:53], v[204:207], v[212:215], v[50:53]
	v_mfma_f32_16x16x32_bf16 v[54:57], v[204:207], v[216:219], v[54:57]
	v_mfma_f32_16x16x32_bf16 v[18:21], v[204:207], v[220:223], v[18:21]
	v_mfma_f32_16x16x32_bf16 v[22:25], v[204:207], v[224:227], v[22:25]
	ds_read_b128 v[204:207], v244 offset:4672
	s_waitcnt vmcnt(15)
	ds_write_b128 v95, v[98:101] offset:18432
	s_waitcnt vmcnt(14)
	ds_write_b128 v95, v[102:105] offset:23040
	s_waitcnt lgkmcnt(9)
	v_mfma_f32_16x16x32_bf16 v[58:61], v[208:211], v[212:215], v[58:61]
	v_mfma_f32_16x16x32_bf16 v[62:65], v[208:211], v[216:219], v[62:65]
	v_mfma_f32_16x16x32_bf16 v[26:29], v[208:211], v[220:223], v[26:29]
	v_mfma_f32_16x16x32_bf16 v[30:33], v[208:211], v[224:227], v[30:33]
	ds_read_b128 v[208:211], v244 offset:6976
	s_waitcnt vmcnt(13)
	ds_write_b128 v95, v[106:109] offset:27648
	s_waitcnt vmcnt(12)
	ds_write_b128 v95, v[110:113] offset:32256
	s_waitcnt lgkmcnt(7)
	v_mfma_f32_16x16x32_bf16 v[34:37], v[196:199], v[228:231], v[34:37]
	v_mfma_f32_16x16x32_bf16 v[38:41], v[196:199], v[232:235], v[38:41]
	v_mfma_f32_16x16x32_bf16 v[2:5], v[196:199], v[236:239], v[2:5]
	v_mfma_f32_16x16x32_bf16 v[6:9], v[196:199], v[240:243], v[6:9]
	s_waitcnt vmcnt(11)
	ds_write_b128 v95, v[114:117] offset:55296
	s_waitcnt vmcnt(10)
	ds_write_b128 v95, v[118:121] offset:59904
	s_waitcnt lgkmcnt(8)
	v_mfma_f32_16x16x32_bf16 v[42:45], v[200:203], v[228:231], v[42:45]
	v_mfma_f32_16x16x32_bf16 v[46:49], v[200:203], v[232:235], v[46:49]
	v_mfma_f32_16x16x32_bf16 v[10:13], v[200:203], v[236:239], v[10:13]
	v_mfma_f32_16x16x32_bf16 v[14:17], v[200:203], v[240:243], v[14:17]
	s_waitcnt vmcnt(9)
	ds_write_b128 v95, v[122:125] offset:64512
	s_waitcnt vmcnt(8)
	ds_write_b128 v96, v[126:129] offset:32256
	s_waitcnt lgkmcnt(9)
	v_mfma_f32_16x16x32_bf16 v[50:53], v[204:207], v[228:231], v[50:53]
	v_mfma_f32_16x16x32_bf16 v[54:57], v[204:207], v[232:235], v[54:57]
	v_mfma_f32_16x16x32_bf16 v[18:21], v[204:207], v[236:239], v[18:21]
	v_mfma_f32_16x16x32_bf16 v[22:25], v[204:207], v[240:243], v[22:25]
	s_waitcnt lgkmcnt(6)
	v_mfma_f32_16x16x32_bf16 v[58:61], v[208:211], v[228:231], v[58:61]
	v_mfma_f32_16x16x32_bf16 v[62:65], v[208:211], v[232:235], v[62:65]
	v_mfma_f32_16x16x32_bf16 v[26:29], v[208:211], v[236:239], v[26:29]
	v_mfma_f32_16x16x32_bf16 v[30:33], v[208:211], v[240:243], v[30:33]
	s_waitcnt lgkmcnt(0)
	s_barrier
	global_load_dwordx4 v[98:101], v[72:73], off offset:1152
	global_load_dwordx4 v[102:105], v[74:75], off offset:1152
	global_load_dwordx4 v[106:109], v[76:77], off offset:1152
	global_load_dwordx4 v[110:113], v[78:79], off offset:1152
	global_load_dwordx4 v[114:117], v[80:81], off offset:1152
	global_load_dwordx4 v[118:121], v[82:83], off offset:1152
	global_load_dwordx4 v[122:125], v[84:85], off offset:1152
	global_load_dwordx4 v[126:129], v[86:87], off offset:1152
	ds_read_b128 v[212:215], v245 offset:55296
	ds_read_b128 v[196:199], v244 offset:18432
	ds_read_b128 v[216:219], v245 offset:57600
	ds_read_b128 v[220:223], v245 offset:59904
	ds_read_b128 v[224:227], v245 offset:62208
	ds_read_b128 v[200:203], v244 offset:20736
	ds_read_b128 v[204:207], v244 offset:23040
	ds_read_b128 v[208:211], v244 offset:25344
	s_waitcnt lgkmcnt(6)
	v_mfma_f32_16x16x32_bf16 v[34:37], v[196:199], v[212:215], v[34:37]
	ds_read_b128 v[228:231], v245 offset:55360
	s_waitcnt lgkmcnt(6)
	v_mfma_f32_16x16x32_bf16 v[38:41], v[196:199], v[216:219], v[38:41]
	ds_read_b128 v[232:235], v245 offset:57664
	s_waitcnt lgkmcnt(6)
	v_mfma_f32_16x16x32_bf16 v[2:5], v[196:199], v[220:223], v[2:5]
	ds_read_b128 v[236:239], v245 offset:59968
	s_waitcnt lgkmcnt(6)
	v_mfma_f32_16x16x32_bf16 v[6:9], v[196:199], v[224:227], v[6:9]
	ds_read_b128 v[240:243], v245 offset:62272
	ds_read_b128 v[196:199], v244 offset:18496
	s_waitcnt lgkmcnt(7)
	v_mfma_f32_16x16x32_bf16 v[42:45], v[200:203], v[212:215], v[42:45]
	v_mfma_f32_16x16x32_bf16 v[46:49], v[200:203], v[216:219], v[46:49]
	v_mfma_f32_16x16x32_bf16 v[10:13], v[200:203], v[220:223], v[10:13]
	v_mfma_f32_16x16x32_bf16 v[14:17], v[200:203], v[224:227], v[14:17]
	ds_read_b128 v[200:203], v244 offset:20800
	s_waitcnt lgkmcnt(7)
	v_mfma_f32_16x16x32_bf16 v[50:53], v[204:207], v[212:215], v[50:53]
	v_mfma_f32_16x16x32_bf16 v[54:57], v[204:207], v[216:219], v[54:57]
	v_mfma_f32_16x16x32_bf16 v[18:21], v[204:207], v[220:223], v[18:21]
	v_mfma_f32_16x16x32_bf16 v[22:25], v[204:207], v[224:227], v[22:25]
	ds_read_b128 v[204:207], v244 offset:23104
	s_waitcnt vmcnt(15)
	ds_write_b128 v95, v[132:135]
	s_waitcnt vmcnt(14)
	ds_write_b128 v95, v[136:139] offset:4608
	s_waitcnt lgkmcnt(9)
	v_mfma_f32_16x16x32_bf16 v[58:61], v[208:211], v[212:215], v[58:61]
	v_mfma_f32_16x16x32_bf16 v[62:65], v[208:211], v[216:219], v[62:65]
	v_mfma_f32_16x16x32_bf16 v[26:29], v[208:211], v[220:223], v[26:29]
	v_mfma_f32_16x16x32_bf16 v[30:33], v[208:211], v[224:227], v[30:33]
	ds_read_b128 v[208:211], v244 offset:25408
	s_waitcnt vmcnt(13)
	ds_write_b128 v95, v[140:143] offset:9216
	s_waitcnt vmcnt(12)
	ds_write_b128 v95, v[144:147] offset:13824
	s_waitcnt lgkmcnt(7)
	v_mfma_f32_16x16x32_bf16 v[34:37], v[196:199], v[228:231], v[34:37]
	v_mfma_f32_16x16x32_bf16 v[38:41], v[196:199], v[232:235], v[38:41]
	v_mfma_f32_16x16x32_bf16 v[2:5], v[196:199], v[236:239], v[2:5]
	v_mfma_f32_16x16x32_bf16 v[6:9], v[196:199], v[240:243], v[6:9]
	s_waitcnt vmcnt(11)
	ds_write_b128 v95, v[148:151] offset:36864
	s_waitcnt vmcnt(10)
	ds_write_b128 v95, v[152:155] offset:41472
	s_waitcnt lgkmcnt(8)
	v_mfma_f32_16x16x32_bf16 v[42:45], v[200:203], v[228:231], v[42:45]
	v_mfma_f32_16x16x32_bf16 v[46:49], v[200:203], v[232:235], v[46:49]
	v_mfma_f32_16x16x32_bf16 v[10:13], v[200:203], v[236:239], v[10:13]
	v_mfma_f32_16x16x32_bf16 v[14:17], v[200:203], v[240:243], v[14:17]
	s_waitcnt vmcnt(9)
	ds_write_b128 v95, v[156:159] offset:46080
	s_waitcnt vmcnt(8)
	ds_write_b128 v95, v[160:163] offset:50688
	s_waitcnt lgkmcnt(9)
	v_mfma_f32_16x16x32_bf16 v[50:53], v[204:207], v[228:231], v[50:53]
	v_mfma_f32_16x16x32_bf16 v[54:57], v[204:207], v[232:235], v[54:57]
	v_mfma_f32_16x16x32_bf16 v[18:21], v[204:207], v[236:239], v[18:21]
	v_mfma_f32_16x16x32_bf16 v[22:25], v[204:207], v[240:243], v[22:25]
	s_waitcnt lgkmcnt(6)
	v_mfma_f32_16x16x32_bf16 v[58:61], v[208:211], v[228:231], v[58:61]
	v_mfma_f32_16x16x32_bf16 v[62:65], v[208:211], v[232:235], v[62:65]
	v_mfma_f32_16x16x32_bf16 v[26:29], v[208:211], v[236:239], v[26:29]
	v_mfma_f32_16x16x32_bf16 v[30:33], v[208:211], v[240:243], v[30:33]
	s_waitcnt lgkmcnt(0)
	s_barrier
	global_load_dwordx4 v[132:135], v[72:73], off offset:1280
	global_load_dwordx4 v[136:139], v[74:75], off offset:1280
	global_load_dwordx4 v[140:143], v[76:77], off offset:1280
	global_load_dwordx4 v[144:147], v[78:79], off offset:1280
	global_load_dwordx4 v[148:151], v[80:81], off offset:1280
	global_load_dwordx4 v[152:155], v[82:83], off offset:1280
	global_load_dwordx4 v[156:159], v[84:85], off offset:1280
	global_load_dwordx4 v[160:163], v[86:87], off offset:1280
	ds_read_b128 v[212:215], v245 offset:36864
	ds_read_b128 v[196:199], v244
	ds_read_b128 v[216:219], v245 offset:39168
	ds_read_b128 v[220:223], v245 offset:41472
	ds_read_b128 v[224:227], v245 offset:43776
	ds_read_b128 v[200:203], v244 offset:2304
	ds_read_b128 v[204:207], v244 offset:4608
	ds_read_b128 v[208:211], v244 offset:6912
	s_waitcnt lgkmcnt(6)
	v_mfma_f32_16x16x32_bf16 v[34:37], v[196:199], v[212:215], v[34:37]
	ds_read_b128 v[228:231], v245 offset:36928
	s_waitcnt lgkmcnt(6)
	v_mfma_f32_16x16x32_bf16 v[38:41], v[196:199], v[216:219], v[38:41]
	ds_read_b128 v[232:235], v245 offset:39232
	s_waitcnt lgkmcnt(6)
	v_mfma_f32_16x16x32_bf16 v[2:5], v[196:199], v[220:223], v[2:5]
	ds_read_b128 v[236:239], v245 offset:41536
	s_waitcnt lgkmcnt(6)
	v_mfma_f32_16x16x32_bf16 v[6:9], v[196:199], v[224:227], v[6:9]
	ds_read_b128 v[240:243], v245 offset:43840
	ds_read_b128 v[196:199], v244 offset:64
	s_waitcnt lgkmcnt(7)
	v_mfma_f32_16x16x32_bf16 v[42:45], v[200:203], v[212:215], v[42:45]
	v_mfma_f32_16x16x32_bf16 v[46:49], v[200:203], v[216:219], v[46:49]
	v_mfma_f32_16x16x32_bf16 v[10:13], v[200:203], v[220:223], v[10:13]
	v_mfma_f32_16x16x32_bf16 v[14:17], v[200:203], v[224:227], v[14:17]
	ds_read_b128 v[200:203], v244 offset:2368
	s_waitcnt lgkmcnt(7)
	v_mfma_f32_16x16x32_bf16 v[50:53], v[204:207], v[212:215], v[50:53]
	v_mfma_f32_16x16x32_bf16 v[54:57], v[204:207], v[216:219], v[54:57]
	v_mfma_f32_16x16x32_bf16 v[18:21], v[204:207], v[220:223], v[18:21]
	v_mfma_f32_16x16x32_bf16 v[22:25], v[204:207], v[224:227], v[22:25]
	ds_read_b128 v[204:207], v244 offset:4672
	s_waitcnt vmcnt(15)
	ds_write_b128 v95, v[98:101] offset:18432
	s_waitcnt vmcnt(14)
	ds_write_b128 v95, v[102:105] offset:23040
	s_waitcnt lgkmcnt(9)
	v_mfma_f32_16x16x32_bf16 v[58:61], v[208:211], v[212:215], v[58:61]
	v_mfma_f32_16x16x32_bf16 v[62:65], v[208:211], v[216:219], v[62:65]
	v_mfma_f32_16x16x32_bf16 v[26:29], v[208:211], v[220:223], v[26:29]
	v_mfma_f32_16x16x32_bf16 v[30:33], v[208:211], v[224:227], v[30:33]
	ds_read_b128 v[208:211], v244 offset:6976
	s_waitcnt vmcnt(13)
	ds_write_b128 v95, v[106:109] offset:27648
	s_waitcnt vmcnt(12)
	ds_write_b128 v95, v[110:113] offset:32256
	s_waitcnt lgkmcnt(7)
	v_mfma_f32_16x16x32_bf16 v[34:37], v[196:199], v[228:231], v[34:37]
	v_mfma_f32_16x16x32_bf16 v[38:41], v[196:199], v[232:235], v[38:41]
	v_mfma_f32_16x16x32_bf16 v[2:5], v[196:199], v[236:239], v[2:5]
	v_mfma_f32_16x16x32_bf16 v[6:9], v[196:199], v[240:243], v[6:9]
	s_waitcnt vmcnt(11)
	ds_write_b128 v95, v[114:117] offset:55296
	s_waitcnt vmcnt(10)
	ds_write_b128 v95, v[118:121] offset:59904
	s_waitcnt lgkmcnt(8)
	v_mfma_f32_16x16x32_bf16 v[42:45], v[200:203], v[228:231], v[42:45]
	v_mfma_f32_16x16x32_bf16 v[46:49], v[200:203], v[232:235], v[46:49]
	v_mfma_f32_16x16x32_bf16 v[10:13], v[200:203], v[236:239], v[10:13]
	v_mfma_f32_16x16x32_bf16 v[14:17], v[200:203], v[240:243], v[14:17]
	s_waitcnt vmcnt(9)
	ds_write_b128 v95, v[122:125] offset:64512
	s_waitcnt vmcnt(8)
	ds_write_b128 v96, v[126:129] offset:32256
	s_waitcnt lgkmcnt(9)
	v_mfma_f32_16x16x32_bf16 v[50:53], v[204:207], v[228:231], v[50:53]
	v_mfma_f32_16x16x32_bf16 v[54:57], v[204:207], v[232:235], v[54:57]
	v_mfma_f32_16x16x32_bf16 v[18:21], v[204:207], v[236:239], v[18:21]
	v_mfma_f32_16x16x32_bf16 v[22:25], v[204:207], v[240:243], v[22:25]
	s_waitcnt lgkmcnt(6)
	v_mfma_f32_16x16x32_bf16 v[58:61], v[208:211], v[228:231], v[58:61]
	v_mfma_f32_16x16x32_bf16 v[62:65], v[208:211], v[232:235], v[62:65]
	v_mfma_f32_16x16x32_bf16 v[26:29], v[208:211], v[236:239], v[26:29]
	v_mfma_f32_16x16x32_bf16 v[30:33], v[208:211], v[240:243], v[30:33]
	s_waitcnt lgkmcnt(0)
	s_barrier
	global_load_dwordx4 v[98:101], v[72:73], off offset:1408
	global_load_dwordx4 v[102:105], v[74:75], off offset:1408
	global_load_dwordx4 v[106:109], v[76:77], off offset:1408
	global_load_dwordx4 v[110:113], v[78:79], off offset:1408
	global_load_dwordx4 v[114:117], v[80:81], off offset:1408
	global_load_dwordx4 v[118:121], v[82:83], off offset:1408
	global_load_dwordx4 v[122:125], v[84:85], off offset:1408
	global_load_dwordx4 v[126:129], v[86:87], off offset:1408
	ds_read_b128 v[212:215], v245 offset:55296
	ds_read_b128 v[196:199], v244 offset:18432
	ds_read_b128 v[216:219], v245 offset:57600
	ds_read_b128 v[220:223], v245 offset:59904
	ds_read_b128 v[224:227], v245 offset:62208
	ds_read_b128 v[200:203], v244 offset:20736
	ds_read_b128 v[204:207], v244 offset:23040
	ds_read_b128 v[208:211], v244 offset:25344
	s_waitcnt lgkmcnt(6)
	v_mfma_f32_16x16x32_bf16 v[34:37], v[196:199], v[212:215], v[34:37]
	ds_read_b128 v[228:231], v245 offset:55360
	s_waitcnt lgkmcnt(6)
	v_mfma_f32_16x16x32_bf16 v[38:41], v[196:199], v[216:219], v[38:41]
	ds_read_b128 v[232:235], v245 offset:57664
	s_waitcnt lgkmcnt(6)
	v_mfma_f32_16x16x32_bf16 v[2:5], v[196:199], v[220:223], v[2:5]
	ds_read_b128 v[236:239], v245 offset:59968
	s_waitcnt lgkmcnt(6)
	v_mfma_f32_16x16x32_bf16 v[6:9], v[196:199], v[224:227], v[6:9]
	ds_read_b128 v[240:243], v245 offset:62272
	ds_read_b128 v[196:199], v244 offset:18496
	s_waitcnt lgkmcnt(7)
	v_mfma_f32_16x16x32_bf16 v[42:45], v[200:203], v[212:215], v[42:45]
	v_mfma_f32_16x16x32_bf16 v[46:49], v[200:203], v[216:219], v[46:49]
	v_mfma_f32_16x16x32_bf16 v[10:13], v[200:203], v[220:223], v[10:13]
	v_mfma_f32_16x16x32_bf16 v[14:17], v[200:203], v[224:227], v[14:17]
	ds_read_b128 v[200:203], v244 offset:20800
	s_waitcnt lgkmcnt(7)
	v_mfma_f32_16x16x32_bf16 v[50:53], v[204:207], v[212:215], v[50:53]
	v_mfma_f32_16x16x32_bf16 v[54:57], v[204:207], v[216:219], v[54:57]
	v_mfma_f32_16x16x32_bf16 v[18:21], v[204:207], v[220:223], v[18:21]
	v_mfma_f32_16x16x32_bf16 v[22:25], v[204:207], v[224:227], v[22:25]
	ds_read_b128 v[204:207], v244 offset:23104
	s_waitcnt vmcnt(15)
	ds_write_b128 v95, v[132:135]
	s_waitcnt vmcnt(14)
	ds_write_b128 v95, v[136:139] offset:4608
	s_waitcnt lgkmcnt(9)
	v_mfma_f32_16x16x32_bf16 v[58:61], v[208:211], v[212:215], v[58:61]
	v_mfma_f32_16x16x32_bf16 v[62:65], v[208:211], v[216:219], v[62:65]
	v_mfma_f32_16x16x32_bf16 v[26:29], v[208:211], v[220:223], v[26:29]
	v_mfma_f32_16x16x32_bf16 v[30:33], v[208:211], v[224:227], v[30:33]
	ds_read_b128 v[208:211], v244 offset:25408
	s_waitcnt vmcnt(13)
	ds_write_b128 v95, v[140:143] offset:9216
	s_waitcnt vmcnt(12)
	ds_write_b128 v95, v[144:147] offset:13824
	s_waitcnt lgkmcnt(7)
	v_mfma_f32_16x16x32_bf16 v[34:37], v[196:199], v[228:231], v[34:37]
	v_mfma_f32_16x16x32_bf16 v[38:41], v[196:199], v[232:235], v[38:41]
	v_mfma_f32_16x16x32_bf16 v[2:5], v[196:199], v[236:239], v[2:5]
	v_mfma_f32_16x16x32_bf16 v[6:9], v[196:199], v[240:243], v[6:9]
	s_waitcnt vmcnt(11)
	ds_write_b128 v95, v[148:151] offset:36864
	s_waitcnt vmcnt(10)
	ds_write_b128 v95, v[152:155] offset:41472
	s_waitcnt lgkmcnt(8)
	v_mfma_f32_16x16x32_bf16 v[42:45], v[200:203], v[228:231], v[42:45]
	v_mfma_f32_16x16x32_bf16 v[46:49], v[200:203], v[232:235], v[46:49]
	v_mfma_f32_16x16x32_bf16 v[10:13], v[200:203], v[236:239], v[10:13]
	v_mfma_f32_16x16x32_bf16 v[14:17], v[200:203], v[240:243], v[14:17]
	s_waitcnt vmcnt(9)
	ds_write_b128 v95, v[156:159] offset:46080
	s_waitcnt vmcnt(8)
	ds_write_b128 v95, v[160:163] offset:50688
	s_waitcnt lgkmcnt(9)
	v_mfma_f32_16x16x32_bf16 v[50:53], v[204:207], v[228:231], v[50:53]
	v_mfma_f32_16x16x32_bf16 v[54:57], v[204:207], v[232:235], v[54:57]
	v_mfma_f32_16x16x32_bf16 v[18:21], v[204:207], v[236:239], v[18:21]
	v_mfma_f32_16x16x32_bf16 v[22:25], v[204:207], v[240:243], v[22:25]
	s_waitcnt lgkmcnt(6)
	v_mfma_f32_16x16x32_bf16 v[58:61], v[208:211], v[228:231], v[58:61]
	v_mfma_f32_16x16x32_bf16 v[62:65], v[208:211], v[232:235], v[62:65]
	v_mfma_f32_16x16x32_bf16 v[26:29], v[208:211], v[236:239], v[26:29]
	v_mfma_f32_16x16x32_bf16 v[30:33], v[208:211], v[240:243], v[30:33]
	s_waitcnt lgkmcnt(0)
	s_barrier
	global_load_dwordx4 v[132:135], v[72:73], off offset:1536
	global_load_dwordx4 v[136:139], v[74:75], off offset:1536
	global_load_dwordx4 v[140:143], v[76:77], off offset:1536
	global_load_dwordx4 v[144:147], v[78:79], off offset:1536
	global_load_dwordx4 v[148:151], v[80:81], off offset:1536
	global_load_dwordx4 v[152:155], v[82:83], off offset:1536
	global_load_dwordx4 v[156:159], v[84:85], off offset:1536
	global_load_dwordx4 v[160:163], v[86:87], off offset:1536
	ds_read_b128 v[212:215], v245 offset:36864
	ds_read_b128 v[196:199], v244
	ds_read_b128 v[216:219], v245 offset:39168
	ds_read_b128 v[220:223], v245 offset:41472
	ds_read_b128 v[224:227], v245 offset:43776
	ds_read_b128 v[200:203], v244 offset:2304
	ds_read_b128 v[204:207], v244 offset:4608
	ds_read_b128 v[208:211], v244 offset:6912
	s_waitcnt lgkmcnt(6)
	v_mfma_f32_16x16x32_bf16 v[34:37], v[196:199], v[212:215], v[34:37]
	ds_read_b128 v[228:231], v245 offset:36928
	s_waitcnt lgkmcnt(6)
	v_mfma_f32_16x16x32_bf16 v[38:41], v[196:199], v[216:219], v[38:41]
	ds_read_b128 v[232:235], v245 offset:39232
	s_waitcnt lgkmcnt(6)
	v_mfma_f32_16x16x32_bf16 v[2:5], v[196:199], v[220:223], v[2:5]
	ds_read_b128 v[236:239], v245 offset:41536
	s_waitcnt lgkmcnt(6)
	v_mfma_f32_16x16x32_bf16 v[6:9], v[196:199], v[224:227], v[6:9]
	ds_read_b128 v[240:243], v245 offset:43840
	ds_read_b128 v[196:199], v244 offset:64
	s_waitcnt lgkmcnt(7)
	v_mfma_f32_16x16x32_bf16 v[42:45], v[200:203], v[212:215], v[42:45]
	v_mfma_f32_16x16x32_bf16 v[46:49], v[200:203], v[216:219], v[46:49]
	v_mfma_f32_16x16x32_bf16 v[10:13], v[200:203], v[220:223], v[10:13]
	v_mfma_f32_16x16x32_bf16 v[14:17], v[200:203], v[224:227], v[14:17]
	ds_read_b128 v[200:203], v244 offset:2368
	s_waitcnt lgkmcnt(7)
	v_mfma_f32_16x16x32_bf16 v[50:53], v[204:207], v[212:215], v[50:53]
	v_mfma_f32_16x16x32_bf16 v[54:57], v[204:207], v[216:219], v[54:57]
	v_mfma_f32_16x16x32_bf16 v[18:21], v[204:207], v[220:223], v[18:21]
	v_mfma_f32_16x16x32_bf16 v[22:25], v[204:207], v[224:227], v[22:25]
	ds_read_b128 v[204:207], v244 offset:4672
	s_waitcnt vmcnt(15)
	ds_write_b128 v95, v[98:101] offset:18432
	s_waitcnt vmcnt(14)
	ds_write_b128 v95, v[102:105] offset:23040
	s_waitcnt lgkmcnt(9)
	v_mfma_f32_16x16x32_bf16 v[58:61], v[208:211], v[212:215], v[58:61]
	v_mfma_f32_16x16x32_bf16 v[62:65], v[208:211], v[216:219], v[62:65]
	v_mfma_f32_16x16x32_bf16 v[26:29], v[208:211], v[220:223], v[26:29]
	v_mfma_f32_16x16x32_bf16 v[30:33], v[208:211], v[224:227], v[30:33]
	ds_read_b128 v[208:211], v244 offset:6976
	s_waitcnt vmcnt(13)
	ds_write_b128 v95, v[106:109] offset:27648
	s_waitcnt vmcnt(12)
	ds_write_b128 v95, v[110:113] offset:32256
	s_waitcnt lgkmcnt(7)
	v_mfma_f32_16x16x32_bf16 v[34:37], v[196:199], v[228:231], v[34:37]
	v_mfma_f32_16x16x32_bf16 v[38:41], v[196:199], v[232:235], v[38:41]
	v_mfma_f32_16x16x32_bf16 v[2:5], v[196:199], v[236:239], v[2:5]
	v_mfma_f32_16x16x32_bf16 v[6:9], v[196:199], v[240:243], v[6:9]
	s_waitcnt vmcnt(11)
	ds_write_b128 v95, v[114:117] offset:55296
	s_waitcnt vmcnt(10)
	ds_write_b128 v95, v[118:121] offset:59904
	s_waitcnt lgkmcnt(8)
	v_mfma_f32_16x16x32_bf16 v[42:45], v[200:203], v[228:231], v[42:45]
	v_mfma_f32_16x16x32_bf16 v[46:49], v[200:203], v[232:235], v[46:49]
	v_mfma_f32_16x16x32_bf16 v[10:13], v[200:203], v[236:239], v[10:13]
	v_mfma_f32_16x16x32_bf16 v[14:17], v[200:203], v[240:243], v[14:17]
	s_waitcnt vmcnt(9)
	ds_write_b128 v95, v[122:125] offset:64512
	s_waitcnt vmcnt(8)
	ds_write_b128 v96, v[126:129] offset:32256
	s_waitcnt lgkmcnt(9)
	v_mfma_f32_16x16x32_bf16 v[50:53], v[204:207], v[228:231], v[50:53]
	v_mfma_f32_16x16x32_bf16 v[54:57], v[204:207], v[232:235], v[54:57]
	v_mfma_f32_16x16x32_bf16 v[18:21], v[204:207], v[236:239], v[18:21]
	v_mfma_f32_16x16x32_bf16 v[22:25], v[204:207], v[240:243], v[22:25]
	s_waitcnt lgkmcnt(6)
	v_mfma_f32_16x16x32_bf16 v[58:61], v[208:211], v[228:231], v[58:61]
	v_mfma_f32_16x16x32_bf16 v[62:65], v[208:211], v[232:235], v[62:65]
	v_mfma_f32_16x16x32_bf16 v[26:29], v[208:211], v[236:239], v[26:29]
	v_mfma_f32_16x16x32_bf16 v[30:33], v[208:211], v[240:243], v[30:33]
	s_waitcnt lgkmcnt(0)
	s_barrier
	global_load_dwordx4 v[98:101], v[72:73], off offset:1664
	global_load_dwordx4 v[102:105], v[74:75], off offset:1664
	global_load_dwordx4 v[106:109], v[76:77], off offset:1664
	global_load_dwordx4 v[110:113], v[78:79], off offset:1664
	global_load_dwordx4 v[114:117], v[80:81], off offset:1664
	global_load_dwordx4 v[118:121], v[82:83], off offset:1664
	global_load_dwordx4 v[122:125], v[84:85], off offset:1664
	global_load_dwordx4 v[126:129], v[86:87], off offset:1664
	ds_read_b128 v[212:215], v245 offset:55296
	ds_read_b128 v[196:199], v244 offset:18432
	ds_read_b128 v[216:219], v245 offset:57600
	ds_read_b128 v[220:223], v245 offset:59904
	ds_read_b128 v[224:227], v245 offset:62208
	ds_read_b128 v[200:203], v244 offset:20736
	ds_read_b128 v[204:207], v244 offset:23040
	ds_read_b128 v[208:211], v244 offset:25344
	s_waitcnt lgkmcnt(6)
	v_mfma_f32_16x16x32_bf16 v[34:37], v[196:199], v[212:215], v[34:37]
	ds_read_b128 v[228:231], v245 offset:55360
	s_waitcnt lgkmcnt(6)
	v_mfma_f32_16x16x32_bf16 v[38:41], v[196:199], v[216:219], v[38:41]
	ds_read_b128 v[232:235], v245 offset:57664
	s_waitcnt lgkmcnt(6)
	v_mfma_f32_16x16x32_bf16 v[2:5], v[196:199], v[220:223], v[2:5]
	ds_read_b128 v[236:239], v245 offset:59968
	s_waitcnt lgkmcnt(6)
	v_mfma_f32_16x16x32_bf16 v[6:9], v[196:199], v[224:227], v[6:9]
	ds_read_b128 v[240:243], v245 offset:62272
	ds_read_b128 v[196:199], v244 offset:18496
	s_waitcnt lgkmcnt(7)
	v_mfma_f32_16x16x32_bf16 v[42:45], v[200:203], v[212:215], v[42:45]
	v_mfma_f32_16x16x32_bf16 v[46:49], v[200:203], v[216:219], v[46:49]
	v_mfma_f32_16x16x32_bf16 v[10:13], v[200:203], v[220:223], v[10:13]
	v_mfma_f32_16x16x32_bf16 v[14:17], v[200:203], v[224:227], v[14:17]
	ds_read_b128 v[200:203], v244 offset:20800
	s_waitcnt lgkmcnt(7)
	v_mfma_f32_16x16x32_bf16 v[50:53], v[204:207], v[212:215], v[50:53]
	v_mfma_f32_16x16x32_bf16 v[54:57], v[204:207], v[216:219], v[54:57]
	v_mfma_f32_16x16x32_bf16 v[18:21], v[204:207], v[220:223], v[18:21]
	v_mfma_f32_16x16x32_bf16 v[22:25], v[204:207], v[224:227], v[22:25]
	ds_read_b128 v[204:207], v244 offset:23104
	s_waitcnt vmcnt(15)
	ds_write_b128 v95, v[132:135]
	s_waitcnt vmcnt(14)
	ds_write_b128 v95, v[136:139] offset:4608
	s_waitcnt lgkmcnt(9)
	v_mfma_f32_16x16x32_bf16 v[58:61], v[208:211], v[212:215], v[58:61]
	v_mfma_f32_16x16x32_bf16 v[62:65], v[208:211], v[216:219], v[62:65]
	v_mfma_f32_16x16x32_bf16 v[26:29], v[208:211], v[220:223], v[26:29]
	v_mfma_f32_16x16x32_bf16 v[30:33], v[208:211], v[224:227], v[30:33]
	ds_read_b128 v[208:211], v244 offset:25408
	s_waitcnt vmcnt(13)
	ds_write_b128 v95, v[140:143] offset:9216
	s_waitcnt vmcnt(12)
	ds_write_b128 v95, v[144:147] offset:13824
	s_waitcnt lgkmcnt(7)
	v_mfma_f32_16x16x32_bf16 v[34:37], v[196:199], v[228:231], v[34:37]
	v_mfma_f32_16x16x32_bf16 v[38:41], v[196:199], v[232:235], v[38:41]
	v_mfma_f32_16x16x32_bf16 v[2:5], v[196:199], v[236:239], v[2:5]
	v_mfma_f32_16x16x32_bf16 v[6:9], v[196:199], v[240:243], v[6:9]
	s_waitcnt vmcnt(11)
	ds_write_b128 v95, v[148:151] offset:36864
	s_waitcnt vmcnt(10)
	ds_write_b128 v95, v[152:155] offset:41472
	s_waitcnt lgkmcnt(8)
	v_mfma_f32_16x16x32_bf16 v[42:45], v[200:203], v[228:231], v[42:45]
	v_mfma_f32_16x16x32_bf16 v[46:49], v[200:203], v[232:235], v[46:49]
	v_mfma_f32_16x16x32_bf16 v[10:13], v[200:203], v[236:239], v[10:13]
	v_mfma_f32_16x16x32_bf16 v[14:17], v[200:203], v[240:243], v[14:17]
	s_waitcnt vmcnt(9)
	ds_write_b128 v95, v[156:159] offset:46080
	s_waitcnt vmcnt(8)
	ds_write_b128 v95, v[160:163] offset:50688
	s_waitcnt lgkmcnt(9)
	v_mfma_f32_16x16x32_bf16 v[50:53], v[204:207], v[228:231], v[50:53]
	v_mfma_f32_16x16x32_bf16 v[54:57], v[204:207], v[232:235], v[54:57]
	v_mfma_f32_16x16x32_bf16 v[18:21], v[204:207], v[236:239], v[18:21]
	v_mfma_f32_16x16x32_bf16 v[22:25], v[204:207], v[240:243], v[22:25]
	s_waitcnt lgkmcnt(6)
	v_mfma_f32_16x16x32_bf16 v[58:61], v[208:211], v[228:231], v[58:61]
	v_mfma_f32_16x16x32_bf16 v[62:65], v[208:211], v[232:235], v[62:65]
	v_mfma_f32_16x16x32_bf16 v[26:29], v[208:211], v[236:239], v[26:29]
	v_mfma_f32_16x16x32_bf16 v[30:33], v[208:211], v[240:243], v[30:33]
	s_waitcnt lgkmcnt(0)
	s_barrier
	global_load_dwordx4 v[132:135], v[72:73], off offset:1792
	global_load_dwordx4 v[136:139], v[74:75], off offset:1792
	global_load_dwordx4 v[140:143], v[76:77], off offset:1792
	global_load_dwordx4 v[144:147], v[78:79], off offset:1792
	global_load_dwordx4 v[148:151], v[80:81], off offset:1792
	global_load_dwordx4 v[152:155], v[82:83], off offset:1792
	global_load_dwordx4 v[156:159], v[84:85], off offset:1792
	global_load_dwordx4 v[160:163], v[86:87], off offset:1792
	ds_read_b128 v[212:215], v245 offset:36864
	ds_read_b128 v[196:199], v244
	ds_read_b128 v[216:219], v245 offset:39168
	ds_read_b128 v[220:223], v245 offset:41472
	ds_read_b128 v[224:227], v245 offset:43776
	ds_read_b128 v[200:203], v244 offset:2304
	ds_read_b128 v[204:207], v244 offset:4608
	ds_read_b128 v[208:211], v244 offset:6912
	s_waitcnt lgkmcnt(6)
	v_mfma_f32_16x16x32_bf16 v[34:37], v[196:199], v[212:215], v[34:37]
	ds_read_b128 v[228:231], v245 offset:36928
	s_waitcnt lgkmcnt(6)
	v_mfma_f32_16x16x32_bf16 v[38:41], v[196:199], v[216:219], v[38:41]
	ds_read_b128 v[232:235], v245 offset:39232
	s_waitcnt lgkmcnt(6)
	v_mfma_f32_16x16x32_bf16 v[2:5], v[196:199], v[220:223], v[2:5]
	ds_read_b128 v[236:239], v245 offset:41536
	s_waitcnt lgkmcnt(6)
	v_mfma_f32_16x16x32_bf16 v[6:9], v[196:199], v[224:227], v[6:9]
	ds_read_b128 v[240:243], v245 offset:43840
	ds_read_b128 v[196:199], v244 offset:64
	s_waitcnt lgkmcnt(7)
	v_mfma_f32_16x16x32_bf16 v[42:45], v[200:203], v[212:215], v[42:45]
	v_mfma_f32_16x16x32_bf16 v[46:49], v[200:203], v[216:219], v[46:49]
	v_mfma_f32_16x16x32_bf16 v[10:13], v[200:203], v[220:223], v[10:13]
	v_mfma_f32_16x16x32_bf16 v[14:17], v[200:203], v[224:227], v[14:17]
	ds_read_b128 v[200:203], v244 offset:2368
	s_waitcnt lgkmcnt(7)
	v_mfma_f32_16x16x32_bf16 v[50:53], v[204:207], v[212:215], v[50:53]
	v_mfma_f32_16x16x32_bf16 v[54:57], v[204:207], v[216:219], v[54:57]
	v_mfma_f32_16x16x32_bf16 v[18:21], v[204:207], v[220:223], v[18:21]
	v_mfma_f32_16x16x32_bf16 v[22:25], v[204:207], v[224:227], v[22:25]
	ds_read_b128 v[204:207], v244 offset:4672
	s_waitcnt vmcnt(15)
	ds_write_b128 v95, v[98:101] offset:18432
	s_waitcnt vmcnt(14)
	ds_write_b128 v95, v[102:105] offset:23040
	s_waitcnt lgkmcnt(9)
	v_mfma_f32_16x16x32_bf16 v[58:61], v[208:211], v[212:215], v[58:61]
	v_mfma_f32_16x16x32_bf16 v[62:65], v[208:211], v[216:219], v[62:65]
	v_mfma_f32_16x16x32_bf16 v[26:29], v[208:211], v[220:223], v[26:29]
	v_mfma_f32_16x16x32_bf16 v[30:33], v[208:211], v[224:227], v[30:33]
	ds_read_b128 v[208:211], v244 offset:6976
	s_waitcnt vmcnt(13)
	ds_write_b128 v95, v[106:109] offset:27648
	s_waitcnt vmcnt(12)
	ds_write_b128 v95, v[110:113] offset:32256
	s_waitcnt lgkmcnt(7)
	v_mfma_f32_16x16x32_bf16 v[34:37], v[196:199], v[228:231], v[34:37]
	v_mfma_f32_16x16x32_bf16 v[38:41], v[196:199], v[232:235], v[38:41]
	v_mfma_f32_16x16x32_bf16 v[2:5], v[196:199], v[236:239], v[2:5]
	v_mfma_f32_16x16x32_bf16 v[6:9], v[196:199], v[240:243], v[6:9]
	s_waitcnt vmcnt(11)
	ds_write_b128 v95, v[114:117] offset:55296
	s_waitcnt vmcnt(10)
	ds_write_b128 v95, v[118:121] offset:59904
	s_waitcnt lgkmcnt(8)
	v_mfma_f32_16x16x32_bf16 v[42:45], v[200:203], v[228:231], v[42:45]
	v_mfma_f32_16x16x32_bf16 v[46:49], v[200:203], v[232:235], v[46:49]
	v_mfma_f32_16x16x32_bf16 v[10:13], v[200:203], v[236:239], v[10:13]
	v_mfma_f32_16x16x32_bf16 v[14:17], v[200:203], v[240:243], v[14:17]
	s_waitcnt vmcnt(9)
	ds_write_b128 v95, v[122:125] offset:64512
	s_waitcnt vmcnt(8)
	ds_write_b128 v96, v[126:129] offset:32256
	s_waitcnt lgkmcnt(9)
	v_mfma_f32_16x16x32_bf16 v[50:53], v[204:207], v[228:231], v[50:53]
	v_mfma_f32_16x16x32_bf16 v[54:57], v[204:207], v[232:235], v[54:57]
	v_mfma_f32_16x16x32_bf16 v[18:21], v[204:207], v[236:239], v[18:21]
	v_mfma_f32_16x16x32_bf16 v[22:25], v[204:207], v[240:243], v[22:25]
	s_waitcnt lgkmcnt(6)
	v_mfma_f32_16x16x32_bf16 v[58:61], v[208:211], v[228:231], v[58:61]
	v_mfma_f32_16x16x32_bf16 v[62:65], v[208:211], v[232:235], v[62:65]
	v_mfma_f32_16x16x32_bf16 v[26:29], v[208:211], v[236:239], v[26:29]
	v_mfma_f32_16x16x32_bf16 v[30:33], v[208:211], v[240:243], v[30:33]
	s_waitcnt lgkmcnt(0)
	s_barrier
	global_load_dwordx4 v[98:101], v[72:73], off offset:1920
	s_nop 0
	global_load_dwordx4 v[72:75], v[74:75], off offset:1920
	s_nop 0
	global_load_dwordx4 v[102:105], v[76:77], off offset:1920
	s_nop 0
	global_load_dwordx4 v[76:79], v[78:79], off offset:1920
	s_nop 0
	global_load_dwordx4 v[106:109], v[80:81], off offset:1920
	s_nop 0
	global_load_dwordx4 v[80:83], v[82:83], off offset:1920
	s_nop 0
	global_load_dwordx4 v[110:113], v[84:85], off offset:1920
	s_nop 0
	global_load_dwordx4 v[84:87], v[86:87], off offset:1920
	ds_read_b128 v[212:215], v245 offset:55296
	ds_read_b128 v[196:199], v244 offset:18432
	ds_read_b128 v[216:219], v245 offset:57600
	ds_read_b128 v[220:223], v245 offset:59904
	ds_read_b128 v[224:227], v245 offset:62208
	ds_read_b128 v[200:203], v244 offset:20736
	ds_read_b128 v[204:207], v244 offset:23040
	ds_read_b128 v[208:211], v244 offset:25344
	s_waitcnt lgkmcnt(6)
	v_mfma_f32_16x16x32_bf16 v[34:37], v[196:199], v[212:215], v[34:37]
	ds_read_b128 v[228:231], v245 offset:55360
	s_waitcnt lgkmcnt(6)
	v_mfma_f32_16x16x32_bf16 v[38:41], v[196:199], v[216:219], v[38:41]
	ds_read_b128 v[232:235], v245 offset:57664
	s_waitcnt lgkmcnt(6)
	v_mfma_f32_16x16x32_bf16 v[2:5], v[196:199], v[220:223], v[2:5]
	ds_read_b128 v[236:239], v245 offset:59968
	s_waitcnt lgkmcnt(6)
	v_mfma_f32_16x16x32_bf16 v[6:9], v[196:199], v[224:227], v[6:9]
	ds_read_b128 v[240:243], v245 offset:62272
	ds_read_b128 v[196:199], v244 offset:18496
	s_waitcnt lgkmcnt(7)
	v_mfma_f32_16x16x32_bf16 v[42:45], v[200:203], v[212:215], v[42:45]
	v_mfma_f32_16x16x32_bf16 v[46:49], v[200:203], v[216:219], v[46:49]
	v_mfma_f32_16x16x32_bf16 v[10:13], v[200:203], v[220:223], v[10:13]
	v_mfma_f32_16x16x32_bf16 v[14:17], v[200:203], v[224:227], v[14:17]
	ds_read_b128 v[200:203], v244 offset:20800
	s_waitcnt lgkmcnt(7)
	v_mfma_f32_16x16x32_bf16 v[50:53], v[204:207], v[212:215], v[50:53]
	v_mfma_f32_16x16x32_bf16 v[54:57], v[204:207], v[216:219], v[54:57]
	v_mfma_f32_16x16x32_bf16 v[18:21], v[204:207], v[220:223], v[18:21]
	v_mfma_f32_16x16x32_bf16 v[22:25], v[204:207], v[224:227], v[22:25]
	ds_read_b128 v[204:207], v244 offset:23104
	s_waitcnt vmcnt(15)
	ds_write_b128 v95, v[132:135]
	s_waitcnt vmcnt(14)
	ds_write_b128 v95, v[136:139] offset:4608
	s_waitcnt lgkmcnt(9)
	v_mfma_f32_16x16x32_bf16 v[58:61], v[208:211], v[212:215], v[58:61]
	v_mfma_f32_16x16x32_bf16 v[62:65], v[208:211], v[216:219], v[62:65]
	v_mfma_f32_16x16x32_bf16 v[26:29], v[208:211], v[220:223], v[26:29]
	v_mfma_f32_16x16x32_bf16 v[30:33], v[208:211], v[224:227], v[30:33]
	ds_read_b128 v[208:211], v244 offset:25408
	s_waitcnt vmcnt(13)
	ds_write_b128 v95, v[140:143] offset:9216
	s_waitcnt vmcnt(12)
	ds_write_b128 v95, v[144:147] offset:13824
	s_waitcnt lgkmcnt(7)
	v_mfma_f32_16x16x32_bf16 v[34:37], v[196:199], v[228:231], v[34:37]
	v_mfma_f32_16x16x32_bf16 v[38:41], v[196:199], v[232:235], v[38:41]
	v_mfma_f32_16x16x32_bf16 v[2:5], v[196:199], v[236:239], v[2:5]
	v_mfma_f32_16x16x32_bf16 v[6:9], v[196:199], v[240:243], v[6:9]
	s_waitcnt vmcnt(11)
	ds_write_b128 v95, v[148:151] offset:36864
	s_waitcnt vmcnt(10)
	ds_write_b128 v95, v[152:155] offset:41472
	s_waitcnt lgkmcnt(8)
	v_mfma_f32_16x16x32_bf16 v[42:45], v[200:203], v[228:231], v[42:45]
	v_mfma_f32_16x16x32_bf16 v[46:49], v[200:203], v[232:235], v[46:49]
	v_mfma_f32_16x16x32_bf16 v[10:13], v[200:203], v[236:239], v[10:13]
	v_mfma_f32_16x16x32_bf16 v[14:17], v[200:203], v[240:243], v[14:17]
	s_waitcnt vmcnt(9)
	ds_write_b128 v95, v[156:159] offset:46080
	s_waitcnt vmcnt(8)
	ds_write_b128 v95, v[160:163] offset:50688
	s_waitcnt lgkmcnt(9)
	v_mfma_f32_16x16x32_bf16 v[50:53], v[204:207], v[228:231], v[50:53]
	v_mfma_f32_16x16x32_bf16 v[54:57], v[204:207], v[232:235], v[54:57]
	v_mfma_f32_16x16x32_bf16 v[18:21], v[204:207], v[236:239], v[18:21]
	v_mfma_f32_16x16x32_bf16 v[22:25], v[204:207], v[240:243], v[22:25]
	s_waitcnt lgkmcnt(6)
	v_mfma_f32_16x16x32_bf16 v[58:61], v[208:211], v[228:231], v[58:61]
	v_mfma_f32_16x16x32_bf16 v[62:65], v[208:211], v[232:235], v[62:65]
	v_mfma_f32_16x16x32_bf16 v[26:29], v[208:211], v[236:239], v[26:29]
	v_mfma_f32_16x16x32_bf16 v[30:33], v[208:211], v[240:243], v[30:33]
	s_waitcnt lgkmcnt(0)
	s_barrier
	ds_read_b128 v[212:215], v245 offset:36864
	ds_read_b128 v[196:199], v244
	ds_read_b128 v[216:219], v245 offset:39168
	ds_read_b128 v[220:223], v245 offset:41472
	ds_read_b128 v[224:227], v245 offset:43776
	ds_read_b128 v[200:203], v244 offset:2304
	ds_read_b128 v[204:207], v244 offset:4608
	ds_read_b128 v[208:211], v244 offset:6912
	s_waitcnt lgkmcnt(6)
	v_mfma_f32_16x16x32_bf16 v[34:37], v[196:199], v[212:215], v[34:37]
	ds_read_b128 v[228:231], v245 offset:36928
	s_waitcnt lgkmcnt(6)
	v_mfma_f32_16x16x32_bf16 v[38:41], v[196:199], v[216:219], v[38:41]
	ds_read_b128 v[232:235], v245 offset:39232
	s_waitcnt lgkmcnt(6)
	v_mfma_f32_16x16x32_bf16 v[2:5], v[196:199], v[220:223], v[2:5]
	ds_read_b128 v[236:239], v245 offset:41536
	s_waitcnt lgkmcnt(6)
	v_mfma_f32_16x16x32_bf16 v[6:9], v[196:199], v[224:227], v[6:9]
	ds_read_b128 v[240:243], v245 offset:43840
	ds_read_b128 v[196:199], v244 offset:64
	s_waitcnt lgkmcnt(7)
	v_mfma_f32_16x16x32_bf16 v[42:45], v[200:203], v[212:215], v[42:45]
	v_mfma_f32_16x16x32_bf16 v[46:49], v[200:203], v[216:219], v[46:49]
	v_mfma_f32_16x16x32_bf16 v[10:13], v[200:203], v[220:223], v[10:13]
	v_mfma_f32_16x16x32_bf16 v[14:17], v[200:203], v[224:227], v[14:17]
	ds_read_b128 v[200:203], v244 offset:2368
	s_waitcnt lgkmcnt(7)
	v_mfma_f32_16x16x32_bf16 v[50:53], v[204:207], v[212:215], v[50:53]
	v_mfma_f32_16x16x32_bf16 v[54:57], v[204:207], v[216:219], v[54:57]
	v_mfma_f32_16x16x32_bf16 v[18:21], v[204:207], v[220:223], v[18:21]
	v_mfma_f32_16x16x32_bf16 v[22:25], v[204:207], v[224:227], v[22:25]
	ds_read_b128 v[204:207], v244 offset:4672
	s_waitcnt vmcnt(7)
	ds_write_b128 v95, v[98:101] offset:18432
	s_waitcnt vmcnt(6)
	ds_write_b128 v95, v[72:75] offset:23040
	s_waitcnt lgkmcnt(9)
	v_mfma_f32_16x16x32_bf16 v[58:61], v[208:211], v[212:215], v[58:61]
	v_mfma_f32_16x16x32_bf16 v[62:65], v[208:211], v[216:219], v[62:65]
	v_mfma_f32_16x16x32_bf16 v[26:29], v[208:211], v[220:223], v[26:29]
	v_mfma_f32_16x16x32_bf16 v[30:33], v[208:211], v[224:227], v[30:33]
	ds_read_b128 v[208:211], v244 offset:6976
	s_waitcnt vmcnt(5)
	ds_write_b128 v95, v[102:105] offset:27648
	s_waitcnt vmcnt(4)
	ds_write_b128 v95, v[76:79] offset:32256
	s_waitcnt lgkmcnt(7)
	v_mfma_f32_16x16x32_bf16 v[34:37], v[196:199], v[228:231], v[34:37]
	v_mfma_f32_16x16x32_bf16 v[38:41], v[196:199], v[232:235], v[38:41]
	v_mfma_f32_16x16x32_bf16 v[2:5], v[196:199], v[236:239], v[2:5]
	v_mfma_f32_16x16x32_bf16 v[6:9], v[196:199], v[240:243], v[6:9]
	s_waitcnt vmcnt(3)
	ds_write_b128 v95, v[106:109] offset:55296
	s_waitcnt vmcnt(2)
	ds_write_b128 v95, v[80:83] offset:59904
	s_waitcnt lgkmcnt(8)
	v_mfma_f32_16x16x32_bf16 v[42:45], v[200:203], v[228:231], v[42:45]
	v_mfma_f32_16x16x32_bf16 v[46:49], v[200:203], v[232:235], v[46:49]
	v_mfma_f32_16x16x32_bf16 v[10:13], v[200:203], v[236:239], v[10:13]
	v_mfma_f32_16x16x32_bf16 v[14:17], v[200:203], v[240:243], v[14:17]
	s_waitcnt vmcnt(1)
	ds_write_b128 v95, v[110:113] offset:64512
	s_waitcnt vmcnt(0)
	ds_write_b128 v96, v[84:87] offset:32256
	s_waitcnt lgkmcnt(9)
	v_mfma_f32_16x16x32_bf16 v[50:53], v[204:207], v[228:231], v[50:53]
	v_mfma_f32_16x16x32_bf16 v[54:57], v[204:207], v[232:235], v[54:57]
	v_mfma_f32_16x16x32_bf16 v[18:21], v[204:207], v[236:239], v[18:21]
	v_mfma_f32_16x16x32_bf16 v[22:25], v[204:207], v[240:243], v[22:25]
	s_waitcnt lgkmcnt(6)
	v_mfma_f32_16x16x32_bf16 v[58:61], v[208:211], v[228:231], v[58:61]
	v_mfma_f32_16x16x32_bf16 v[62:65], v[208:211], v[232:235], v[62:65]
	v_mfma_f32_16x16x32_bf16 v[26:29], v[208:211], v[236:239], v[26:29]
	v_mfma_f32_16x16x32_bf16 v[30:33], v[208:211], v[240:243], v[30:33]
	s_waitcnt lgkmcnt(0)
	s_barrier
	ds_read_b128 v[212:215], v245 offset:55296
	ds_read_b128 v[196:199], v244 offset:18432
	ds_read_b128 v[216:219], v245 offset:57600
	ds_read_b128 v[220:223], v245 offset:59904
	ds_read_b128 v[224:227], v245 offset:62208
	ds_read_b128 v[200:203], v244 offset:20736
	ds_read_b128 v[204:207], v244 offset:23040
	ds_read_b128 v[208:211], v244 offset:25344
	s_waitcnt lgkmcnt(6)
	v_mfma_f32_16x16x32_bf16 v[34:37], v[196:199], v[212:215], v[34:37]
	ds_read_b128 v[228:231], v245 offset:55360
	s_waitcnt lgkmcnt(6)
	v_mfma_f32_16x16x32_bf16 v[38:41], v[196:199], v[216:219], v[38:41]
	ds_read_b128 v[232:235], v245 offset:57664
	s_waitcnt lgkmcnt(6)
	v_mfma_f32_16x16x32_bf16 v[2:5], v[196:199], v[220:223], v[2:5]
	ds_read_b128 v[236:239], v245 offset:59968
	s_waitcnt lgkmcnt(6)
	v_mfma_f32_16x16x32_bf16 v[6:9], v[196:199], v[224:227], v[6:9]
	ds_read_b128 v[240:243], v245 offset:62272
	ds_read_b128 v[196:199], v244 offset:18496
	s_waitcnt lgkmcnt(7)
	v_mfma_f32_16x16x32_bf16 v[42:45], v[200:203], v[212:215], v[42:45]
	v_mfma_f32_16x16x32_bf16 v[46:49], v[200:203], v[216:219], v[46:49]
	v_mfma_f32_16x16x32_bf16 v[10:13], v[200:203], v[220:223], v[10:13]
	v_mfma_f32_16x16x32_bf16 v[14:17], v[200:203], v[224:227], v[14:17]
	ds_read_b128 v[200:203], v244 offset:20800
	s_waitcnt lgkmcnt(7)
	v_mfma_f32_16x16x32_bf16 v[50:53], v[204:207], v[212:215], v[50:53]
	v_mfma_f32_16x16x32_bf16 v[54:57], v[204:207], v[216:219], v[54:57]
	v_mfma_f32_16x16x32_bf16 v[18:21], v[204:207], v[220:223], v[18:21]
	v_mfma_f32_16x16x32_bf16 v[22:25], v[204:207], v[224:227], v[22:25]
	ds_read_b128 v[204:207], v244 offset:23104
	s_waitcnt lgkmcnt(7)
	v_mfma_f32_16x16x32_bf16 v[58:61], v[208:211], v[212:215], v[58:61]
	v_mfma_f32_16x16x32_bf16 v[62:65], v[208:211], v[216:219], v[62:65]
	v_mfma_f32_16x16x32_bf16 v[26:29], v[208:211], v[220:223], v[26:29]
	v_mfma_f32_16x16x32_bf16 v[30:33], v[208:211], v[224:227], v[30:33]
	ds_read_b128 v[208:211], v244 offset:25408
	s_waitcnt lgkmcnt(3)
	v_mfma_f32_16x16x32_bf16 v[34:37], v[196:199], v[228:231], v[34:37]
	v_mfma_f32_16x16x32_bf16 v[38:41], v[196:199], v[232:235], v[38:41]
	v_mfma_f32_16x16x32_bf16 v[2:5], v[196:199], v[236:239], v[2:5]
	v_mfma_f32_16x16x32_bf16 v[6:9], v[196:199], v[240:243], v[6:9]
	s_waitcnt lgkmcnt(2)
	v_mfma_f32_16x16x32_bf16 v[42:45], v[200:203], v[228:231], v[42:45]
	v_mfma_f32_16x16x32_bf16 v[46:49], v[200:203], v[232:235], v[46:49]
	v_mfma_f32_16x16x32_bf16 v[10:13], v[200:203], v[236:239], v[10:13]
	v_mfma_f32_16x16x32_bf16 v[14:17], v[200:203], v[240:243], v[14:17]
	s_waitcnt lgkmcnt(1)
	v_mfma_f32_16x16x32_bf16 v[50:53], v[204:207], v[228:231], v[50:53]
	v_mfma_f32_16x16x32_bf16 v[54:57], v[204:207], v[232:235], v[54:57]
	v_mfma_f32_16x16x32_bf16 v[18:21], v[204:207], v[236:239], v[18:21]
	v_mfma_f32_16x16x32_bf16 v[22:25], v[204:207], v[240:243], v[22:25]
	s_waitcnt lgkmcnt(0)
	v_mfma_f32_16x16x32_bf16 v[58:61], v[208:211], v[228:231], v[58:61]
	v_mfma_f32_16x16x32_bf16 v[62:65], v[208:211], v[232:235], v[62:65]
	v_mfma_f32_16x16x32_bf16 v[26:29], v[208:211], v[236:239], v[26:29]
	v_mfma_f32_16x16x32_bf16 v[30:33], v[208:211], v[240:243], v[30:33]
	v_or_b32_e32 v66, s5, v88
	s_addk_i32 s5, 0xf000
	s_lshr_b32 s5, s5, 12
	s_mulk_i32 s5, 0xc00
	s_addk_i32 s5, 0x3000
	s_cmp_gt_u32 s0, 31
	v_lshlrev_b32_e32 v66, 12, v66
	s_cselect_b32 s0, s5, 0x2400
	v_lshl_add_u64 v[148:149], s[80:81], 0, v[66:67]
	v_add_lshl_u32 v66, s4, v97, 2
	s_lshl_b64 s[4:5], s[0:1], 2
	s_add_u32 s0, s82, s4
	s_addc_u32 s5, s83, s5
	s_add_u32 s4, s0, 0xe958000
	v_lshl_add_u64 v[150:151], v[148:149], 0, v[66:67]
	s_addc_u32 s5, s5, 0
	v_or_b32_e32 v152, 0xe0, v66
	v_or_b32_e32 v154, 32, v66
	v_or_b32_e32 v156, 64, v66
	v_or_b32_e32 v158, 0x60, v66
	v_or_b32_e32 v160, 0x80, v66
	v_or_b32_e32 v162, 0xa0, v66
	v_or_b32_e32 v164, 0xc0, v66
	v_mov_b32_e32 v155, v67
	v_mov_b32_e32 v157, v67
	v_mov_b32_e32 v159, v67
	v_mov_b32_e32 v161, v67
	v_mov_b32_e32 v163, v67
	v_mov_b32_e32 v165, v67
	v_mov_b32_e32 v153, v67
	s_add_i32 s11, s11, 1
	s_mul_i32 s0, s11, s7
	s_add_i32 s10, s10, s7
	s_waitcnt lgkmcnt(0)
	s_barrier
	s_nop 7
	v_permlane16_swap_b32_e32 v34, v38
	v_permlane16_swap_b32_e32 v35, v39
	v_permlane16_swap_b32_e32 v36, v40
	v_permlane16_swap_b32_e32 v37, v41
	v_permlane16_swap_b32_e32 v42, v46
	v_permlane16_swap_b32_e32 v43, v47
	v_permlane16_swap_b32_e32 v44, v48
	v_permlane16_swap_b32_e32 v45, v49
	v_permlane16_swap_b32_e32 v2, v6
	v_permlane16_swap_b32_e32 v3, v7
	v_permlane16_swap_b32_e32 v4, v8
	v_permlane16_swap_b32_e32 v5, v9
	v_permlane16_swap_b32_e32 v10, v14
	v_permlane16_swap_b32_e32 v11, v15
	v_permlane16_swap_b32_e32 v12, v16
	v_permlane16_swap_b32_e32 v13, v17
	v_permlane16_swap_b32_e32 v50, v54
	v_permlane16_swap_b32_e32 v51, v55
	v_permlane16_swap_b32_e32 v52, v56
	v_permlane16_swap_b32_e32 v53, v57
	v_permlane16_swap_b32_e32 v58, v62
	v_permlane16_swap_b32_e32 v59, v63
	v_permlane16_swap_b32_e32 v60, v64
	v_permlane16_swap_b32_e32 v61, v65
	v_permlane16_swap_b32_e32 v18, v22
	v_permlane16_swap_b32_e32 v19, v23
	v_permlane16_swap_b32_e32 v20, v24
	v_permlane16_swap_b32_e32 v21, v25
	v_permlane16_swap_b32_e32 v26, v30
	v_permlane16_swap_b32_e32 v27, v31
	v_permlane16_swap_b32_e32 v28, v32
	v_permlane16_swap_b32_e32 v29, v33
	v_permlane32_swap_b32_e32 v34, v38
	v_permlane32_swap_b32_e32 v35, v39
	v_permlane32_swap_b32_e32 v36, v40
	v_permlane32_swap_b32_e32 v37, v41
	v_permlane32_swap_b32_e32 v42, v46
	v_permlane32_swap_b32_e32 v43, v47
	v_permlane32_swap_b32_e32 v44, v48
	v_permlane32_swap_b32_e32 v45, v49
	v_permlane32_swap_b32_e32 v2, v6
	v_permlane32_swap_b32_e32 v3, v7
	v_permlane32_swap_b32_e32 v4, v8
	v_permlane32_swap_b32_e32 v5, v9
	v_permlane32_swap_b32_e32 v10, v14
	v_permlane32_swap_b32_e32 v11, v15
	v_permlane32_swap_b32_e32 v12, v16
	v_permlane32_swap_b32_e32 v13, v17
	v_permlane32_swap_b32_e32 v50, v54
	v_permlane32_swap_b32_e32 v51, v55
	v_permlane32_swap_b32_e32 v52, v56
	v_permlane32_swap_b32_e32 v53, v57
	v_permlane32_swap_b32_e32 v58, v62
	v_permlane32_swap_b32_e32 v59, v63
	v_permlane32_swap_b32_e32 v60, v64
	v_permlane32_swap_b32_e32 v61, v65
	v_permlane32_swap_b32_e32 v18, v22
	v_permlane32_swap_b32_e32 v19, v23
	v_permlane32_swap_b32_e32 v20, v24
	v_permlane32_swap_b32_e32 v21, v25
	v_permlane32_swap_b32_e32 v26, v30
	v_permlane32_swap_b32_e32 v27, v31
	v_permlane32_swap_b32_e32 v28, v32
	v_permlane32_swap_b32_e32 v29, v33
	global_load_dwordx4 v[76:79], v[150:151], off offset:224
	global_load_dwordx4 v[84:87], v152, s[4:5]
	global_load_dwordx4 v[80:83], v[150:151], off offset:192
	s_waitcnt vmcnt(1)
	v_fma_f32 v62, v62, v84, v76
	v_fma_f32 v63, v63, v85, v77
	global_load_dwordx4 v[72:75], v164, s[4:5]
	global_load_dwordx4 v[98:101], v[150:151], off offset:160
	global_load_dwordx4 v[102:105], v162, s[4:5]
	global_load_dwordx4 v[106:109], v[150:151], off offset:128
	global_load_dwordx4 v[110:113], v160, s[4:5]
	global_load_dwordx4 v[114:117], v[150:151], off offset:96
	global_load_dwordx4 v[118:121], v158, s[4:5]
	global_load_dwordx4 v[122:125], v[150:151], off offset:64
	global_load_dwordx4 v[126:129], v156, s[4:5]
	global_load_dwordx4 v[132:135], v[150:151], off offset:32
	global_load_dwordx4 v[136:139], v154, s[4:5]
	global_load_dwordx4 v[140:143], v[150:151], off
	global_load_dwordx4 v[144:147], v66, s[4:5]
	v_pk_fma_f32 v[64:65], v[64:65], v[86:87], v[78:79]
	global_store_dwordx4 v[150:151], v[62:65], off offset:224
	s_waitcnt vmcnt(13)
	v_pk_fma_f32 v[58:59], v[58:59], v[72:73], v[80:81]
	v_pk_fma_f32 v[60:61], v[60:61], v[74:75], v[82:83]
	s_waitcnt vmcnt(11)
	v_pk_fma_f32 v[54:55], v[54:55], v[102:103], v[98:99]
	v_pk_fma_f32 v[56:57], v[56:57], v[104:105], v[100:101]
	s_waitcnt vmcnt(9)
	v_pk_fma_f32 v[50:51], v[50:51], v[110:111], v[106:107]
	v_pk_fma_f32 v[52:53], v[52:53], v[112:113], v[108:109]
	s_waitcnt vmcnt(7)
	v_pk_fma_f32 v[46:47], v[46:47], v[118:119], v[114:115]
	v_pk_fma_f32 v[48:49], v[48:49], v[120:121], v[116:117]
	s_waitcnt vmcnt(5)
	v_pk_fma_f32 v[42:43], v[42:43], v[126:127], v[122:123]
	v_pk_fma_f32 v[44:45], v[44:45], v[128:129], v[124:125]
	s_waitcnt vmcnt(3)
	v_pk_fma_f32 v[38:39], v[38:39], v[136:137], v[132:133]
	v_pk_fma_f32 v[40:41], v[40:41], v[138:139], v[134:135]
	s_waitcnt vmcnt(1)
	v_pk_fma_f32 v[34:35], v[34:35], v[144:145], v[140:141]
	v_pk_fma_f32 v[36:37], v[36:37], v[146:147], v[142:143]
	global_store_dwordx4 v[150:151], v[34:37], off
	global_store_dwordx4 v[150:151], v[38:41], off offset:32
	global_store_dwordx4 v[150:151], v[42:45], off offset:64
	v_lshl_add_u64 v[34:35], v[148:149], 0, s[2:3]
	global_store_dwordx4 v[150:151], v[46:49], off offset:96
	global_store_dwordx4 v[150:151], v[50:53], off offset:128
	global_store_dwordx4 v[150:151], v[54:57], off offset:160
	global_store_dwordx4 v[150:151], v[58:61], off offset:192
	v_lshl_add_u64 v[114:115], v[34:35], 0, v[66:67]
	v_lshl_add_u64 v[116:117], v[34:35], 0, v[154:155]
	v_lshl_add_u64 v[118:119], v[34:35], 0, v[156:157]
	v_lshl_add_u64 v[120:121], v[34:35], 0, v[158:159]
	v_lshl_add_u64 v[122:123], v[34:35], 0, v[160:161]
	v_lshl_add_u64 v[124:125], v[34:35], 0, v[162:163]
	v_lshl_add_u64 v[126:127], v[34:35], 0, v[164:165]
	v_lshl_add_u64 v[128:129], v[34:35], 0, v[152:153]
	global_load_dwordx4 v[34:37], v[128:129], off
	global_load_dwordx4 v[38:41], v152, s[4:5]
	global_load_dwordx4 v[42:45], v[126:127], off
	global_load_dwordx4 v[46:49], v164, s[4:5]
	global_load_dwordx4 v[50:53], v[124:125], off
	global_load_dwordx4 v[54:57], v162, s[4:5]
	global_load_dwordx4 v[58:61], v[122:123], off
	global_load_dwordx4 v[62:65], v160, s[4:5]
	global_load_dwordx4 v[72:75], v[120:121], off
	global_load_dwordx4 v[76:79], v158, s[4:5]
	global_load_dwordx4 v[80:83], v[118:119], off
	global_load_dwordx4 v[84:87], v156, s[4:5]
	global_load_dwordx4 v[98:101], v[116:117], off
	global_load_dwordx4 v[102:105], v154, s[4:5]
	global_load_dwordx4 v[106:109], v[114:115], off
	global_load_dwordx4 v[110:113], v66, s[4:5]
	s_add_i32 s4, s0, s6
	s_cmpk_lt_u32 s10, 0x60
	s_waitcnt vmcnt(14)
	v_pk_fma_f32 v[30:31], v[30:31], v[38:39], v[34:35]
	v_pk_fma_f32 v[32:33], v[32:33], v[40:41], v[36:37]
	s_waitcnt vmcnt(12)
	v_pk_fma_f32 v[26:27], v[26:27], v[46:47], v[42:43]
	v_pk_fma_f32 v[28:29], v[28:29], v[48:49], v[44:45]
	s_waitcnt vmcnt(10)
	v_pk_fma_f32 v[22:23], v[22:23], v[54:55], v[50:51]
	v_pk_fma_f32 v[24:25], v[24:25], v[56:57], v[52:53]
	s_waitcnt vmcnt(8)
	v_pk_fma_f32 v[18:19], v[18:19], v[62:63], v[58:59]
	v_pk_fma_f32 v[20:21], v[20:21], v[64:65], v[60:61]
	s_waitcnt vmcnt(6)
	v_pk_fma_f32 v[14:15], v[14:15], v[76:77], v[72:73]
	v_pk_fma_f32 v[16:17], v[16:17], v[78:79], v[74:75]
	s_waitcnt vmcnt(4)
	v_pk_fma_f32 v[10:11], v[10:11], v[84:85], v[80:81]
	v_pk_fma_f32 v[12:13], v[12:13], v[86:87], v[82:83]
	s_waitcnt vmcnt(2)
	v_pk_fma_f32 v[6:7], v[6:7], v[102:103], v[98:99]
	v_pk_fma_f32 v[8:9], v[8:9], v[104:105], v[100:101]
	s_waitcnt vmcnt(0)
	v_pk_fma_f32 v[2:3], v[2:3], v[110:111], v[106:107]
	v_pk_fma_f32 v[4:5], v[4:5], v[112:113], v[108:109]
	global_store_dwordx4 v[114:115], v[2:5], off
	global_store_dwordx4 v[116:117], v[6:9], off
	global_store_dwordx4 v[118:119], v[10:13], off
	global_store_dwordx4 v[120:121], v[14:17], off
	global_store_dwordx4 v[122:123], v[18:21], off
	global_store_dwordx4 v[124:125], v[22:25], off
	global_store_dwordx4 v[126:127], v[26:29], off
	global_store_dwordx4 v[128:129], v[30:33], off
	s_cbranch_scc1 .LBB0_1871
